# M1 prologue reorder + rotated M1 k-loop + EpiResid y-load hoist in M2/E4/O5 epilogues
# speedup vs baseline: 1.0366x; 1.0366x over previous
.LBB0_681:
	s_add_i32 s9, s7, 1
	s_bitcmp1_b32 s9, 0
	s_cselect_b32 s10, 0xe000, 0
	v_add_u32_e32 v115, s10, v109
	v_lshl_add_u64 v[116:117], v[98:99], 0, s[2:3]
	v_readfirstlane_b32 s10, v115
	v_add_u32_e32 v120, 0x2000, v115
	v_lshl_add_u64 v[118:119], v[116:117], 0, s[12:13]
	s_mov_b32 m0, s10
	v_readfirstlane_b32 s10, v120
	s_waitcnt vmcnt(0)
	s_waitcnt vmcnt(0) lgkmcnt(0)
	s_barrier
	global_load_lds_dwordx4 v[118:119], off
	v_lshl_add_u64 v[118:119], v[116:117], 0, s[16:17]
	s_mov_b32 m0, s10
	v_lshl_add_u64 v[116:117], v[116:117], 0, s[18:19]
	global_load_lds_dwordx4 v[118:119], off
	v_add_u32_e32 v118, 0x4000, v115
	v_add_u32_e32 v120, 0x6000, v115
	v_readfirstlane_b32 s10, v118
	s_mov_b32 m0, s10
	s_mov_b64 s[10:11], 0x6a94080
	global_load_lds_dwordx4 v[116:117], off
	v_lshl_add_u64 v[116:117], v[96:97], 0, s[2:3]
	v_lshl_add_u64 v[118:119], v[116:117], 0, s[10:11]
	v_readfirstlane_b32 s10, v120
	s_mov_b32 m0, s10
	s_mov_b64 s[10:11], 0x6ab4080
	v_add_u32_e32 v120, 0x8000, v115
	global_load_lds_dwordx4 v[118:119], off
	v_lshl_add_u64 v[118:119], v[116:117], 0, s[10:11]
	v_readfirstlane_b32 s10, v120
	s_mov_b32 m0, s10
	s_mov_b64 s[10:11], 0x6ad4080
	v_add_u32_e32 v120, 0xa000, v115
	global_load_lds_dwordx4 v[118:119], off
	v_lshl_add_u64 v[118:119], v[116:117], 0, s[10:11]
	v_readfirstlane_b32 s10, v120
	s_mov_b32 m0, s10
	s_mov_b64 s[10:11], 0x6af4080
	v_add_u32_e32 v115, 0xc000, v115
	v_lshl_add_u64 v[116:117], v[116:117], 0, s[10:11]
	v_readfirstlane_b32 s10, v115
	global_load_lds_dwordx4 v[118:119], off
	s_mov_b32 m0, s10
	s_nop 0
	global_load_lds_dwordx4 v[116:117], off
	s_bitcmp1_b32 s7, 0
	s_cselect_b32 s7, 0xe000, 0
	v_add_u32_e32 v115, s7, v114
	v_add_u32_e32 v120, v115, v111
	ds_read_b128 v[116:119], v120 offset:0
	v_add_u32_e32 v128, s7, v113
	ds_read_b128 v[120:123], v120 offset:0x1000
	v_add_u32_e32 v134, v128, v111
	ds_read_b128 v[124:127], v134 offset:0
	ds_read_b128 v[130:133], v134 offset:0x1000
	ds_read_b128 v[134:137], v134 offset:0x2000
	v_add_u32_e32 v148, v115, v110
	ds_read_b128 v[144:147], v148 offset:0
	ds_read_b128 v[148:151], v148 offset:0x1000
	v_add_u32_e32 v152, v128, v110
	ds_read_b128 v[182:185], v152 offset:0
	ds_read_b128 v[186:189], v152 offset:0x1000
	ds_read_b128 v[190:193], v152 offset:0x2000
	s_waitcnt lgkmcnt(5)
	s_nop 0
	v_mfma_f32_32x32x16_bf16 v[64:79], v[116:119], v[124:127], v[64:79]
	v_mfma_f32_32x32x16_bf16 v[32:47], v[116:119], v[130:133], v[32:47]
	v_mfma_f32_32x32x16_bf16 v[0:15], v[116:119], v[134:137], v[0:15]
	v_mfma_f32_32x32x16_bf16 v[80:95], v[120:123], v[124:127], v[80:95]
	v_mfma_f32_32x32x16_bf16 v[48:63], v[120:123], v[130:133], v[48:63]
	v_mfma_f32_32x32x16_bf16 v[16:31], v[120:123], v[134:137], v[16:31]
	v_add_u32_e32 v120, v115, v108
	ds_read_b128 v[116:119], v120 offset:0
	ds_read_b128 v[120:123], v120 offset:0x1000
	v_add_u32_e32 v134, v128, v108
	ds_read_b128 v[124:127], v134 offset:0
	ds_read_b128 v[130:133], v134 offset:0x1000
	ds_read_b128 v[134:137], v134 offset:0x2000
	s_waitcnt lgkmcnt(5)
	s_nop 0
	v_mfma_f32_32x32x16_bf16 v[64:79], v[144:147], v[182:185], v[64:79]
	v_mfma_f32_32x32x16_bf16 v[32:47], v[144:147], v[186:189], v[32:47]
	v_mfma_f32_32x32x16_bf16 v[0:15], v[144:147], v[190:193], v[0:15]
	v_mfma_f32_32x32x16_bf16 v[80:95], v[148:151], v[182:185], v[80:95]
	v_mfma_f32_32x32x16_bf16 v[48:63], v[148:151], v[186:189], v[48:63]
	v_mfma_f32_32x32x16_bf16 v[16:31], v[148:151], v[190:193], v[16:31]
	v_add_u32_e32 v115, v115, v107
	ds_read_b128 v[144:147], v115 offset:0
	ds_read_b128 v[148:151], v115 offset:0x1000
	v_add_u32_e32 v115, v128, v107
	ds_read_b128 v[182:185], v115 offset:0
	ds_read_b128 v[186:189], v115 offset:0x1000
	ds_read_b128 v[190:193], v115 offset:0x2000
	s_waitcnt lgkmcnt(5)
	s_nop 0
	v_mfma_f32_32x32x16_bf16 v[64:79], v[116:119], v[124:127], v[64:79]
	v_mfma_f32_32x32x16_bf16 v[32:47], v[116:119], v[130:133], v[32:47]
	v_mfma_f32_32x32x16_bf16 v[0:15], v[116:119], v[134:137], v[0:15]
	v_mfma_f32_32x32x16_bf16 v[80:95], v[120:123], v[124:127], v[80:95]
	v_mfma_f32_32x32x16_bf16 v[48:63], v[120:123], v[130:133], v[48:63]
	v_mfma_f32_32x32x16_bf16 v[16:31], v[120:123], v[134:137], v[16:31]
	s_waitcnt lgkmcnt(0)
	s_nop 0
	v_mfma_f32_32x32x16_bf16 v[64:79], v[144:147], v[182:185], v[64:79]
	v_mfma_f32_32x32x16_bf16 v[32:47], v[144:147], v[186:189], v[32:47]
	v_mfma_f32_32x32x16_bf16 v[0:15], v[144:147], v[190:193], v[0:15]
	v_mfma_f32_32x32x16_bf16 v[80:95], v[148:151], v[182:185], v[80:95]
	v_mfma_f32_32x32x16_bf16 v[48:63], v[148:151], v[186:189], v[48:63]
	v_mfma_f32_32x32x16_bf16 v[16:31], v[148:151], v[190:193], v[16:31]
	s_add_u32 s2, s2, 0x80
	s_addc_u32 s3, s3, 0
	s_cmpk_eq_i32 s2, 0x780
	s_mov_b32 s7, s9
	s_cbranch_scc0 .LBB0_681
	s_waitcnt vmcnt(0)
	s_waitcnt vmcnt(0) lgkmcnt(0)
	s_barrier
	v_add_u32_e32 v109, 0x14000, v112
	v_add_u32_e32 v112, v109, v111
	ds_read_b128 v[96:99], v112 offset:0
	v_add_u32_e32 v128, 0xe000, v113
	ds_read_b128 v[112:115], v112 offset:0x1000
	v_add_u32_e32 v111, v128, v111
	ds_read_b128 v[116:119], v111 offset:0
	ds_read_b128 v[120:123], v111 offset:0x1000
	ds_read_b128 v[124:127], v111 offset:0x2000
	v_add_u32_e32 v111, v109, v110
	ds_read_b128 v[130:133], v111 offset:0
	ds_read_b128 v[134:137], v111 offset:0x1000
	v_add_u32_e32 v110, v128, v110
	ds_read_b128 v[144:147], v110 offset:0
	ds_read_b128 v[148:151], v110 offset:0x1000
	ds_read_b128 v[182:185], v110 offset:0x2000
	s_waitcnt lgkmcnt(5)
	s_nop 0
	v_mfma_f32_32x32x16_bf16 v[64:79], v[96:99], v[116:119], v[64:79]
	v_mfma_f32_32x32x16_bf16 v[32:47], v[96:99], v[120:123], v[32:47]
	v_mfma_f32_32x32x16_bf16 v[0:15], v[96:99], v[124:127], v[0:15]
	v_mfma_f32_32x32x16_bf16 v[48:63], v[112:115], v[120:123], v[48:63]
	v_mfma_f32_32x32x16_bf16 v[16:31], v[112:115], v[124:127], v[16:31]
	v_mfma_f32_32x32x16_bf16 v[80:95], v[112:115], v[116:119], v[80:95]
	v_add_u32_e32 v110, v109, v108
	ds_read_b128 v[96:99], v110 offset:0
	ds_read_b128 v[110:113], v110 offset:0x1000
	v_add_u32_e32 v108, v128, v108
	ds_read_b128 v[114:117], v108 offset:0
	ds_read_b128 v[118:121], v108 offset:0x1000
	ds_read_b128 v[122:125], v108 offset:0x2000
	s_waitcnt lgkmcnt(5)
	s_nop 0
	v_mfma_f32_32x32x16_bf16 v[64:79], v[130:133], v[144:147], v[64:79]
	v_mfma_f32_32x32x16_bf16 v[32:47], v[130:133], v[148:151], v[32:47]
	v_mfma_f32_32x32x16_bf16 v[0:15], v[130:133], v[182:185], v[0:15]
	v_mfma_f32_32x32x16_bf16 v[48:63], v[134:137], v[148:151], v[48:63]
	v_mfma_f32_32x32x16_bf16 v[16:31], v[134:137], v[182:185], v[16:31]
	v_mfma_f32_32x32x16_bf16 v[80:95], v[134:137], v[144:147], v[80:95]
	v_add_u32_e32 v108, v109, v107
	ds_read_b128 v[130:133], v108 offset:0
	ds_read_b128 v[134:137], v108 offset:0x1000
	v_add_u32_e32 v107, v128, v107
	ds_read_b128 v[144:147], v107 offset:0
	ds_read_b128 v[148:151], v107 offset:0x1000
	ds_read_b128 v[182:185], v107 offset:0x2000
	s_waitcnt lgkmcnt(5)
	s_nop 0
	v_mfma_f32_32x32x16_bf16 v[64:79], v[96:99], v[114:117], v[64:79]
	v_mfma_f32_32x32x16_bf16 v[32:47], v[96:99], v[118:121], v[32:47]
	v_mfma_f32_32x32x16_bf16 v[0:15], v[96:99], v[122:125], v[0:15]
	v_mfma_f32_32x32x16_bf16 v[48:63], v[110:113], v[118:121], v[48:63]
	v_mfma_f32_32x32x16_bf16 v[16:31], v[110:113], v[122:125], v[16:31]
	v_mfma_f32_32x32x16_bf16 v[80:95], v[110:113], v[114:117], v[80:95]
	s_waitcnt lgkmcnt(0)
	s_nop 0
	v_mfma_f32_32x32x16_bf16 v[64:79], v[130:133], v[144:147], v[64:79]
	v_mfma_f32_32x32x16_bf16 v[32:47], v[130:133], v[148:151], v[32:47]
	v_mfma_f32_32x32x16_bf16 v[0:15], v[130:133], v[182:185], v[0:15]
	v_mfma_f32_32x32x16_bf16 v[48:63], v[134:137], v[148:151], v[48:63]
	v_mfma_f32_32x32x16_bf16 v[16:31], v[134:137], v[182:185], v[16:31]
	v_mfma_f32_32x32x16_bf16 v[80:95], v[134:137], v[144:147], v[80:95]
	v_add_u32_e32 v96, s4, v106
	v_lshrrev_b32_e32 v128, 4, v101
	v_and_b32_e32 v112, 15, v100
	v_or_b32_e32 v100, v96, v128
	v_add_u32_e32 v105, s8, v105
	v_ashrrev_i32_e32 v101, 31, v100
	v_lshl_or_b32 v98, v112, 2, v105
	v_lshlrev_b64 v[106:107], 12, v[100:101]
	v_ashrrev_i32_e32 v99, 31, v98
	v_lshl_add_u64 v[106:107], s[40:41], 0, v[106:107]
	v_lshl_add_u64 v[110:111], v[98:99], 2, v[106:107]
	s_barrier
	global_load_dwordx4 v[198:201], v[110:111], off
	v_add_co_u32_e32 v182, vcc, 0x4000, v110
	s_nop 1
	v_addc_co_u32_e32 v183, vcc, 0, v111, vcc
	global_load_dwordx4 v[202:205], v[182:183], off
	v_add_co_u32_e32 v182, vcc, 0x4000, v182
	s_nop 1
	v_addc_co_u32_e32 v183, vcc, 0, v183, vcc
	global_load_dwordx4 v[206:209], v[182:183], off
	v_add_co_u32_e32 v182, vcc, 0x4000, v182
	s_nop 1
	v_addc_co_u32_e32 v183, vcc, 0, v183, vcc
	global_load_dwordx4 v[210:213], v[182:183], off
	v_add_co_u32_e32 v182, vcc, 0x4000, v182
	s_nop 1
	v_addc_co_u32_e32 v183, vcc, 0, v183, vcc
	global_load_dwordx4 v[214:217], v[182:183], off
	v_add_co_u32_e32 v182, vcc, 0x4000, v182
	s_nop 1
	v_addc_co_u32_e32 v183, vcc, 0, v183, vcc
	global_load_dwordx4 v[218:221], v[182:183], off
	v_add_co_u32_e32 v182, vcc, 0x4000, v182
	s_nop 1
	v_addc_co_u32_e32 v183, vcc, 0, v183, vcc
	global_load_dwordx4 v[222:225], v[182:183], off
	v_add_co_u32_e32 v182, vcc, 0x4000, v182
	s_nop 1
	v_addc_co_u32_e32 v183, vcc, 0, v183, vcc
	global_load_dwordx4 v[226:229], v[182:183], off
	s_movk_i32 s2, 0x2400
	s_cmp_lt_i32 s5, 22
	v_mul_lo_u32 v97, v103, s2
	s_cselect_b64 s[2:3], -1, 0
	s_cmp_gt_i32 s5, 21
	s_movk_i32 s5, 0x110
	v_and_b32_e32 v103, 16, v104
	v_mad_u32_u24 v104, v102, s5, v97
	v_add_u32_e32 v113, 0xfffff000, v96
	v_cndmask_b32_e64 v102, 0, 1, s[2:3]
	s_cselect_b64 s[2:3], -1, 0
	s_add_i32 s7, s4, 0xfffff000
	v_add_u32_e32 v104, v104, v103
	ds_write_b128 v104, v[64:67]
	ds_write_b128 v104, v[68:71] offset:32
	ds_write_b128 v104, v[72:75] offset:64
	ds_write_b128 v104, v[76:79] offset:96
	ds_write_b128 v104, v[80:83] offset:128
	ds_write_b128 v104, v[84:87] offset:160
	ds_write_b128 v104, v[88:91] offset:192
	ds_write_b128 v104, v[92:95] offset:224
	v_xor_b32_e32 v64, s7, v113
	s_movk_i32 s4, 0x400
	v_lshl_or_b32 v97, v112, 4, v97
	v_cmp_gt_u32_e32 vcc, s4, v64
	v_mad_u32_u24 v115, v128, s5, v97
	s_and_b64 s[4:5], s[2:3], vcc
	v_cndmask_b32_e64 v71, 0, 1, s[4:5]
	s_movk_i32 s4, 0x1000
	v_cmp_gt_i32_e32 vcc, s4, v100
	v_subrev_u32_e32 v114, s8, v98
	v_lshl_add_u32 v103, v114, 2, v167
	v_cndmask_b32_e32 v64, v71, v102, vcc
	v_and_b32_e32 v64, 1, v64
	v_cmp_eq_u32_e32 vcc, 1, v64
	v_ashrrev_i32_e32 v68, 6, v105
	s_mov_b32 s4, 0xc000
	v_cndmask_b32_e64 v64, v171, 0, vcc
	v_add_u32_e32 v70, v103, v64
	ds_read_b128 v[64:67], v115
	ds_read_b128 v[72:75], v70
	v_cmp_eq_u32_e64 s[36:37], 0, v112
	v_mad_i64_i32 v[68:69], s[4:5], v68, s4, 0
	s_and_b64 vcc, exec, s[0:1]
	s_waitcnt vmcnt(7) lgkmcnt(0)
	v_pk_fma_f32 v[66:67], v[66:67], v[74:75], v[200:201]
	v_pk_fma_f32 v[64:65], v[64:65], v[72:73], v[198:199]
	global_store_dwordx4 v[110:111], v[64:67], off
	s_cbranch_vccnz .LBB0_686
	ds_read_b128 v[72:75], v70 offset:2048
	v_lshlrev_b64 v[76:77], 10, v[100:101]
	v_lshl_add_u64 v[76:77], v[76:77], 1, s[42:43]
	v_lshl_add_u64 v[76:77], v[98:99], 1, v[76:77]
	s_waitcnt lgkmcnt(0)
	v_pk_mul_f32 v[72:73], v[64:65], v[72:73]
	v_pk_mul_f32 v[64:65], v[64:65], v[64:65]
	v_pk_mul_f32 v[74:75], v[66:67], v[74:75]
	v_pk_mul_f32 v[66:67], v[66:67], v[66:67]
	v_add_f32_e32 v64, v64, v65
	v_add_f32_e32 v64, v66, v64
	v_add_f32_e32 v64, v67, v64
	v_cvt_pk_bf16_f32 v72, v72, v73
	v_cvt_pk_bf16_f32 v73, v74, v75
	v_add_f32_dpp v64, v64, v64 quad_perm:[1,0,3,2] row_mask:0xf bank_mask:0xf bound_ctrl:1
	global_store_dwordx2 v[76:77], v[72:73], off
	s_nop 0
	v_add_f32_dpp v64, v64, v64 quad_perm:[2,3,0,1] row_mask:0xf bank_mask:0xf bound_ctrl:1
	s_nop 1
	v_add_f32_dpp v64, v64, v64 row_half_mirror row_mask:0xf bank_mask:0xf bound_ctrl:1
	s_nop 1
	v_mov_b32_dpp v65, v64 row_mirror row_mask:0xf bank_mask:0xf bound_ctrl:1
	s_and_saveexec_b64 s[4:5], s[36:37]
	s_cbranch_execz .LBB0_685
	v_lshl_add_u64 v[66:67], s[52:53], 0, v[68:69]
	v_lshl_add_u64 v[66:67], v[100:101], 2, v[66:67]
	v_add_f32_e32 v64, v64, v65
	global_store_dword v[66:67], v64, off

.LBB0_686:
	v_or_b32_e32 v70, 4, v128
	v_or_b32_e32 v72, v96, v70
	v_ashrrev_i32_e32 v73, 31, v72
	v_lshlrev_b64 v[64:65], 12, v[72:73]
	v_lshl_add_u64 v[64:65], s[40:41], 0, v[64:65]
	v_lshl_add_u64 v[84:85], v[98:99], 2, v[64:65]
	s_movk_i32 s4, 0x1000
	v_mul_u32_u24_e32 v74, 0x110, v128
	v_cmp_gt_i32_e32 vcc, s4, v72
	v_add_u32_e32 v86, v74, v97
	s_nop 0
	v_cndmask_b32_e32 v74, v71, v102, vcc
	v_and_b32_e32 v74, 1, v74
	v_cmp_eq_u32_e32 vcc, 1, v74
	s_nop 1
	v_cndmask_b32_e64 v74, v171, 0, vcc
	v_add_u32_e32 v74, v103, v74
	ds_read_b128 v[76:79], v86 offset:1088
	ds_read_b128 v[80:83], v74
	s_and_b64 vcc, exec, s[0:1]
	s_waitcnt vmcnt(7) lgkmcnt(0)
	v_pk_fma_f32 v[66:67], v[78:79], v[82:83], v[204:205]
	v_pk_fma_f32 v[64:65], v[76:77], v[80:81], v[202:203]
	global_store_dwordx4 v[84:85], v[64:67], off
	s_cbranch_vccnz .LBB0_690
	ds_read_b128 v[74:77], v74 offset:2048
	v_lshlrev_b64 v[72:73], 10, v[72:73]
	v_lshl_add_u64 v[72:73], v[72:73], 1, s[42:43]
	v_lshl_add_u64 v[72:73], v[98:99], 1, v[72:73]
	s_waitcnt lgkmcnt(0)
	v_pk_mul_f32 v[74:75], v[64:65], v[74:75]
	v_pk_mul_f32 v[64:65], v[64:65], v[64:65]
	v_pk_mul_f32 v[76:77], v[66:67], v[76:77]
	v_pk_mul_f32 v[66:67], v[66:67], v[66:67]
	v_add_f32_e32 v64, v64, v65
	v_add_f32_e32 v64, v66, v64
	v_add_f32_e32 v64, v67, v64
	v_cvt_pk_bf16_f32 v74, v74, v75
	v_cvt_pk_bf16_f32 v75, v76, v77
	v_add_f32_dpp v64, v64, v64 quad_perm:[1,0,3,2] row_mask:0xf bank_mask:0xf bound_ctrl:1
	global_store_dwordx2 v[72:73], v[74:75], off
	s_nop 0
	v_add_f32_dpp v64, v64, v64 quad_perm:[2,3,0,1] row_mask:0xf bank_mask:0xf bound_ctrl:1
	s_nop 1
	v_add_f32_dpp v64, v64, v64 row_half_mirror row_mask:0xf bank_mask:0xf bound_ctrl:1
	s_nop 1
	v_mov_b32_dpp v65, v64 row_mirror row_mask:0xf bank_mask:0xf bound_ctrl:1
	s_and_saveexec_b64 s[4:5], s[36:37]
	s_cbranch_execz .LBB0_689
	v_ashrrev_i32_e32 v97, 31, v96
	v_lshl_add_u64 v[66:67], s[52:53], 0, v[68:69]
	v_lshl_add_u64 v[72:73], v[96:97], 0, v[128:129]
	v_lshl_add_u64 v[66:67], v[72:73], 2, v[66:67]
	v_add_f32_e32 v64, v64, v65
	global_store_dword v[66:67], v64, off offset:16

.LBB0_690:
	v_or_b32_e32 v72, 8, v128
	v_or_b32_e32 v74, v96, v72
	v_ashrrev_i32_e32 v75, 31, v74
	v_lshlrev_b64 v[64:65], 12, v[74:75]
	v_lshl_add_u64 v[64:65], s[40:41], 0, v[64:65]
	v_lshl_add_u64 v[84:85], v[98:99], 2, v[64:65]
	s_movk_i32 s4, 0x1000
	v_cmp_gt_i32_e32 vcc, s4, v74
	s_nop 1
	v_cndmask_b32_e32 v73, v71, v102, vcc
	v_and_b32_e32 v73, 1, v73
	v_cmp_eq_u32_e32 vcc, 1, v73
	s_nop 1
	v_cndmask_b32_e64 v73, v171, 0, vcc
	v_add_u32_e32 v73, v103, v73
	ds_read_b128 v[76:79], v86 offset:2176
	ds_read_b128 v[80:83], v73
	s_and_b64 vcc, exec, s[0:1]
	s_waitcnt vmcnt(7) lgkmcnt(0)
	v_pk_fma_f32 v[66:67], v[78:79], v[82:83], v[208:209]
	v_pk_fma_f32 v[64:65], v[76:77], v[80:81], v[206:207]
	global_store_dwordx4 v[84:85], v[64:67], off
	s_cbranch_vccnz .LBB0_694
	ds_read_b128 v[76:79], v73 offset:2048
	v_lshlrev_b64 v[74:75], 10, v[74:75]
	v_lshl_add_u64 v[74:75], v[74:75], 1, s[42:43]
	v_lshl_add_u64 v[74:75], v[98:99], 1, v[74:75]
	s_waitcnt lgkmcnt(0)
	v_pk_mul_f32 v[76:77], v[64:65], v[76:77]
	v_pk_mul_f32 v[64:65], v[64:65], v[64:65]
	v_pk_mul_f32 v[78:79], v[66:67], v[78:79]
	v_pk_mul_f32 v[66:67], v[66:67], v[66:67]
	v_add_f32_e32 v64, v64, v65
	v_add_f32_e32 v64, v66, v64
	v_add_f32_e32 v64, v67, v64
	v_cvt_pk_bf16_f32 v76, v76, v77
	v_cvt_pk_bf16_f32 v77, v78, v79
	v_add_f32_dpp v64, v64, v64 quad_perm:[1,0,3,2] row_mask:0xf bank_mask:0xf bound_ctrl:1
	global_store_dwordx2 v[74:75], v[76:77], off
	s_nop 0
	v_add_f32_dpp v64, v64, v64 quad_perm:[2,3,0,1] row_mask:0xf bank_mask:0xf bound_ctrl:1
	s_nop 1
	v_add_f32_dpp v64, v64, v64 row_half_mirror row_mask:0xf bank_mask:0xf bound_ctrl:1
	s_nop 1
	v_mov_b32_dpp v65, v64 row_mirror row_mask:0xf bank_mask:0xf bound_ctrl:1
	s_and_saveexec_b64 s[4:5], s[36:37]
	s_cbranch_execz .LBB0_693
	v_ashrrev_i32_e32 v97, 31, v96
	v_lshl_add_u64 v[66:67], s[52:53], 0, v[68:69]
	v_lshl_add_u64 v[74:75], v[96:97], 0, v[128:129]
	v_lshl_add_u64 v[66:67], v[74:75], 2, v[66:67]
	v_add_f32_e32 v64, v64, v65
	global_store_dword v[66:67], v64, off offset:32

.LBB0_694:
	v_or_b32_e32 v74, 12, v128
	v_or_b32_e32 v76, v96, v74
	v_ashrrev_i32_e32 v77, 31, v76
	v_lshlrev_b64 v[64:65], 12, v[76:77]
	v_lshl_add_u64 v[64:65], s[40:41], 0, v[64:65]
	v_lshl_add_u64 v[88:89], v[98:99], 2, v[64:65]
	s_movk_i32 s4, 0x1000
	v_cmp_gt_i32_e32 vcc, s4, v76
	s_nop 1
	v_cndmask_b32_e32 v73, v71, v102, vcc
	v_and_b32_e32 v73, 1, v73
	v_cmp_eq_u32_e32 vcc, 1, v73
	s_nop 1
	v_cndmask_b32_e64 v73, v171, 0, vcc
	v_add_u32_e32 v73, v103, v73
	ds_read_b128 v[78:81], v86 offset:3264
	ds_read_b128 v[82:85], v73
	s_and_b64 vcc, exec, s[0:1]
	s_waitcnt vmcnt(7) lgkmcnt(0)
	v_pk_fma_f32 v[66:67], v[80:81], v[84:85], v[212:213]
	v_pk_fma_f32 v[64:65], v[78:79], v[82:83], v[210:211]
	global_store_dwordx4 v[88:89], v[64:67], off
	s_cbranch_vccnz .LBB0_698
	ds_read_b128 v[78:81], v73 offset:2048
	v_lshlrev_b64 v[76:77], 10, v[76:77]
	v_lshl_add_u64 v[76:77], v[76:77], 1, s[42:43]
	v_lshl_add_u64 v[76:77], v[98:99], 1, v[76:77]
	s_waitcnt lgkmcnt(0)
	v_pk_mul_f32 v[78:79], v[64:65], v[78:79]
	v_pk_mul_f32 v[64:65], v[64:65], v[64:65]
	v_pk_mul_f32 v[80:81], v[66:67], v[80:81]
	v_pk_mul_f32 v[66:67], v[66:67], v[66:67]
	v_add_f32_e32 v64, v64, v65
	v_add_f32_e32 v64, v66, v64
	v_add_f32_e32 v64, v67, v64
	v_cvt_pk_bf16_f32 v78, v78, v79
	v_cvt_pk_bf16_f32 v79, v80, v81
	v_add_f32_dpp v64, v64, v64 quad_perm:[1,0,3,2] row_mask:0xf bank_mask:0xf bound_ctrl:1
	global_store_dwordx2 v[76:77], v[78:79], off
	s_nop 0
	v_add_f32_dpp v64, v64, v64 quad_perm:[2,3,0,1] row_mask:0xf bank_mask:0xf bound_ctrl:1
	s_nop 1
	v_add_f32_dpp v64, v64, v64 row_half_mirror row_mask:0xf bank_mask:0xf bound_ctrl:1
	s_nop 1
	v_mov_b32_dpp v65, v64 row_mirror row_mask:0xf bank_mask:0xf bound_ctrl:1
	s_and_saveexec_b64 s[4:5], s[36:37]
	s_cbranch_execz .LBB0_697
	v_ashrrev_i32_e32 v97, 31, v96
	v_lshl_add_u64 v[66:67], s[52:53], 0, v[68:69]
	v_lshl_add_u64 v[76:77], v[96:97], 0, v[128:129]
	v_lshl_add_u64 v[66:67], v[76:77], 2, v[66:67]
	v_add_f32_e32 v64, v64, v65
	global_store_dword v[66:67], v64, off offset:48

.LBB0_698:
	v_or_b32_e32 v76, 16, v128
	v_or_b32_e32 v78, v96, v76
	v_ashrrev_i32_e32 v79, 31, v78
	v_lshlrev_b64 v[64:65], 12, v[78:79]
	v_lshl_add_u64 v[64:65], s[40:41], 0, v[64:65]
	v_lshl_add_u64 v[84:85], v[98:99], 2, v[64:65]
	s_movk_i32 s4, 0x1000
	v_cmp_gt_i32_e32 vcc, s4, v78
	s_nop 1
	v_cndmask_b32_e32 v73, v71, v102, vcc
	v_and_b32_e32 v73, 1, v73
	v_cmp_eq_u32_e32 vcc, 1, v73
	s_nop 1
	v_cndmask_b32_e64 v73, v171, 0, vcc
	v_add_u32_e32 v73, v103, v73
	ds_read_b128 v[80:83], v86 offset:4352
	ds_read_b128 v[88:91], v73
	s_and_b64 vcc, exec, s[0:1]
	s_waitcnt vmcnt(7) lgkmcnt(0)
	v_pk_fma_f32 v[66:67], v[82:83], v[90:91], v[216:217]
	v_pk_fma_f32 v[64:65], v[80:81], v[88:89], v[214:215]
	global_store_dwordx4 v[84:85], v[64:67], off
	s_cbranch_vccnz .LBB0_702
	ds_read_b128 v[80:83], v73 offset:2048
	v_lshlrev_b64 v[78:79], 10, v[78:79]
	v_lshl_add_u64 v[78:79], v[78:79], 1, s[42:43]
	v_lshl_add_u64 v[78:79], v[98:99], 1, v[78:79]
	s_waitcnt lgkmcnt(0)
	v_pk_mul_f32 v[80:81], v[64:65], v[80:81]
	v_pk_mul_f32 v[64:65], v[64:65], v[64:65]
	v_pk_mul_f32 v[82:83], v[66:67], v[82:83]
	v_pk_mul_f32 v[66:67], v[66:67], v[66:67]
	v_add_f32_e32 v64, v64, v65
	v_add_f32_e32 v64, v66, v64
	v_add_f32_e32 v64, v67, v64
	v_cvt_pk_bf16_f32 v80, v80, v81
	v_cvt_pk_bf16_f32 v81, v82, v83
	v_add_f32_dpp v64, v64, v64 quad_perm:[1,0,3,2] row_mask:0xf bank_mask:0xf bound_ctrl:1
	global_store_dwordx2 v[78:79], v[80:81], off
	s_nop 0
	v_add_f32_dpp v64, v64, v64 quad_perm:[2,3,0,1] row_mask:0xf bank_mask:0xf bound_ctrl:1
	s_nop 1
	v_add_f32_dpp v64, v64, v64 row_half_mirror row_mask:0xf bank_mask:0xf bound_ctrl:1
	s_nop 1
	v_mov_b32_dpp v65, v64 row_mirror row_mask:0xf bank_mask:0xf bound_ctrl:1
	s_and_saveexec_b64 s[4:5], s[36:37]
	s_cbranch_execz .LBB0_701
	v_ashrrev_i32_e32 v97, 31, v96
	v_lshl_add_u64 v[66:67], s[52:53], 0, v[68:69]
	v_lshl_add_u64 v[78:79], v[96:97], 0, v[128:129]
	v_lshl_add_u64 v[66:67], v[78:79], 2, v[66:67]
	v_add_f32_e32 v64, v64, v65
	global_store_dword v[66:67], v64, off offset:64

.LBB0_702:
	v_or_b32_e32 v78, 20, v128
	v_or_b32_e32 v80, v96, v78
	v_ashrrev_i32_e32 v81, 31, v80
	v_lshlrev_b64 v[64:65], 12, v[80:81]
	v_lshl_add_u64 v[64:65], s[40:41], 0, v[64:65]
	v_lshl_add_u64 v[92:93], v[98:99], 2, v[64:65]
	s_movk_i32 s4, 0x1000
	v_cmp_gt_i32_e32 vcc, s4, v80
	s_nop 1
	v_cndmask_b32_e32 v73, v71, v102, vcc
	v_and_b32_e32 v73, 1, v73
	v_cmp_eq_u32_e32 vcc, 1, v73
	s_nop 1
	v_cndmask_b32_e64 v73, v171, 0, vcc
	v_add_u32_e32 v73, v103, v73
	ds_read_b128 v[82:85], v86 offset:5440
	ds_read_b128 v[88:91], v73
	s_and_b64 vcc, exec, s[0:1]
	s_waitcnt vmcnt(7) lgkmcnt(0)
	v_pk_fma_f32 v[66:67], v[84:85], v[90:91], v[220:221]
	v_pk_fma_f32 v[64:65], v[82:83], v[88:89], v[218:219]
	global_store_dwordx4 v[92:93], v[64:67], off
	s_cbranch_vccnz .LBB0_706
	ds_read_b128 v[82:85], v73 offset:2048
	v_lshlrev_b64 v[80:81], 10, v[80:81]
	v_lshl_add_u64 v[80:81], v[80:81], 1, s[42:43]
	v_lshl_add_u64 v[80:81], v[98:99], 1, v[80:81]
	s_waitcnt lgkmcnt(0)
	v_pk_mul_f32 v[82:83], v[64:65], v[82:83]
	v_pk_mul_f32 v[64:65], v[64:65], v[64:65]
	v_pk_mul_f32 v[84:85], v[66:67], v[84:85]
	v_pk_mul_f32 v[66:67], v[66:67], v[66:67]
	v_add_f32_e32 v64, v64, v65
	v_add_f32_e32 v64, v66, v64
	v_add_f32_e32 v64, v67, v64
	v_cvt_pk_bf16_f32 v82, v82, v83
	v_cvt_pk_bf16_f32 v83, v84, v85
	v_add_f32_dpp v64, v64, v64 quad_perm:[1,0,3,2] row_mask:0xf bank_mask:0xf bound_ctrl:1
	global_store_dwordx2 v[80:81], v[82:83], off
	s_nop 0
	v_add_f32_dpp v64, v64, v64 quad_perm:[2,3,0,1] row_mask:0xf bank_mask:0xf bound_ctrl:1
	s_nop 1
	v_add_f32_dpp v64, v64, v64 row_half_mirror row_mask:0xf bank_mask:0xf bound_ctrl:1
	s_nop 1
	v_mov_b32_dpp v65, v64 row_mirror row_mask:0xf bank_mask:0xf bound_ctrl:1
	s_and_saveexec_b64 s[4:5], s[36:37]
	s_cbranch_execz .LBB0_705
	v_ashrrev_i32_e32 v97, 31, v96
	v_lshl_add_u64 v[66:67], s[52:53], 0, v[68:69]
	v_lshl_add_u64 v[80:81], v[96:97], 0, v[128:129]
	v_lshl_add_u64 v[66:67], v[80:81], 2, v[66:67]
	v_add_f32_e32 v64, v64, v65
	global_store_dword v[66:67], v64, off offset:80

.LBB0_706:
	v_or_b32_e32 v80, 24, v128
	v_or_b32_e32 v82, v96, v80
	v_ashrrev_i32_e32 v83, 31, v82
	v_lshlrev_b64 v[64:65], 12, v[82:83]
	v_lshl_add_u64 v[64:65], s[40:41], 0, v[64:65]
	v_lshl_add_u64 v[84:85], v[98:99], 2, v[64:65]
	s_movk_i32 s4, 0x1000
	v_cmp_gt_i32_e32 vcc, s4, v82
	s_nop 1
	v_cndmask_b32_e32 v73, v71, v102, vcc
	v_and_b32_e32 v73, 1, v73
	v_cmp_eq_u32_e32 vcc, 1, v73
	s_nop 1
	v_cndmask_b32_e64 v73, v171, 0, vcc
	v_add_u32_e32 v73, v103, v73
	ds_read_b128 v[88:91], v86 offset:6528
	ds_read_b128 v[92:95], v73
	s_and_b64 vcc, exec, s[0:1]
	s_waitcnt vmcnt(7) lgkmcnt(0)
	v_pk_fma_f32 v[66:67], v[90:91], v[94:95], v[224:225]
	v_pk_fma_f32 v[64:65], v[88:89], v[92:93], v[222:223]
	global_store_dwordx4 v[84:85], v[64:67], off
	s_cbranch_vccnz .LBB0_710
	ds_read_b128 v[88:91], v73 offset:2048
	v_lshlrev_b64 v[82:83], 10, v[82:83]
	v_lshl_add_u64 v[82:83], v[82:83], 1, s[42:43]
	v_lshl_add_u64 v[82:83], v[98:99], 1, v[82:83]
	s_waitcnt lgkmcnt(0)
	v_pk_mul_f32 v[88:89], v[64:65], v[88:89]
	v_pk_mul_f32 v[64:65], v[64:65], v[64:65]
	v_pk_mul_f32 v[84:85], v[66:67], v[90:91]
	v_pk_mul_f32 v[66:67], v[66:67], v[66:67]
	v_add_f32_e32 v64, v64, v65
	v_add_f32_e32 v64, v66, v64
	v_add_f32_e32 v64, v67, v64
	v_cvt_pk_bf16_f32 v88, v88, v89
	v_cvt_pk_bf16_f32 v89, v84, v85
	v_add_f32_dpp v64, v64, v64 quad_perm:[1,0,3,2] row_mask:0xf bank_mask:0xf bound_ctrl:1
	global_store_dwordx2 v[82:83], v[88:89], off
	s_nop 0
	v_add_f32_dpp v64, v64, v64 quad_perm:[2,3,0,1] row_mask:0xf bank_mask:0xf bound_ctrl:1
	s_nop 1
	v_add_f32_dpp v64, v64, v64 row_half_mirror row_mask:0xf bank_mask:0xf bound_ctrl:1
	s_nop 1
	v_mov_b32_dpp v65, v64 row_mirror row_mask:0xf bank_mask:0xf bound_ctrl:1
	s_and_saveexec_b64 s[4:5], s[36:37]
	s_cbranch_execz .LBB0_709
	v_ashrrev_i32_e32 v97, 31, v96
	v_lshl_add_u64 v[66:67], s[52:53], 0, v[68:69]
	v_lshl_add_u64 v[82:83], v[96:97], 0, v[128:129]
	v_lshl_add_u64 v[66:67], v[82:83], 2, v[66:67]
	v_add_f32_e32 v64, v64, v65
	global_store_dword v[66:67], v64, off offset:96

.LBB0_710:
	v_or_b32_e32 v82, 28, v128
	v_or_b32_e32 v84, v96, v82
	v_ashrrev_i32_e32 v85, 31, v84
	v_lshlrev_b64 v[64:65], 12, v[84:85]
	v_lshl_add_u64 v[64:65], s[40:41], 0, v[64:65]
	v_lshl_add_u64 v[100:101], v[98:99], 2, v[64:65]
	s_movk_i32 s4, 0x1000
	v_cmp_gt_i32_e32 vcc, s4, v84
	s_nop 1
	v_cndmask_b32_e32 v71, v71, v102, vcc
	v_and_b32_e32 v71, 1, v71
	v_cmp_eq_u32_e32 vcc, 1, v71
	s_nop 1
	v_cndmask_b32_e64 v71, v171, 0, vcc
	v_add_u32_e32 v71, v103, v71
	ds_read_b128 v[88:91], v86 offset:7616
	ds_read_b128 v[92:95], v71
	s_and_b64 vcc, exec, s[0:1]
	s_waitcnt vmcnt(7) lgkmcnt(0)
	v_pk_fma_f32 v[66:67], v[90:91], v[94:95], v[228:229]
	v_pk_fma_f32 v[64:65], v[88:89], v[92:93], v[226:227]
	global_store_dwordx4 v[100:101], v[64:67], off
	s_cbranch_vccnz .LBB0_714
	ds_read_b128 v[88:91], v71 offset:2048
	v_lshlrev_b64 v[84:85], 10, v[84:85]
	v_lshl_add_u64 v[84:85], v[84:85], 1, s[42:43]
	v_lshl_add_u64 v[84:85], v[98:99], 1, v[84:85]
	s_waitcnt lgkmcnt(0)
	v_pk_mul_f32 v[88:89], v[64:65], v[88:89]
	v_pk_mul_f32 v[64:65], v[64:65], v[64:65]
	v_pk_mul_f32 v[90:91], v[66:67], v[90:91]
	v_pk_mul_f32 v[66:67], v[66:67], v[66:67]
	v_add_f32_e32 v64, v64, v65
	v_add_f32_e32 v64, v66, v64
	v_add_f32_e32 v64, v67, v64
	v_cvt_pk_bf16_f32 v88, v88, v89
	v_cvt_pk_bf16_f32 v89, v90, v91
	v_add_f32_dpp v64, v64, v64 quad_perm:[1,0,3,2] row_mask:0xf bank_mask:0xf bound_ctrl:1
	global_store_dwordx2 v[84:85], v[88:89], off
	s_nop 0
	v_add_f32_dpp v64, v64, v64 quad_perm:[2,3,0,1] row_mask:0xf bank_mask:0xf bound_ctrl:1
	s_nop 1
	v_add_f32_dpp v64, v64, v64 row_half_mirror row_mask:0xf bank_mask:0xf bound_ctrl:1
	s_nop 1
	v_mov_b32_dpp v65, v64 row_mirror row_mask:0xf bank_mask:0xf bound_ctrl:1
	s_and_saveexec_b64 s[4:5], s[36:37]
	s_cbranch_execz .LBB0_713
	v_ashrrev_i32_e32 v97, 31, v96
	v_lshl_add_u64 v[66:67], s[52:53], 0, v[68:69]
	v_lshl_add_u64 v[84:85], v[96:97], 0, v[128:129]
	v_lshl_add_u64 v[66:67], v[84:85], 2, v[66:67]
	v_add_f32_e32 v64, v64, v65
	global_store_dword v[66:67], v64, off offset:112

.LBB0_714:
	s_nop 0
	v_add_u32_e32 v66, 32, v96
	v_or_b32_e32 v64, v66, v128
	v_ashrrev_i32_e32 v65, 31, v64
	v_lshlrev_b64 v[84:85], 12, v[64:65]
	v_lshl_add_u64 v[84:85], s[40:41], 0, v[84:85]
	v_lshl_add_u64 v[84:85], v[98:99], 2, v[84:85]
	global_load_dwordx4 v[198:201], v[84:85], off
	v_add_co_u32_e32 v182, vcc, 0x4000, v84
	s_nop 1
	v_addc_co_u32_e32 v183, vcc, 0, v85, vcc
	global_load_dwordx4 v[202:205], v[182:183], off
	v_add_co_u32_e32 v182, vcc, 0x4000, v182
	s_nop 1
	v_addc_co_u32_e32 v183, vcc, 0, v183, vcc
	global_load_dwordx4 v[206:209], v[182:183], off
	v_add_co_u32_e32 v182, vcc, 0x4000, v182
	s_nop 1
	v_addc_co_u32_e32 v183, vcc, 0, v183, vcc
	global_load_dwordx4 v[210:213], v[182:183], off
	v_add_co_u32_e32 v182, vcc, 0x4000, v182
	s_nop 1
	v_addc_co_u32_e32 v183, vcc, 0, v183, vcc
	global_load_dwordx4 v[214:217], v[182:183], off
	v_add_co_u32_e32 v182, vcc, 0x4000, v182
	s_nop 1
	v_addc_co_u32_e32 v183, vcc, 0, v183, vcc
	global_load_dwordx4 v[218:221], v[182:183], off
	v_add_co_u32_e32 v182, vcc, 0x4000, v182
	s_nop 1
	v_addc_co_u32_e32 v183, vcc, 0, v183, vcc
	global_load_dwordx4 v[222:225], v[182:183], off
	v_add_co_u32_e32 v182, vcc, 0x4000, v182
	s_nop 1
	v_addc_co_u32_e32 v183, vcc, 0, v183, vcc
	global_load_dwordx4 v[226:229], v[182:183], off
	ds_write_b128 v104, v[32:35]
	ds_write_b128 v104, v[36:39] offset:32
	ds_write_b128 v104, v[40:43] offset:64
	ds_write_b128 v104, v[44:47] offset:96
	ds_write_b128 v104, v[48:51] offset:128
	ds_write_b128 v104, v[52:55] offset:160
	ds_write_b128 v104, v[56:59] offset:192
	ds_write_b128 v104, v[60:63] offset:224
	v_add_u32_e32 v32, 0xfffff020, v96
	v_xor_b32_e32 v32, s7, v32
	s_movk_i32 s4, 0x400
	v_cmp_gt_u32_e32 vcc, s4, v32
	s_and_b64 s[4:5], s[2:3], vcc
	v_cndmask_b32_e64 v38, 0, 1, s[4:5]
	s_movk_i32 s4, 0x1000
	v_cmp_gt_i32_e32 vcc, s4, v64
	s_nop 1
	v_cndmask_b32_e32 v32, v38, v102, vcc
	v_and_b32_e32 v32, 1, v32
	v_cmp_eq_u32_e32 vcc, 1, v32
	s_nop 1
	v_cndmask_b32_e64 v32, v171, 0, vcc
	v_add_u32_e32 v36, v103, v32
	ds_read_b128 v[32:35], v86
	ds_read_b128 v[40:43], v36
	s_and_b64 vcc, exec, s[0:1]
	s_waitcnt vmcnt(7) lgkmcnt(0)
	v_pk_fma_f32 v[34:35], v[34:35], v[42:43], v[200:201]
	v_pk_fma_f32 v[32:33], v[32:33], v[40:41], v[198:199]
	global_store_dwordx4 v[84:85], v[32:35], off
	s_cbranch_vccnz .LBB0_718
	ds_read_b128 v[40:43], v36 offset:2048
	v_lshlrev_b64 v[36:37], 10, v[64:65]
	v_lshl_add_u64 v[36:37], v[36:37], 1, s[42:43]
	v_lshl_add_u64 v[36:37], v[98:99], 1, v[36:37]
	s_waitcnt lgkmcnt(0)
	v_pk_mul_f32 v[40:41], v[32:33], v[40:41]
	v_pk_mul_f32 v[32:33], v[32:33], v[32:33]
	v_pk_mul_f32 v[42:43], v[34:35], v[42:43]
	v_pk_mul_f32 v[34:35], v[34:35], v[34:35]
	v_add_f32_e32 v32, v32, v33
	v_add_f32_e32 v32, v34, v32
	v_add_f32_e32 v32, v35, v32
	v_cvt_pk_bf16_f32 v40, v40, v41
	v_cvt_pk_bf16_f32 v41, v42, v43
	v_add_f32_dpp v32, v32, v32 quad_perm:[1,0,3,2] row_mask:0xf bank_mask:0xf bound_ctrl:1
	global_store_dwordx2 v[36:37], v[40:41], off
	s_nop 0
	v_add_f32_dpp v32, v32, v32 quad_perm:[2,3,0,1] row_mask:0xf bank_mask:0xf bound_ctrl:1
	s_nop 1
	v_add_f32_dpp v32, v32, v32 row_half_mirror row_mask:0xf bank_mask:0xf bound_ctrl:1
	s_nop 1
	v_mov_b32_dpp v33, v32 row_mirror row_mask:0xf bank_mask:0xf bound_ctrl:1
	s_and_saveexec_b64 s[4:5], s[36:37]
	s_cbranch_execz .LBB0_717
	v_ashrrev_i32_e32 v97, 31, v96
	v_lshl_add_u64 v[34:35], s[52:53], 0, v[68:69]
	v_lshl_add_u64 v[36:37], v[96:97], 0, v[128:129]
	v_lshl_add_u64 v[34:35], v[36:37], 2, v[34:35]
	v_add_f32_e32 v32, v32, v33
	global_store_dword v[34:35], v32, off offset:128

.LBB0_718:
	v_or_b32_e32 v36, v66, v70
	v_ashrrev_i32_e32 v37, 31, v36
	v_lshlrev_b64 v[32:33], 12, v[36:37]
	v_lshl_add_u64 v[32:33], s[40:41], 0, v[32:33]
	v_lshl_add_u64 v[48:49], v[98:99], 2, v[32:33]
	s_movk_i32 s4, 0x1000
	v_cmp_gt_i32_e32 vcc, s4, v36
	s_nop 1
	v_cndmask_b32_e32 v39, v38, v102, vcc
	v_and_b32_e32 v39, 1, v39
	v_cmp_eq_u32_e32 vcc, 1, v39
	s_nop 1
	v_cndmask_b32_e64 v39, v171, 0, vcc
	v_add_u32_e32 v39, v103, v39
	ds_read_b128 v[40:43], v86 offset:1088
	ds_read_b128 v[44:47], v39
	s_and_b64 vcc, exec, s[0:1]
	s_waitcnt vmcnt(7) lgkmcnt(0)
	v_pk_fma_f32 v[34:35], v[42:43], v[46:47], v[204:205]
	v_pk_fma_f32 v[32:33], v[40:41], v[44:45], v[202:203]
	global_store_dwordx4 v[48:49], v[32:35], off
	s_cbranch_vccnz .LBB0_722
	ds_read_b128 v[40:43], v39 offset:2048
	v_lshlrev_b64 v[36:37], 10, v[36:37]
	v_lshl_add_u64 v[36:37], v[36:37], 1, s[42:43]
	v_lshl_add_u64 v[36:37], v[98:99], 1, v[36:37]
	s_waitcnt lgkmcnt(0)
	v_pk_mul_f32 v[40:41], v[32:33], v[40:41]
	v_pk_mul_f32 v[32:33], v[32:33], v[32:33]
	v_pk_mul_f32 v[42:43], v[34:35], v[42:43]
	v_pk_mul_f32 v[34:35], v[34:35], v[34:35]
	v_add_f32_e32 v32, v32, v33
	v_add_f32_e32 v32, v34, v32
	v_add_f32_e32 v32, v35, v32
	v_cvt_pk_bf16_f32 v40, v40, v41
	v_cvt_pk_bf16_f32 v41, v42, v43
	v_add_f32_dpp v32, v32, v32 quad_perm:[1,0,3,2] row_mask:0xf bank_mask:0xf bound_ctrl:1
	global_store_dwordx2 v[36:37], v[40:41], off
	s_nop 0
	v_add_f32_dpp v32, v32, v32 quad_perm:[2,3,0,1] row_mask:0xf bank_mask:0xf bound_ctrl:1
	s_nop 1
	v_add_f32_dpp v32, v32, v32 row_half_mirror row_mask:0xf bank_mask:0xf bound_ctrl:1
	s_nop 1
	v_mov_b32_dpp v33, v32 row_mirror row_mask:0xf bank_mask:0xf bound_ctrl:1
	s_and_saveexec_b64 s[4:5], s[36:37]
	s_cbranch_execz .LBB0_721
	v_mov_b32_e32 v71, v129
	v_ashrrev_i32_e32 v97, 31, v96
	v_lshl_add_u64 v[34:35], s[52:53], 0, v[68:69]
	v_lshl_add_u64 v[36:37], v[96:97], 0, v[70:71]
	v_lshl_add_u64 v[34:35], v[36:37], 2, v[34:35]
	v_add_f32_e32 v32, v32, v33
	global_store_dword v[34:35], v32, off offset:128

.LBB0_722:
	v_or_b32_e32 v36, v66, v72
	v_ashrrev_i32_e32 v37, 31, v36
	v_lshlrev_b64 v[32:33], 12, v[36:37]
	v_lshl_add_u64 v[32:33], s[40:41], 0, v[32:33]
	v_lshl_add_u64 v[48:49], v[98:99], 2, v[32:33]
	s_movk_i32 s4, 0x1000
	v_cmp_gt_i32_e32 vcc, s4, v36
	s_nop 1
	v_cndmask_b32_e32 v39, v38, v102, vcc
	v_and_b32_e32 v39, 1, v39
	v_cmp_eq_u32_e32 vcc, 1, v39
	s_nop 1
	v_cndmask_b32_e64 v39, v171, 0, vcc
	v_add_u32_e32 v39, v103, v39
	ds_read_b128 v[40:43], v86 offset:2176
	ds_read_b128 v[44:47], v39
	s_and_b64 vcc, exec, s[0:1]
	s_waitcnt vmcnt(7) lgkmcnt(0)
	v_pk_fma_f32 v[34:35], v[42:43], v[46:47], v[208:209]
	v_pk_fma_f32 v[32:33], v[40:41], v[44:45], v[206:207]
	global_store_dwordx4 v[48:49], v[32:35], off
	s_cbranch_vccnz .LBB0_726
	ds_read_b128 v[40:43], v39 offset:2048
	v_lshlrev_b64 v[36:37], 10, v[36:37]
	v_lshl_add_u64 v[36:37], v[36:37], 1, s[42:43]
	v_lshl_add_u64 v[36:37], v[98:99], 1, v[36:37]
	s_waitcnt lgkmcnt(0)
	v_pk_mul_f32 v[40:41], v[32:33], v[40:41]
	v_pk_mul_f32 v[32:33], v[32:33], v[32:33]
	v_pk_mul_f32 v[42:43], v[34:35], v[42:43]
	v_pk_mul_f32 v[34:35], v[34:35], v[34:35]
	v_add_f32_e32 v32, v32, v33
	v_add_f32_e32 v32, v34, v32
	v_add_f32_e32 v32, v35, v32
	v_cvt_pk_bf16_f32 v40, v40, v41
	v_cvt_pk_bf16_f32 v41, v42, v43
	v_add_f32_dpp v32, v32, v32 quad_perm:[1,0,3,2] row_mask:0xf bank_mask:0xf bound_ctrl:1
	global_store_dwordx2 v[36:37], v[40:41], off
	s_nop 0
	v_add_f32_dpp v32, v32, v32 quad_perm:[2,3,0,1] row_mask:0xf bank_mask:0xf bound_ctrl:1
	s_nop 1
	v_add_f32_dpp v32, v32, v32 row_half_mirror row_mask:0xf bank_mask:0xf bound_ctrl:1
	s_nop 1
	v_mov_b32_dpp v33, v32 row_mirror row_mask:0xf bank_mask:0xf bound_ctrl:1
	s_and_saveexec_b64 s[4:5], s[36:37]
	s_cbranch_execz .LBB0_725
	v_mov_b32_e32 v73, v129
	v_ashrrev_i32_e32 v97, 31, v96
	v_lshl_add_u64 v[34:35], s[52:53], 0, v[68:69]
	v_lshl_add_u64 v[36:37], v[96:97], 0, v[72:73]
	v_lshl_add_u64 v[34:35], v[36:37], 2, v[34:35]
	v_add_f32_e32 v32, v32, v33
	global_store_dword v[34:35], v32, off offset:128

.LBB0_726:
	v_or_b32_e32 v36, v66, v74
	v_ashrrev_i32_e32 v37, 31, v36
	v_lshlrev_b64 v[32:33], 12, v[36:37]
	v_lshl_add_u64 v[32:33], s[40:41], 0, v[32:33]
	v_lshl_add_u64 v[48:49], v[98:99], 2, v[32:33]
	s_movk_i32 s4, 0x1000
	v_cmp_gt_i32_e32 vcc, s4, v36
	s_nop 1
	v_cndmask_b32_e32 v39, v38, v102, vcc
	v_and_b32_e32 v39, 1, v39
	v_cmp_eq_u32_e32 vcc, 1, v39
	s_nop 1
	v_cndmask_b32_e64 v39, v171, 0, vcc
	v_add_u32_e32 v39, v103, v39
	ds_read_b128 v[40:43], v86 offset:3264
	ds_read_b128 v[44:47], v39
	s_and_b64 vcc, exec, s[0:1]
	s_waitcnt vmcnt(7) lgkmcnt(0)
	v_pk_fma_f32 v[34:35], v[42:43], v[46:47], v[212:213]
	v_pk_fma_f32 v[32:33], v[40:41], v[44:45], v[210:211]
	global_store_dwordx4 v[48:49], v[32:35], off
	s_cbranch_vccnz .LBB0_730
	ds_read_b128 v[40:43], v39 offset:2048
	v_lshlrev_b64 v[36:37], 10, v[36:37]
	v_lshl_add_u64 v[36:37], v[36:37], 1, s[42:43]
	v_lshl_add_u64 v[36:37], v[98:99], 1, v[36:37]
	s_waitcnt lgkmcnt(0)
	v_pk_mul_f32 v[40:41], v[32:33], v[40:41]
	v_pk_mul_f32 v[32:33], v[32:33], v[32:33]
	v_pk_mul_f32 v[42:43], v[34:35], v[42:43]
	v_pk_mul_f32 v[34:35], v[34:35], v[34:35]
	v_add_f32_e32 v32, v32, v33
	v_add_f32_e32 v32, v34, v32
	v_add_f32_e32 v32, v35, v32
	v_cvt_pk_bf16_f32 v40, v40, v41
	v_cvt_pk_bf16_f32 v41, v42, v43
	v_add_f32_dpp v32, v32, v32 quad_perm:[1,0,3,2] row_mask:0xf bank_mask:0xf bound_ctrl:1
	global_store_dwordx2 v[36:37], v[40:41], off
	s_nop 0
	v_add_f32_dpp v32, v32, v32 quad_perm:[2,3,0,1] row_mask:0xf bank_mask:0xf bound_ctrl:1
	s_nop 1
	v_add_f32_dpp v32, v32, v32 row_half_mirror row_mask:0xf bank_mask:0xf bound_ctrl:1
	s_nop 1
	v_mov_b32_dpp v33, v32 row_mirror row_mask:0xf bank_mask:0xf bound_ctrl:1
	s_and_saveexec_b64 s[4:5], s[36:37]
	s_cbranch_execz .LBB0_729
	v_mov_b32_e32 v75, v129
	v_ashrrev_i32_e32 v97, 31, v96
	v_lshl_add_u64 v[34:35], s[52:53], 0, v[68:69]
	v_lshl_add_u64 v[36:37], v[96:97], 0, v[74:75]
	v_lshl_add_u64 v[34:35], v[36:37], 2, v[34:35]
	v_add_f32_e32 v32, v32, v33
	global_store_dword v[34:35], v32, off offset:128

.LBB0_730:
	v_or_b32_e32 v36, v66, v76
	v_ashrrev_i32_e32 v37, 31, v36
	v_lshlrev_b64 v[32:33], 12, v[36:37]
	v_lshl_add_u64 v[32:33], s[40:41], 0, v[32:33]
	v_lshl_add_u64 v[48:49], v[98:99], 2, v[32:33]
	s_movk_i32 s4, 0x1000
	v_cmp_gt_i32_e32 vcc, s4, v36
	s_nop 1
	v_cndmask_b32_e32 v39, v38, v102, vcc
	v_and_b32_e32 v39, 1, v39
	v_cmp_eq_u32_e32 vcc, 1, v39
	s_nop 1
	v_cndmask_b32_e64 v39, v171, 0, vcc
	v_add_u32_e32 v39, v103, v39
	ds_read_b128 v[40:43], v86 offset:4352
	ds_read_b128 v[44:47], v39
	s_and_b64 vcc, exec, s[0:1]
	s_waitcnt vmcnt(7) lgkmcnt(0)
	v_pk_fma_f32 v[34:35], v[42:43], v[46:47], v[216:217]
	v_pk_fma_f32 v[32:33], v[40:41], v[44:45], v[214:215]
	global_store_dwordx4 v[48:49], v[32:35], off
	s_cbranch_vccnz .LBB0_734
	ds_read_b128 v[40:43], v39 offset:2048
	v_lshlrev_b64 v[36:37], 10, v[36:37]
	v_lshl_add_u64 v[36:37], v[36:37], 1, s[42:43]
	v_lshl_add_u64 v[36:37], v[98:99], 1, v[36:37]
	s_waitcnt lgkmcnt(0)
	v_pk_mul_f32 v[40:41], v[32:33], v[40:41]
	v_pk_mul_f32 v[32:33], v[32:33], v[32:33]
	v_pk_mul_f32 v[42:43], v[34:35], v[42:43]
	v_pk_mul_f32 v[34:35], v[34:35], v[34:35]
	v_add_f32_e32 v32, v32, v33
	v_add_f32_e32 v32, v34, v32
	v_add_f32_e32 v32, v35, v32
	v_cvt_pk_bf16_f32 v40, v40, v41
	v_cvt_pk_bf16_f32 v41, v42, v43
	v_add_f32_dpp v32, v32, v32 quad_perm:[1,0,3,2] row_mask:0xf bank_mask:0xf bound_ctrl:1
	global_store_dwordx2 v[36:37], v[40:41], off
	s_nop 0
	v_add_f32_dpp v32, v32, v32 quad_perm:[2,3,0,1] row_mask:0xf bank_mask:0xf bound_ctrl:1
	s_nop 1
	v_add_f32_dpp v32, v32, v32 row_half_mirror row_mask:0xf bank_mask:0xf bound_ctrl:1
	s_nop 1
	v_mov_b32_dpp v33, v32 row_mirror row_mask:0xf bank_mask:0xf bound_ctrl:1
	s_and_saveexec_b64 s[4:5], s[36:37]
	s_cbranch_execz .LBB0_733
	v_mov_b32_e32 v77, v129
	v_ashrrev_i32_e32 v97, 31, v96
	v_lshl_add_u64 v[34:35], s[52:53], 0, v[68:69]
	v_lshl_add_u64 v[36:37], v[96:97], 0, v[76:77]
	v_lshl_add_u64 v[34:35], v[36:37], 2, v[34:35]
	v_add_f32_e32 v32, v32, v33
	global_store_dword v[34:35], v32, off offset:128

.LBB0_734:
	v_or_b32_e32 v36, v66, v78
	v_ashrrev_i32_e32 v37, 31, v36
	v_lshlrev_b64 v[32:33], 12, v[36:37]
	v_lshl_add_u64 v[32:33], s[40:41], 0, v[32:33]
	v_lshl_add_u64 v[48:49], v[98:99], 2, v[32:33]
	s_movk_i32 s4, 0x1000
	v_cmp_gt_i32_e32 vcc, s4, v36
	s_nop 1
	v_cndmask_b32_e32 v39, v38, v102, vcc
	v_and_b32_e32 v39, 1, v39
	v_cmp_eq_u32_e32 vcc, 1, v39
	s_nop 1
	v_cndmask_b32_e64 v39, v171, 0, vcc
	v_add_u32_e32 v39, v103, v39
	ds_read_b128 v[40:43], v86 offset:5440
	ds_read_b128 v[44:47], v39
	s_and_b64 vcc, exec, s[0:1]
	s_waitcnt vmcnt(7) lgkmcnt(0)
	v_pk_fma_f32 v[34:35], v[42:43], v[46:47], v[220:221]
	v_pk_fma_f32 v[32:33], v[40:41], v[44:45], v[218:219]
	global_store_dwordx4 v[48:49], v[32:35], off
	s_cbranch_vccnz .LBB0_738
	ds_read_b128 v[40:43], v39 offset:2048
	v_lshlrev_b64 v[36:37], 10, v[36:37]
	v_lshl_add_u64 v[36:37], v[36:37], 1, s[42:43]
	v_lshl_add_u64 v[36:37], v[98:99], 1, v[36:37]
	s_waitcnt lgkmcnt(0)
	v_pk_mul_f32 v[40:41], v[32:33], v[40:41]
	v_pk_mul_f32 v[32:33], v[32:33], v[32:33]
	v_pk_mul_f32 v[42:43], v[34:35], v[42:43]
	v_pk_mul_f32 v[34:35], v[34:35], v[34:35]
	v_add_f32_e32 v32, v32, v33
	v_add_f32_e32 v32, v34, v32
	v_add_f32_e32 v32, v35, v32
	v_cvt_pk_bf16_f32 v40, v40, v41
	v_cvt_pk_bf16_f32 v41, v42, v43
	v_add_f32_dpp v32, v32, v32 quad_perm:[1,0,3,2] row_mask:0xf bank_mask:0xf bound_ctrl:1
	global_store_dwordx2 v[36:37], v[40:41], off
	s_nop 0
	v_add_f32_dpp v32, v32, v32 quad_perm:[2,3,0,1] row_mask:0xf bank_mask:0xf bound_ctrl:1
	s_nop 1
	v_add_f32_dpp v32, v32, v32 row_half_mirror row_mask:0xf bank_mask:0xf bound_ctrl:1
	s_nop 1
	v_mov_b32_dpp v33, v32 row_mirror row_mask:0xf bank_mask:0xf bound_ctrl:1
	s_and_saveexec_b64 s[4:5], s[36:37]
	s_cbranch_execz .LBB0_737
	v_mov_b32_e32 v79, v129
	v_ashrrev_i32_e32 v97, 31, v96
	v_lshl_add_u64 v[34:35], s[52:53], 0, v[68:69]
	v_lshl_add_u64 v[36:37], v[96:97], 0, v[78:79]
	v_lshl_add_u64 v[34:35], v[36:37], 2, v[34:35]
	v_add_f32_e32 v32, v32, v33
	global_store_dword v[34:35], v32, off offset:128

.LBB0_738:
	v_or_b32_e32 v36, v66, v80
	v_ashrrev_i32_e32 v37, 31, v36
	v_lshlrev_b64 v[32:33], 12, v[36:37]
	v_lshl_add_u64 v[32:33], s[40:41], 0, v[32:33]
	v_lshl_add_u64 v[48:49], v[98:99], 2, v[32:33]
	s_movk_i32 s4, 0x1000
	v_cmp_gt_i32_e32 vcc, s4, v36
	s_nop 1
	v_cndmask_b32_e32 v39, v38, v102, vcc
	v_and_b32_e32 v39, 1, v39
	v_cmp_eq_u32_e32 vcc, 1, v39
	s_nop 1
	v_cndmask_b32_e64 v39, v171, 0, vcc
	v_add_u32_e32 v39, v103, v39
	ds_read_b128 v[40:43], v86 offset:6528
	ds_read_b128 v[44:47], v39
	s_and_b64 vcc, exec, s[0:1]
	s_waitcnt vmcnt(7) lgkmcnt(0)
	v_pk_fma_f32 v[34:35], v[42:43], v[46:47], v[224:225]
	v_pk_fma_f32 v[32:33], v[40:41], v[44:45], v[222:223]
	global_store_dwordx4 v[48:49], v[32:35], off
	s_cbranch_vccnz .LBB0_742
	ds_read_b128 v[40:43], v39 offset:2048
	v_lshlrev_b64 v[36:37], 10, v[36:37]
	v_lshl_add_u64 v[36:37], v[36:37], 1, s[42:43]
	v_lshl_add_u64 v[36:37], v[98:99], 1, v[36:37]
	s_waitcnt lgkmcnt(0)
	v_pk_mul_f32 v[40:41], v[32:33], v[40:41]
	v_pk_mul_f32 v[32:33], v[32:33], v[32:33]
	v_pk_mul_f32 v[42:43], v[34:35], v[42:43]
	v_pk_mul_f32 v[34:35], v[34:35], v[34:35]
	v_add_f32_e32 v32, v32, v33
	v_add_f32_e32 v32, v34, v32
	v_add_f32_e32 v32, v35, v32
	v_cvt_pk_bf16_f32 v40, v40, v41
	v_cvt_pk_bf16_f32 v41, v42, v43
	v_add_f32_dpp v32, v32, v32 quad_perm:[1,0,3,2] row_mask:0xf bank_mask:0xf bound_ctrl:1
	global_store_dwordx2 v[36:37], v[40:41], off
	s_nop 0
	v_add_f32_dpp v32, v32, v32 quad_perm:[2,3,0,1] row_mask:0xf bank_mask:0xf bound_ctrl:1
	s_nop 1
	v_add_f32_dpp v32, v32, v32 row_half_mirror row_mask:0xf bank_mask:0xf bound_ctrl:1
	s_nop 1
	v_mov_b32_dpp v33, v32 row_mirror row_mask:0xf bank_mask:0xf bound_ctrl:1
	s_and_saveexec_b64 s[4:5], s[36:37]
	s_cbranch_execz .LBB0_741
	v_mov_b32_e32 v81, v129
	v_ashrrev_i32_e32 v97, 31, v96
	v_lshl_add_u64 v[34:35], s[52:53], 0, v[68:69]
	v_lshl_add_u64 v[36:37], v[96:97], 0, v[80:81]
	v_lshl_add_u64 v[34:35], v[36:37], 2, v[34:35]
	v_add_f32_e32 v32, v32, v33
	global_store_dword v[34:35], v32, off offset:128

.LBB0_742:
	v_or_b32_e32 v36, v66, v82
	v_ashrrev_i32_e32 v37, 31, v36
	v_lshlrev_b64 v[32:33], 12, v[36:37]
	v_lshl_add_u64 v[32:33], s[40:41], 0, v[32:33]
	v_lshl_add_u64 v[48:49], v[98:99], 2, v[32:33]
	s_movk_i32 s4, 0x1000
	v_cmp_gt_i32_e32 vcc, s4, v36
	s_nop 1
	v_cndmask_b32_e32 v38, v38, v102, vcc
	v_and_b32_e32 v38, 1, v38
	v_cmp_eq_u32_e32 vcc, 1, v38
	s_nop 1
	v_cndmask_b32_e64 v38, v171, 0, vcc
	v_add_u32_e32 v38, v103, v38
	ds_read_b128 v[40:43], v86 offset:7616
	ds_read_b128 v[44:47], v38
	s_and_b64 vcc, exec, s[0:1]
	s_waitcnt vmcnt(7) lgkmcnt(0)
	v_pk_fma_f32 v[34:35], v[42:43], v[46:47], v[228:229]
	v_pk_fma_f32 v[32:33], v[40:41], v[44:45], v[226:227]
	global_store_dwordx4 v[48:49], v[32:35], off
	s_cbranch_vccnz .LBB0_746
	ds_read_b128 v[38:41], v38 offset:2048
	v_lshlrev_b64 v[36:37], 10, v[36:37]
	v_lshl_add_u64 v[36:37], v[36:37], 1, s[42:43]
	v_lshl_add_u64 v[36:37], v[98:99], 1, v[36:37]
	s_waitcnt lgkmcnt(0)
	v_pk_mul_f32 v[38:39], v[32:33], v[38:39]
	v_pk_mul_f32 v[32:33], v[32:33], v[32:33]
	v_pk_mul_f32 v[40:41], v[34:35], v[40:41]
	v_pk_mul_f32 v[34:35], v[34:35], v[34:35]
	v_add_f32_e32 v32, v32, v33
	v_add_f32_e32 v32, v34, v32
	v_add_f32_e32 v32, v35, v32
	v_cvt_pk_bf16_f32 v38, v38, v39
	v_cvt_pk_bf16_f32 v39, v40, v41
	v_add_f32_dpp v32, v32, v32 quad_perm:[1,0,3,2] row_mask:0xf bank_mask:0xf bound_ctrl:1
	global_store_dwordx2 v[36:37], v[38:39], off
	s_nop 0
	v_add_f32_dpp v32, v32, v32 quad_perm:[2,3,0,1] row_mask:0xf bank_mask:0xf bound_ctrl:1
	s_nop 1
	v_add_f32_dpp v32, v32, v32 row_half_mirror row_mask:0xf bank_mask:0xf bound_ctrl:1
	s_nop 1
	v_mov_b32_dpp v33, v32 row_mirror row_mask:0xf bank_mask:0xf bound_ctrl:1
	s_and_saveexec_b64 s[4:5], s[36:37]
	s_cbranch_execz .LBB0_745
	v_mov_b32_e32 v83, v129
	v_ashrrev_i32_e32 v97, 31, v96
	v_lshl_add_u64 v[34:35], s[52:53], 0, v[68:69]
	v_lshl_add_u64 v[36:37], v[96:97], 0, v[82:83]
	v_lshl_add_u64 v[34:35], v[36:37], 2, v[34:35]
	v_add_f32_e32 v32, v32, v33
	global_store_dword v[34:35], v32, off offset:128

.LBB0_746:
	s_nop 0
	v_add_u32_e32 v34, 64, v96
	v_or_b32_e32 v32, v34, v128
	v_ashrrev_i32_e32 v33, 31, v32
	v_lshlrev_b64 v[36:37], 12, v[32:33]
	v_lshl_add_u64 v[36:37], s[40:41], 0, v[36:37]
	v_lshl_add_u64 v[40:41], v[98:99], 2, v[36:37]
	global_load_dwordx4 v[198:201], v[40:41], off
	v_add_co_u32_e32 v182, vcc, 0x4000, v40
	s_nop 1
	v_addc_co_u32_e32 v183, vcc, 0, v41, vcc
	global_load_dwordx4 v[202:205], v[182:183], off
	v_add_co_u32_e32 v182, vcc, 0x4000, v182
	s_nop 1
	v_addc_co_u32_e32 v183, vcc, 0, v183, vcc
	global_load_dwordx4 v[206:209], v[182:183], off
	v_add_co_u32_e32 v182, vcc, 0x4000, v182
	s_nop 1
	v_addc_co_u32_e32 v183, vcc, 0, v183, vcc
	global_load_dwordx4 v[210:213], v[182:183], off
	v_add_co_u32_e32 v182, vcc, 0x4000, v182
	s_nop 1
	v_addc_co_u32_e32 v183, vcc, 0, v183, vcc
	global_load_dwordx4 v[214:217], v[182:183], off
	v_add_co_u32_e32 v182, vcc, 0x4000, v182
	s_nop 1
	v_addc_co_u32_e32 v183, vcc, 0, v183, vcc
	global_load_dwordx4 v[218:221], v[182:183], off
	v_add_co_u32_e32 v182, vcc, 0x4000, v182
	s_nop 1
	v_addc_co_u32_e32 v183, vcc, 0, v183, vcc
	global_load_dwordx4 v[222:225], v[182:183], off
	v_add_co_u32_e32 v182, vcc, 0x4000, v182
	s_nop 1
	v_addc_co_u32_e32 v183, vcc, 0, v183, vcc
	global_load_dwordx4 v[226:229], v[182:183], off
	ds_write_b128 v104, v[0:3]
	ds_write_b128 v104, v[4:7] offset:32
	ds_write_b128 v104, v[8:11] offset:64
	ds_write_b128 v104, v[12:15] offset:96
	ds_write_b128 v104, v[16:19] offset:128
	ds_write_b128 v104, v[20:23] offset:160
	ds_write_b128 v104, v[24:27] offset:192
	ds_write_b128 v104, v[28:31] offset:224
	v_add_u32_e32 v0, 0xfffff040, v96
	v_xor_b32_e32 v0, s7, v0
	s_movk_i32 s4, 0x400
	v_cmp_gt_u32_e32 vcc, s4, v0
	s_and_b64 s[2:3], s[2:3], vcc
	v_cndmask_b32_e64 v6, 0, 1, s[2:3]
	s_movk_i32 s2, 0x1000
	v_cmp_gt_i32_e32 vcc, s2, v32
	s_nop 1
	v_cndmask_b32_e32 v0, v6, v102, vcc
	v_and_b32_e32 v0, 1, v0
	v_cmp_eq_u32_e32 vcc, 1, v0
	s_nop 1
	v_cndmask_b32_e64 v0, v171, 0, vcc
	v_add_u32_e32 v4, v103, v0
	ds_read_b128 v[0:3], v86
	ds_read_b128 v[8:11], v4
	s_and_b64 vcc, exec, s[0:1]
	s_waitcnt vmcnt(7) lgkmcnt(0)
	v_pk_fma_f32 v[2:3], v[2:3], v[10:11], v[200:201]
	v_pk_fma_f32 v[0:1], v[0:1], v[8:9], v[198:199]
	global_store_dwordx4 v[40:41], v[0:3], off
	s_cbranch_vccnz .LBB0_750
	ds_read_b128 v[8:11], v4 offset:2048
	v_lshlrev_b64 v[4:5], 10, v[32:33]
	v_lshl_add_u64 v[4:5], v[4:5], 1, s[42:43]
	v_lshl_add_u64 v[4:5], v[98:99], 1, v[4:5]
	s_waitcnt lgkmcnt(0)
	v_pk_mul_f32 v[8:9], v[0:1], v[8:9]
	v_pk_mul_f32 v[0:1], v[0:1], v[0:1]
	v_pk_mul_f32 v[10:11], v[2:3], v[10:11]
	v_pk_mul_f32 v[2:3], v[2:3], v[2:3]
	v_add_f32_e32 v0, v0, v1
	v_add_f32_e32 v0, v2, v0
	v_add_f32_e32 v0, v3, v0
	v_cvt_pk_bf16_f32 v8, v8, v9
	v_cvt_pk_bf16_f32 v9, v10, v11
	v_add_f32_dpp v0, v0, v0 quad_perm:[1,0,3,2] row_mask:0xf bank_mask:0xf bound_ctrl:1
	global_store_dwordx2 v[4:5], v[8:9], off
	s_nop 0
	v_add_f32_dpp v0, v0, v0 quad_perm:[2,3,0,1] row_mask:0xf bank_mask:0xf bound_ctrl:1
	s_nop 1
	v_add_f32_dpp v0, v0, v0 row_half_mirror row_mask:0xf bank_mask:0xf bound_ctrl:1
	s_nop 1
	v_mov_b32_dpp v1, v0 row_mirror row_mask:0xf bank_mask:0xf bound_ctrl:1
	s_and_saveexec_b64 s[2:3], s[36:37]
	s_cbranch_execz .LBB0_749
	v_ashrrev_i32_e32 v97, 31, v96
	v_lshl_add_u64 v[2:3], s[52:53], 0, v[68:69]
	v_lshl_add_u64 v[4:5], v[96:97], 0, v[128:129]
	v_lshl_add_u64 v[2:3], v[4:5], 2, v[2:3]
	v_add_f32_e32 v0, v0, v1
	global_store_dword v[2:3], v0, off offset:256

.LBB0_750:
	v_or_b32_e32 v4, v34, v70
	v_ashrrev_i32_e32 v5, 31, v4
	v_lshlrev_b64 v[0:1], 12, v[4:5]
	v_lshl_add_u64 v[0:1], s[40:41], 0, v[0:1]
	v_lshl_add_u64 v[16:17], v[98:99], 2, v[0:1]
	s_movk_i32 s2, 0x1000
	v_cmp_gt_i32_e32 vcc, s2, v4
	s_nop 1
	v_cndmask_b32_e32 v7, v6, v102, vcc
	v_and_b32_e32 v7, 1, v7
	v_cmp_eq_u32_e32 vcc, 1, v7
	s_nop 1
	v_cndmask_b32_e64 v7, v171, 0, vcc
	v_add_u32_e32 v7, v103, v7
	ds_read_b128 v[8:11], v86 offset:1088
	ds_read_b128 v[12:15], v7
	s_and_b64 vcc, exec, s[0:1]
	s_waitcnt vmcnt(7) lgkmcnt(0)
	v_pk_fma_f32 v[2:3], v[10:11], v[14:15], v[204:205]
	v_pk_fma_f32 v[0:1], v[8:9], v[12:13], v[202:203]
	global_store_dwordx4 v[16:17], v[0:3], off
	s_cbranch_vccnz .LBB0_754
	ds_read_b128 v[8:11], v7 offset:2048
	v_lshlrev_b64 v[4:5], 10, v[4:5]
	v_lshl_add_u64 v[4:5], v[4:5], 1, s[42:43]
	v_lshl_add_u64 v[4:5], v[98:99], 1, v[4:5]
	s_waitcnt lgkmcnt(0)
	v_pk_mul_f32 v[8:9], v[0:1], v[8:9]
	v_pk_mul_f32 v[0:1], v[0:1], v[0:1]
	v_pk_mul_f32 v[10:11], v[2:3], v[10:11]
	v_pk_mul_f32 v[2:3], v[2:3], v[2:3]
	v_add_f32_e32 v0, v0, v1
	v_add_f32_e32 v0, v2, v0
	v_add_f32_e32 v0, v3, v0
	v_cvt_pk_bf16_f32 v8, v8, v9
	v_cvt_pk_bf16_f32 v9, v10, v11
	v_add_f32_dpp v0, v0, v0 quad_perm:[1,0,3,2] row_mask:0xf bank_mask:0xf bound_ctrl:1
	global_store_dwordx2 v[4:5], v[8:9], off
	s_nop 0
	v_add_f32_dpp v0, v0, v0 quad_perm:[2,3,0,1] row_mask:0xf bank_mask:0xf bound_ctrl:1
	s_nop 1
	v_add_f32_dpp v0, v0, v0 row_half_mirror row_mask:0xf bank_mask:0xf bound_ctrl:1
	s_nop 1
	v_mov_b32_dpp v1, v0 row_mirror row_mask:0xf bank_mask:0xf bound_ctrl:1
	s_and_saveexec_b64 s[2:3], s[36:37]
	s_cbranch_execz .LBB0_753
	v_mov_b32_e32 v71, v129
	v_ashrrev_i32_e32 v97, 31, v96
	v_lshl_add_u64 v[2:3], s[52:53], 0, v[68:69]
	v_lshl_add_u64 v[4:5], v[96:97], 0, v[70:71]
	v_lshl_add_u64 v[2:3], v[4:5], 2, v[2:3]
	v_add_f32_e32 v0, v0, v1
	global_store_dword v[2:3], v0, off offset:256

.LBB0_754:
	v_or_b32_e32 v4, v34, v72
	v_ashrrev_i32_e32 v5, 31, v4
	v_lshlrev_b64 v[0:1], 12, v[4:5]
	v_lshl_add_u64 v[0:1], s[40:41], 0, v[0:1]
	v_lshl_add_u64 v[16:17], v[98:99], 2, v[0:1]
	s_movk_i32 s2, 0x1000
	v_cmp_gt_i32_e32 vcc, s2, v4
	s_nop 1
	v_cndmask_b32_e32 v7, v6, v102, vcc
	v_and_b32_e32 v7, 1, v7
	v_cmp_eq_u32_e32 vcc, 1, v7
	s_nop 1
	v_cndmask_b32_e64 v7, v171, 0, vcc
	v_add_u32_e32 v7, v103, v7
	ds_read_b128 v[8:11], v86 offset:2176
	ds_read_b128 v[12:15], v7
	s_and_b64 vcc, exec, s[0:1]
	s_waitcnt vmcnt(7) lgkmcnt(0)
	v_pk_fma_f32 v[2:3], v[10:11], v[14:15], v[208:209]
	v_pk_fma_f32 v[0:1], v[8:9], v[12:13], v[206:207]
	global_store_dwordx4 v[16:17], v[0:3], off
	s_cbranch_vccnz .LBB0_758
	ds_read_b128 v[8:11], v7 offset:2048
	v_lshlrev_b64 v[4:5], 10, v[4:5]
	v_lshl_add_u64 v[4:5], v[4:5], 1, s[42:43]
	v_lshl_add_u64 v[4:5], v[98:99], 1, v[4:5]
	s_waitcnt lgkmcnt(0)
	v_pk_mul_f32 v[8:9], v[0:1], v[8:9]
	v_pk_mul_f32 v[0:1], v[0:1], v[0:1]
	v_pk_mul_f32 v[10:11], v[2:3], v[10:11]
	v_pk_mul_f32 v[2:3], v[2:3], v[2:3]
	v_add_f32_e32 v0, v0, v1
	v_add_f32_e32 v0, v2, v0
	v_add_f32_e32 v0, v3, v0
	v_cvt_pk_bf16_f32 v8, v8, v9
	v_cvt_pk_bf16_f32 v9, v10, v11
	v_add_f32_dpp v0, v0, v0 quad_perm:[1,0,3,2] row_mask:0xf bank_mask:0xf bound_ctrl:1
	global_store_dwordx2 v[4:5], v[8:9], off
	s_nop 0
	v_add_f32_dpp v0, v0, v0 quad_perm:[2,3,0,1] row_mask:0xf bank_mask:0xf bound_ctrl:1
	s_nop 1
	v_add_f32_dpp v0, v0, v0 row_half_mirror row_mask:0xf bank_mask:0xf bound_ctrl:1
	s_nop 1
	v_mov_b32_dpp v1, v0 row_mirror row_mask:0xf bank_mask:0xf bound_ctrl:1
	s_and_saveexec_b64 s[2:3], s[36:37]
	s_cbranch_execz .LBB0_757
	v_mov_b32_e32 v73, v129
	v_ashrrev_i32_e32 v97, 31, v96
	v_lshl_add_u64 v[2:3], s[52:53], 0, v[68:69]
	v_lshl_add_u64 v[4:5], v[96:97], 0, v[72:73]
	v_lshl_add_u64 v[2:3], v[4:5], 2, v[2:3]
	v_add_f32_e32 v0, v0, v1
	global_store_dword v[2:3], v0, off offset:256

.LBB0_758:
	v_or_b32_e32 v4, v34, v74
	v_ashrrev_i32_e32 v5, 31, v4
	v_lshlrev_b64 v[0:1], 12, v[4:5]
	v_lshl_add_u64 v[0:1], s[40:41], 0, v[0:1]
	v_lshl_add_u64 v[16:17], v[98:99], 2, v[0:1]
	s_movk_i32 s2, 0x1000
	v_cmp_gt_i32_e32 vcc, s2, v4
	s_nop 1
	v_cndmask_b32_e32 v7, v6, v102, vcc
	v_and_b32_e32 v7, 1, v7
	v_cmp_eq_u32_e32 vcc, 1, v7
	s_nop 1
	v_cndmask_b32_e64 v7, v171, 0, vcc
	v_add_u32_e32 v7, v103, v7
	ds_read_b128 v[8:11], v86 offset:3264
	ds_read_b128 v[12:15], v7
	s_and_b64 vcc, exec, s[0:1]
	s_waitcnt vmcnt(7) lgkmcnt(0)
	v_pk_fma_f32 v[2:3], v[10:11], v[14:15], v[212:213]
	v_pk_fma_f32 v[0:1], v[8:9], v[12:13], v[210:211]
	global_store_dwordx4 v[16:17], v[0:3], off
	s_cbranch_vccnz .LBB0_762
	ds_read_b128 v[8:11], v7 offset:2048
	v_lshlrev_b64 v[4:5], 10, v[4:5]
	v_lshl_add_u64 v[4:5], v[4:5], 1, s[42:43]
	v_lshl_add_u64 v[4:5], v[98:99], 1, v[4:5]
	s_waitcnt lgkmcnt(0)
	v_pk_mul_f32 v[8:9], v[0:1], v[8:9]
	v_pk_mul_f32 v[0:1], v[0:1], v[0:1]
	v_pk_mul_f32 v[10:11], v[2:3], v[10:11]
	v_pk_mul_f32 v[2:3], v[2:3], v[2:3]
	v_add_f32_e32 v0, v0, v1
	v_add_f32_e32 v0, v2, v0
	v_add_f32_e32 v0, v3, v0
	v_cvt_pk_bf16_f32 v8, v8, v9
	v_cvt_pk_bf16_f32 v9, v10, v11
	v_add_f32_dpp v0, v0, v0 quad_perm:[1,0,3,2] row_mask:0xf bank_mask:0xf bound_ctrl:1
	global_store_dwordx2 v[4:5], v[8:9], off
	s_nop 0
	v_add_f32_dpp v0, v0, v0 quad_perm:[2,3,0,1] row_mask:0xf bank_mask:0xf bound_ctrl:1
	s_nop 1
	v_add_f32_dpp v0, v0, v0 row_half_mirror row_mask:0xf bank_mask:0xf bound_ctrl:1
	s_nop 1
	v_mov_b32_dpp v1, v0 row_mirror row_mask:0xf bank_mask:0xf bound_ctrl:1
	s_and_saveexec_b64 s[2:3], s[36:37]
	s_cbranch_execz .LBB0_761
	v_mov_b32_e32 v75, v129
	v_ashrrev_i32_e32 v97, 31, v96
	v_lshl_add_u64 v[2:3], s[52:53], 0, v[68:69]
	v_lshl_add_u64 v[4:5], v[96:97], 0, v[74:75]
	v_lshl_add_u64 v[2:3], v[4:5], 2, v[2:3]
	v_add_f32_e32 v0, v0, v1
	global_store_dword v[2:3], v0, off offset:256

.LBB0_762:
	v_or_b32_e32 v4, v34, v76
	v_ashrrev_i32_e32 v5, 31, v4
	v_lshlrev_b64 v[0:1], 12, v[4:5]
	v_lshl_add_u64 v[0:1], s[40:41], 0, v[0:1]
	v_lshl_add_u64 v[16:17], v[98:99], 2, v[0:1]
	s_movk_i32 s2, 0x1000
	v_cmp_gt_i32_e32 vcc, s2, v4
	s_nop 1
	v_cndmask_b32_e32 v7, v6, v102, vcc
	v_and_b32_e32 v7, 1, v7
	v_cmp_eq_u32_e32 vcc, 1, v7
	s_nop 1
	v_cndmask_b32_e64 v7, v171, 0, vcc
	v_add_u32_e32 v7, v103, v7
	ds_read_b128 v[8:11], v86 offset:4352
	ds_read_b128 v[12:15], v7
	s_and_b64 vcc, exec, s[0:1]
	s_waitcnt vmcnt(7) lgkmcnt(0)
	v_pk_fma_f32 v[2:3], v[10:11], v[14:15], v[216:217]
	v_pk_fma_f32 v[0:1], v[8:9], v[12:13], v[214:215]
	global_store_dwordx4 v[16:17], v[0:3], off
	s_cbranch_vccnz .LBB0_766
	ds_read_b128 v[8:11], v7 offset:2048
	v_lshlrev_b64 v[4:5], 10, v[4:5]
	v_lshl_add_u64 v[4:5], v[4:5], 1, s[42:43]
	v_lshl_add_u64 v[4:5], v[98:99], 1, v[4:5]
	s_waitcnt lgkmcnt(0)
	v_pk_mul_f32 v[8:9], v[0:1], v[8:9]
	v_pk_mul_f32 v[0:1], v[0:1], v[0:1]
	v_pk_mul_f32 v[10:11], v[2:3], v[10:11]
	v_pk_mul_f32 v[2:3], v[2:3], v[2:3]
	v_add_f32_e32 v0, v0, v1
	v_add_f32_e32 v0, v2, v0
	v_add_f32_e32 v0, v3, v0
	v_cvt_pk_bf16_f32 v8, v8, v9
	v_cvt_pk_bf16_f32 v9, v10, v11
	v_add_f32_dpp v0, v0, v0 quad_perm:[1,0,3,2] row_mask:0xf bank_mask:0xf bound_ctrl:1
	global_store_dwordx2 v[4:5], v[8:9], off
	s_nop 0
	v_add_f32_dpp v0, v0, v0 quad_perm:[2,3,0,1] row_mask:0xf bank_mask:0xf bound_ctrl:1
	s_nop 1
	v_add_f32_dpp v0, v0, v0 row_half_mirror row_mask:0xf bank_mask:0xf bound_ctrl:1
	s_nop 1
	v_mov_b32_dpp v1, v0 row_mirror row_mask:0xf bank_mask:0xf bound_ctrl:1
	s_and_saveexec_b64 s[2:3], s[36:37]
	s_cbranch_execz .LBB0_765
	v_mov_b32_e32 v77, v129
	v_ashrrev_i32_e32 v97, 31, v96
	v_lshl_add_u64 v[2:3], s[52:53], 0, v[68:69]
	v_lshl_add_u64 v[4:5], v[96:97], 0, v[76:77]
	v_lshl_add_u64 v[2:3], v[4:5], 2, v[2:3]
	v_add_f32_e32 v0, v0, v1
	global_store_dword v[2:3], v0, off offset:256

.LBB0_766:
	v_or_b32_e32 v4, v34, v78
	v_ashrrev_i32_e32 v5, 31, v4
	v_lshlrev_b64 v[0:1], 12, v[4:5]
	v_lshl_add_u64 v[0:1], s[40:41], 0, v[0:1]
	v_lshl_add_u64 v[16:17], v[98:99], 2, v[0:1]
	s_movk_i32 s2, 0x1000
	v_cmp_gt_i32_e32 vcc, s2, v4
	s_nop 1
	v_cndmask_b32_e32 v7, v6, v102, vcc
	v_and_b32_e32 v7, 1, v7
	v_cmp_eq_u32_e32 vcc, 1, v7
	s_nop 1
	v_cndmask_b32_e64 v7, v171, 0, vcc
	v_add_u32_e32 v7, v103, v7
	ds_read_b128 v[8:11], v86 offset:5440
	ds_read_b128 v[12:15], v7
	s_and_b64 vcc, exec, s[0:1]
	s_waitcnt vmcnt(7) lgkmcnt(0)
	v_pk_fma_f32 v[2:3], v[10:11], v[14:15], v[220:221]
	v_pk_fma_f32 v[0:1], v[8:9], v[12:13], v[218:219]
	global_store_dwordx4 v[16:17], v[0:3], off
	s_cbranch_vccnz .LBB0_770
	ds_read_b128 v[8:11], v7 offset:2048
	v_lshlrev_b64 v[4:5], 10, v[4:5]
	v_lshl_add_u64 v[4:5], v[4:5], 1, s[42:43]
	v_lshl_add_u64 v[4:5], v[98:99], 1, v[4:5]
	s_waitcnt lgkmcnt(0)
	v_pk_mul_f32 v[8:9], v[0:1], v[8:9]
	v_pk_mul_f32 v[0:1], v[0:1], v[0:1]
	v_pk_mul_f32 v[10:11], v[2:3], v[10:11]
	v_pk_mul_f32 v[2:3], v[2:3], v[2:3]
	v_add_f32_e32 v0, v0, v1
	v_add_f32_e32 v0, v2, v0
	v_add_f32_e32 v0, v3, v0
	v_cvt_pk_bf16_f32 v8, v8, v9
	v_cvt_pk_bf16_f32 v9, v10, v11
	v_add_f32_dpp v0, v0, v0 quad_perm:[1,0,3,2] row_mask:0xf bank_mask:0xf bound_ctrl:1
	global_store_dwordx2 v[4:5], v[8:9], off
	s_nop 0
	v_add_f32_dpp v0, v0, v0 quad_perm:[2,3,0,1] row_mask:0xf bank_mask:0xf bound_ctrl:1
	s_nop 1
	v_add_f32_dpp v0, v0, v0 row_half_mirror row_mask:0xf bank_mask:0xf bound_ctrl:1
	s_nop 1
	v_mov_b32_dpp v1, v0 row_mirror row_mask:0xf bank_mask:0xf bound_ctrl:1
	s_and_saveexec_b64 s[2:3], s[36:37]
	s_cbranch_execz .LBB0_769
	v_mov_b32_e32 v79, v129
	v_ashrrev_i32_e32 v97, 31, v96
	v_lshl_add_u64 v[2:3], s[52:53], 0, v[68:69]
	v_lshl_add_u64 v[4:5], v[96:97], 0, v[78:79]
	v_lshl_add_u64 v[2:3], v[4:5], 2, v[2:3]
	v_add_f32_e32 v0, v0, v1
	global_store_dword v[2:3], v0, off offset:256

.LBB0_770:
	v_or_b32_e32 v4, v34, v80
	v_ashrrev_i32_e32 v5, 31, v4
	v_lshlrev_b64 v[0:1], 12, v[4:5]
	v_lshl_add_u64 v[0:1], s[40:41], 0, v[0:1]
	v_lshl_add_u64 v[16:17], v[98:99], 2, v[0:1]
	s_movk_i32 s2, 0x1000
	v_cmp_gt_i32_e32 vcc, s2, v4
	s_nop 1
	v_cndmask_b32_e32 v7, v6, v102, vcc
	v_and_b32_e32 v7, 1, v7
	v_cmp_eq_u32_e32 vcc, 1, v7
	s_nop 1
	v_cndmask_b32_e64 v7, v171, 0, vcc
	v_add_u32_e32 v7, v103, v7
	ds_read_b128 v[8:11], v86 offset:6528
	ds_read_b128 v[12:15], v7
	s_and_b64 vcc, exec, s[0:1]
	s_waitcnt vmcnt(7) lgkmcnt(0)
	v_pk_fma_f32 v[2:3], v[10:11], v[14:15], v[224:225]
	v_pk_fma_f32 v[0:1], v[8:9], v[12:13], v[222:223]
	global_store_dwordx4 v[16:17], v[0:3], off
	s_cbranch_vccnz .LBB0_774
	ds_read_b128 v[8:11], v7 offset:2048
	v_lshlrev_b64 v[4:5], 10, v[4:5]
	v_lshl_add_u64 v[4:5], v[4:5], 1, s[42:43]
	v_lshl_add_u64 v[4:5], v[98:99], 1, v[4:5]
	s_waitcnt lgkmcnt(0)
	v_pk_mul_f32 v[8:9], v[0:1], v[8:9]
	v_pk_mul_f32 v[0:1], v[0:1], v[0:1]
	v_pk_mul_f32 v[10:11], v[2:3], v[10:11]
	v_pk_mul_f32 v[2:3], v[2:3], v[2:3]
	v_add_f32_e32 v0, v0, v1
	v_add_f32_e32 v0, v2, v0
	v_add_f32_e32 v0, v3, v0
	v_cvt_pk_bf16_f32 v8, v8, v9
	v_cvt_pk_bf16_f32 v9, v10, v11
	v_add_f32_dpp v0, v0, v0 quad_perm:[1,0,3,2] row_mask:0xf bank_mask:0xf bound_ctrl:1
	global_store_dwordx2 v[4:5], v[8:9], off
	s_nop 0
	v_add_f32_dpp v0, v0, v0 quad_perm:[2,3,0,1] row_mask:0xf bank_mask:0xf bound_ctrl:1
	s_nop 1
	v_add_f32_dpp v0, v0, v0 row_half_mirror row_mask:0xf bank_mask:0xf bound_ctrl:1
	s_nop 1
	v_mov_b32_dpp v1, v0 row_mirror row_mask:0xf bank_mask:0xf bound_ctrl:1
	s_and_saveexec_b64 s[2:3], s[36:37]
	s_cbranch_execz .LBB0_773
	v_mov_b32_e32 v81, v129
	v_ashrrev_i32_e32 v97, 31, v96
	v_lshl_add_u64 v[2:3], s[52:53], 0, v[68:69]
	v_lshl_add_u64 v[4:5], v[96:97], 0, v[80:81]
	v_lshl_add_u64 v[2:3], v[4:5], 2, v[2:3]
	v_add_f32_e32 v0, v0, v1
	global_store_dword v[2:3], v0, off offset:256

.LBB0_774:
	v_or_b32_e32 v4, v34, v82
	v_ashrrev_i32_e32 v5, 31, v4
	v_lshlrev_b64 v[0:1], 12, v[4:5]
	v_lshl_add_u64 v[0:1], s[40:41], 0, v[0:1]
	v_lshl_add_u64 v[16:17], v[98:99], 2, v[0:1]
	s_movk_i32 s2, 0x1000
	v_cmp_gt_i32_e32 vcc, s2, v4
	s_nop 1
	v_cndmask_b32_e32 v6, v6, v102, vcc
	v_and_b32_e32 v6, 1, v6
	v_cmp_eq_u32_e32 vcc, 1, v6
	s_nop 1
	v_cndmask_b32_e64 v6, v171, 0, vcc
	v_add_u32_e32 v6, v103, v6
	ds_read_b128 v[8:11], v86 offset:7616
	ds_read_b128 v[12:15], v6
	s_and_b64 vcc, exec, s[0:1]
	s_waitcnt vmcnt(7) lgkmcnt(0)
	v_pk_fma_f32 v[2:3], v[10:11], v[14:15], v[228:229]
	v_pk_fma_f32 v[0:1], v[8:9], v[12:13], v[226:227]
	global_store_dwordx4 v[16:17], v[0:3], off
	s_cbranch_vccnz .LBB0_677
	ds_read_b128 v[6:9], v6 offset:2048
	v_lshlrev_b64 v[4:5], 10, v[4:5]
	v_lshl_add_u64 v[4:5], v[4:5], 1, s[42:43]
	v_lshl_add_u64 v[4:5], v[98:99], 1, v[4:5]
	s_waitcnt lgkmcnt(0)
	v_pk_mul_f32 v[6:7], v[0:1], v[6:7]
	v_pk_mul_f32 v[0:1], v[0:1], v[0:1]
	v_pk_mul_f32 v[8:9], v[2:3], v[8:9]
	v_pk_mul_f32 v[2:3], v[2:3], v[2:3]
	v_add_f32_e32 v0, v0, v1
	v_add_f32_e32 v0, v2, v0
	v_add_f32_e32 v0, v3, v0
	v_cvt_pk_bf16_f32 v6, v6, v7
	v_cvt_pk_bf16_f32 v7, v8, v9
	v_add_f32_dpp v0, v0, v0 quad_perm:[1,0,3,2] row_mask:0xf bank_mask:0xf bound_ctrl:1
	global_store_dwordx2 v[4:5], v[6:7], off
	s_nop 0
	v_add_f32_dpp v0, v0, v0 quad_perm:[2,3,0,1] row_mask:0xf bank_mask:0xf bound_ctrl:1
	s_nop 1
	v_add_f32_dpp v0, v0, v0 row_half_mirror row_mask:0xf bank_mask:0xf bound_ctrl:1
	s_nop 1
	v_mov_b32_dpp v1, v0 row_mirror row_mask:0xf bank_mask:0xf bound_ctrl:1
	s_and_saveexec_b64 s[0:1], s[36:37]
	s_cbranch_execz .LBB0_676
	v_mov_b32_e32 v83, v129
	v_ashrrev_i32_e32 v97, 31, v96
	v_lshl_add_u64 v[2:3], s[52:53], 0, v[68:69]
	v_lshl_add_u64 v[4:5], v[96:97], 0, v[82:83]
	v_lshl_add_u64 v[2:3], v[4:5], 2, v[2:3]
	v_add_f32_e32 v0, v0, v1
	global_store_dword v[2:3], v0, off offset:256
	s_branch .LBB0_676

.LBB0_1223:
	s_add_i32 s9, s7, 1
	s_bitcmp1_b32 s9, 0
	s_cselect_b32 s10, 0xe000, 0
	v_add_u32_e32 v115, s10, v109
	v_lshl_add_u64 v[116:117], v[98:99], 0, s[2:3]
	v_readfirstlane_b32 s10, v115
	v_add_u32_e32 v120, 0x2000, v115
	v_lshl_add_u64 v[118:119], v[116:117], 0, s[12:13]
	s_mov_b32 m0, s10
	v_readfirstlane_b32 s10, v120
	s_waitcnt vmcnt(0)
	s_waitcnt vmcnt(0) lgkmcnt(0)
	s_barrier
	global_load_lds_dwordx4 v[118:119], off
	v_lshl_add_u64 v[118:119], v[116:117], 0, s[16:17]
	s_mov_b32 m0, s10
	v_lshl_add_u64 v[116:117], v[116:117], 0, s[18:19]
	global_load_lds_dwordx4 v[118:119], off
	v_add_u32_e32 v118, 0x4000, v115
	v_add_u32_e32 v120, 0x6000, v115
	v_readfirstlane_b32 s10, v118
	s_mov_b32 m0, s10
	s_mov_b64 s[10:11], 0x5f14080
	global_load_lds_dwordx4 v[116:117], off
	v_lshl_add_u64 v[116:117], v[96:97], 0, s[2:3]
	v_lshl_add_u64 v[118:119], v[116:117], 0, s[10:11]
	v_readfirstlane_b32 s10, v120
	s_mov_b32 m0, s10
	s_mov_b64 s[10:11], 0x5f34080
	v_add_u32_e32 v120, 0x8000, v115
	global_load_lds_dwordx4 v[118:119], off
	v_lshl_add_u64 v[118:119], v[116:117], 0, s[10:11]
	v_readfirstlane_b32 s10, v120
	s_mov_b32 m0, s10
	s_mov_b64 s[10:11], 0x5f54080
	v_add_u32_e32 v120, 0xa000, v115
	global_load_lds_dwordx4 v[118:119], off
	v_lshl_add_u64 v[118:119], v[116:117], 0, s[10:11]
	v_readfirstlane_b32 s10, v120
	s_mov_b32 m0, s10
	s_mov_b64 s[10:11], 0x5f74080
	v_add_u32_e32 v115, 0xc000, v115
	v_lshl_add_u64 v[116:117], v[116:117], 0, s[10:11]
	v_readfirstlane_b32 s10, v115
	global_load_lds_dwordx4 v[118:119], off
	s_mov_b32 m0, s10
	s_nop 0
	global_load_lds_dwordx4 v[116:117], off
	s_bitcmp1_b32 s7, 0
	s_cselect_b32 s7, 0xe000, 0
	v_add_u32_e32 v115, s7, v114
	v_add_u32_e32 v120, v115, v111
	ds_read_b128 v[116:119], v120 offset:0
	v_add_u32_e32 v128, s7, v113
	ds_read_b128 v[120:123], v120 offset:0x1000
	v_add_u32_e32 v134, v128, v111
	ds_read_b128 v[124:127], v134 offset:0
	ds_read_b128 v[130:133], v134 offset:0x1000
	ds_read_b128 v[134:137], v134 offset:0x2000
	v_add_u32_e32 v148, v115, v110
	ds_read_b128 v[144:147], v148 offset:0
	ds_read_b128 v[148:151], v148 offset:0x1000
	v_add_u32_e32 v152, v128, v110
	ds_read_b128 v[182:185], v152 offset:0
	ds_read_b128 v[186:189], v152 offset:0x1000
	ds_read_b128 v[190:193], v152 offset:0x2000
	s_waitcnt lgkmcnt(5)
	s_nop 0
	v_mfma_f32_32x32x16_bf16 v[64:79], v[116:119], v[124:127], v[64:79]
	v_mfma_f32_32x32x16_bf16 v[32:47], v[116:119], v[130:133], v[32:47]
	v_mfma_f32_32x32x16_bf16 v[0:15], v[116:119], v[134:137], v[0:15]
	v_mfma_f32_32x32x16_bf16 v[80:95], v[120:123], v[124:127], v[80:95]
	v_mfma_f32_32x32x16_bf16 v[48:63], v[120:123], v[130:133], v[48:63]
	v_mfma_f32_32x32x16_bf16 v[16:31], v[120:123], v[134:137], v[16:31]
	v_add_u32_e32 v120, v115, v108
	ds_read_b128 v[116:119], v120 offset:0
	ds_read_b128 v[120:123], v120 offset:0x1000
	v_add_u32_e32 v134, v128, v108
	ds_read_b128 v[124:127], v134 offset:0
	ds_read_b128 v[130:133], v134 offset:0x1000
	ds_read_b128 v[134:137], v134 offset:0x2000
	s_waitcnt lgkmcnt(5)
	s_nop 0
	v_mfma_f32_32x32x16_bf16 v[64:79], v[144:147], v[182:185], v[64:79]
	v_mfma_f32_32x32x16_bf16 v[32:47], v[144:147], v[186:189], v[32:47]
	v_mfma_f32_32x32x16_bf16 v[0:15], v[144:147], v[190:193], v[0:15]
	v_mfma_f32_32x32x16_bf16 v[80:95], v[148:151], v[182:185], v[80:95]
	v_mfma_f32_32x32x16_bf16 v[48:63], v[148:151], v[186:189], v[48:63]
	v_mfma_f32_32x32x16_bf16 v[16:31], v[148:151], v[190:193], v[16:31]
	v_add_u32_e32 v115, v115, v107
	ds_read_b128 v[144:147], v115 offset:0
	ds_read_b128 v[148:151], v115 offset:0x1000
	v_add_u32_e32 v115, v128, v107
	ds_read_b128 v[182:185], v115 offset:0
	ds_read_b128 v[186:189], v115 offset:0x1000
	ds_read_b128 v[190:193], v115 offset:0x2000
	s_waitcnt lgkmcnt(5)
	s_nop 0
	v_mfma_f32_32x32x16_bf16 v[64:79], v[116:119], v[124:127], v[64:79]
	v_mfma_f32_32x32x16_bf16 v[32:47], v[116:119], v[130:133], v[32:47]
	v_mfma_f32_32x32x16_bf16 v[0:15], v[116:119], v[134:137], v[0:15]
	v_mfma_f32_32x32x16_bf16 v[80:95], v[120:123], v[124:127], v[80:95]
	v_mfma_f32_32x32x16_bf16 v[48:63], v[120:123], v[130:133], v[48:63]
	v_mfma_f32_32x32x16_bf16 v[16:31], v[120:123], v[134:137], v[16:31]
	s_waitcnt lgkmcnt(0)
	s_nop 0
	v_mfma_f32_32x32x16_bf16 v[64:79], v[144:147], v[182:185], v[64:79]
	v_mfma_f32_32x32x16_bf16 v[32:47], v[144:147], v[186:189], v[32:47]
	v_mfma_f32_32x32x16_bf16 v[0:15], v[144:147], v[190:193], v[0:15]
	v_mfma_f32_32x32x16_bf16 v[80:95], v[148:151], v[182:185], v[80:95]
	v_mfma_f32_32x32x16_bf16 v[48:63], v[148:151], v[186:189], v[48:63]
	v_mfma_f32_32x32x16_bf16 v[16:31], v[148:151], v[190:193], v[16:31]
	s_add_u32 s2, s2, 0x80
	s_addc_u32 s3, s3, 0
	s_cmpk_eq_i32 s2, 0x780
	s_mov_b32 s7, s9
	s_cbranch_scc0 .LBB0_1223
	s_waitcnt vmcnt(0)
	s_waitcnt vmcnt(0) lgkmcnt(0)
	s_barrier
	v_add_u32_e32 v109, 0x14000, v112
	v_add_u32_e32 v112, v109, v111
	ds_read_b128 v[96:99], v112 offset:0
	v_add_u32_e32 v128, 0xe000, v113
	ds_read_b128 v[112:115], v112 offset:0x1000
	v_add_u32_e32 v111, v128, v111
	ds_read_b128 v[116:119], v111 offset:0
	ds_read_b128 v[120:123], v111 offset:0x1000
	ds_read_b128 v[124:127], v111 offset:0x2000
	v_add_u32_e32 v111, v109, v110
	ds_read_b128 v[130:133], v111 offset:0
	ds_read_b128 v[134:137], v111 offset:0x1000
	v_add_u32_e32 v110, v128, v110
	ds_read_b128 v[144:147], v110 offset:0
	ds_read_b128 v[148:151], v110 offset:0x1000
	ds_read_b128 v[182:185], v110 offset:0x2000
	s_waitcnt lgkmcnt(5)
	s_nop 0
	v_mfma_f32_32x32x16_bf16 v[64:79], v[96:99], v[116:119], v[64:79]
	v_mfma_f32_32x32x16_bf16 v[32:47], v[96:99], v[120:123], v[32:47]
	v_mfma_f32_32x32x16_bf16 v[0:15], v[96:99], v[124:127], v[0:15]
	v_mfma_f32_32x32x16_bf16 v[48:63], v[112:115], v[120:123], v[48:63]
	v_mfma_f32_32x32x16_bf16 v[16:31], v[112:115], v[124:127], v[16:31]
	v_mfma_f32_32x32x16_bf16 v[80:95], v[112:115], v[116:119], v[80:95]
	v_add_u32_e32 v110, v109, v108
	ds_read_b128 v[96:99], v110 offset:0
	ds_read_b128 v[110:113], v110 offset:0x1000
	v_add_u32_e32 v108, v128, v108
	ds_read_b128 v[114:117], v108 offset:0
	ds_read_b128 v[118:121], v108 offset:0x1000
	ds_read_b128 v[122:125], v108 offset:0x2000
	s_waitcnt lgkmcnt(5)
	s_nop 0
	v_mfma_f32_32x32x16_bf16 v[64:79], v[130:133], v[144:147], v[64:79]
	v_mfma_f32_32x32x16_bf16 v[32:47], v[130:133], v[148:151], v[32:47]
	v_mfma_f32_32x32x16_bf16 v[0:15], v[130:133], v[182:185], v[0:15]
	v_mfma_f32_32x32x16_bf16 v[48:63], v[134:137], v[148:151], v[48:63]
	v_mfma_f32_32x32x16_bf16 v[16:31], v[134:137], v[182:185], v[16:31]
	v_mfma_f32_32x32x16_bf16 v[80:95], v[134:137], v[144:147], v[80:95]
	v_add_u32_e32 v108, v109, v107
	ds_read_b128 v[130:133], v108 offset:0
	ds_read_b128 v[134:137], v108 offset:0x1000
	v_add_u32_e32 v107, v128, v107
	ds_read_b128 v[144:147], v107 offset:0
	ds_read_b128 v[148:151], v107 offset:0x1000
	ds_read_b128 v[182:185], v107 offset:0x2000
	s_waitcnt lgkmcnt(5)
	s_nop 0
	v_mfma_f32_32x32x16_bf16 v[64:79], v[96:99], v[114:117], v[64:79]
	v_mfma_f32_32x32x16_bf16 v[32:47], v[96:99], v[118:121], v[32:47]
	v_mfma_f32_32x32x16_bf16 v[0:15], v[96:99], v[122:125], v[0:15]
	v_mfma_f32_32x32x16_bf16 v[48:63], v[110:113], v[118:121], v[48:63]
	v_mfma_f32_32x32x16_bf16 v[16:31], v[110:113], v[122:125], v[16:31]
	v_mfma_f32_32x32x16_bf16 v[80:95], v[110:113], v[114:117], v[80:95]
	s_waitcnt lgkmcnt(0)
	s_nop 0
	v_mfma_f32_32x32x16_bf16 v[64:79], v[130:133], v[144:147], v[64:79]
	v_mfma_f32_32x32x16_bf16 v[32:47], v[130:133], v[148:151], v[32:47]
	v_mfma_f32_32x32x16_bf16 v[0:15], v[130:133], v[182:185], v[0:15]
	v_mfma_f32_32x32x16_bf16 v[48:63], v[134:137], v[148:151], v[48:63]
	v_mfma_f32_32x32x16_bf16 v[16:31], v[134:137], v[182:185], v[16:31]
	v_mfma_f32_32x32x16_bf16 v[80:95], v[134:137], v[144:147], v[80:95]
	v_add_u32_e32 v96, s4, v106
	v_lshrrev_b32_e32 v128, 4, v101
	v_and_b32_e32 v112, 15, v100
	v_or_b32_e32 v100, v96, v128
	v_add_u32_e32 v105, s8, v105
	v_ashrrev_i32_e32 v101, 31, v100
	v_lshl_or_b32 v98, v112, 2, v105
	v_lshlrev_b64 v[106:107], 12, v[100:101]
	v_ashrrev_i32_e32 v99, 31, v98
	v_lshl_add_u64 v[106:107], s[42:43], 0, v[106:107]
	v_lshl_add_u64 v[110:111], v[98:99], 2, v[106:107]
	s_barrier
	global_load_dwordx4 v[198:201], v[110:111], off
	v_add_co_u32_e32 v182, vcc, 0x4000, v110
	s_nop 1
	v_addc_co_u32_e32 v183, vcc, 0, v111, vcc
	global_load_dwordx4 v[202:205], v[182:183], off
	v_add_co_u32_e32 v182, vcc, 0x4000, v182
	s_nop 1
	v_addc_co_u32_e32 v183, vcc, 0, v183, vcc
	global_load_dwordx4 v[206:209], v[182:183], off
	v_add_co_u32_e32 v182, vcc, 0x4000, v182
	s_nop 1
	v_addc_co_u32_e32 v183, vcc, 0, v183, vcc
	global_load_dwordx4 v[210:213], v[182:183], off
	v_add_co_u32_e32 v182, vcc, 0x4000, v182
	s_nop 1
	v_addc_co_u32_e32 v183, vcc, 0, v183, vcc
	global_load_dwordx4 v[214:217], v[182:183], off
	v_add_co_u32_e32 v182, vcc, 0x4000, v182
	s_nop 1
	v_addc_co_u32_e32 v183, vcc, 0, v183, vcc
	global_load_dwordx4 v[218:221], v[182:183], off
	v_add_co_u32_e32 v182, vcc, 0x4000, v182
	s_nop 1
	v_addc_co_u32_e32 v183, vcc, 0, v183, vcc
	global_load_dwordx4 v[222:225], v[182:183], off
	v_add_co_u32_e32 v182, vcc, 0x4000, v182
	s_nop 1
	v_addc_co_u32_e32 v183, vcc, 0, v183, vcc
	global_load_dwordx4 v[226:229], v[182:183], off
	s_movk_i32 s2, 0x2400
	s_cmp_lt_i32 s5, 22
	v_mul_lo_u32 v97, v103, s2
	s_cselect_b64 s[2:3], -1, 0
	s_cmp_gt_i32 s5, 21
	s_movk_i32 s5, 0x110
	v_and_b32_e32 v103, 16, v104
	v_mad_u32_u24 v104, v102, s5, v97
	v_add_u32_e32 v113, 0xfffff000, v96
	v_cndmask_b32_e64 v102, 0, 1, s[2:3]
	s_cselect_b64 s[2:3], -1, 0
	s_add_i32 s7, s4, 0xfffff000
	v_add_u32_e32 v104, v104, v103
	ds_write_b128 v104, v[64:67]
	ds_write_b128 v104, v[68:71] offset:32
	ds_write_b128 v104, v[72:75] offset:64
	ds_write_b128 v104, v[76:79] offset:96
	ds_write_b128 v104, v[80:83] offset:128
	ds_write_b128 v104, v[84:87] offset:160
	ds_write_b128 v104, v[88:91] offset:192
	ds_write_b128 v104, v[92:95] offset:224
	v_xor_b32_e32 v64, s7, v113
	s_movk_i32 s4, 0x400
	v_lshl_or_b32 v97, v112, 4, v97
	v_cmp_gt_u32_e32 vcc, s4, v64
	v_mad_u32_u24 v115, v128, s5, v97
	s_and_b64 s[4:5], s[2:3], vcc
	v_cndmask_b32_e64 v71, 0, 1, s[4:5]
	s_movk_i32 s4, 0x1000
	v_cmp_gt_i32_e32 vcc, s4, v100
	v_subrev_u32_e32 v114, s8, v98
	v_lshl_add_u32 v103, v114, 2, v167
	v_cndmask_b32_e32 v64, v71, v102, vcc
	v_and_b32_e32 v64, 1, v64
	v_cmp_eq_u32_e32 vcc, 1, v64
	v_ashrrev_i32_e32 v68, 6, v105
	s_mov_b32 s4, 0xc000
	v_cndmask_b32_e64 v64, v171, 0, vcc
	v_add_u32_e32 v70, v103, v64
	ds_read_b128 v[64:67], v115
	ds_read_b128 v[72:75], v70
	v_cmp_eq_u32_e64 s[40:41], 0, v112
	v_mad_i64_i32 v[68:69], s[4:5], v68, s4, 0
	s_and_b64 vcc, exec, s[0:1]
	s_waitcnt vmcnt(7) lgkmcnt(0)
	v_pk_fma_f32 v[66:67], v[66:67], v[74:75], v[200:201]
	v_pk_fma_f32 v[64:65], v[64:65], v[72:73], v[198:199]
	global_store_dwordx4 v[110:111], v[64:67], off
	s_cbranch_vccnz .LBB0_1228
	ds_read_b128 v[72:75], v70 offset:2048
	v_lshlrev_b64 v[76:77], 10, v[100:101]
	v_lshl_add_u64 v[76:77], v[76:77], 1, s[44:45]
	v_lshl_add_u64 v[76:77], v[98:99], 1, v[76:77]
	s_waitcnt lgkmcnt(0)
	v_pk_mul_f32 v[72:73], v[64:65], v[72:73]
	v_pk_mul_f32 v[64:65], v[64:65], v[64:65]
	v_pk_mul_f32 v[74:75], v[66:67], v[74:75]
	v_pk_mul_f32 v[66:67], v[66:67], v[66:67]
	v_add_f32_e32 v64, v64, v65
	v_add_f32_e32 v64, v66, v64
	v_add_f32_e32 v64, v67, v64
	v_cvt_pk_bf16_f32 v72, v72, v73
	v_cvt_pk_bf16_f32 v73, v74, v75
	v_add_f32_dpp v64, v64, v64 quad_perm:[1,0,3,2] row_mask:0xf bank_mask:0xf bound_ctrl:1
	global_store_dwordx2 v[76:77], v[72:73], off
	s_nop 0
	v_add_f32_dpp v64, v64, v64 quad_perm:[2,3,0,1] row_mask:0xf bank_mask:0xf bound_ctrl:1
	s_nop 1
	v_add_f32_dpp v64, v64, v64 row_half_mirror row_mask:0xf bank_mask:0xf bound_ctrl:1
	s_nop 1
	v_mov_b32_dpp v65, v64 row_mirror row_mask:0xf bank_mask:0xf bound_ctrl:1
	s_and_saveexec_b64 s[4:5], s[40:41]
	s_cbranch_execz .LBB0_1227
	v_lshl_add_u64 v[66:67], s[48:49], 0, v[68:69]
	v_lshl_add_u64 v[66:67], v[100:101], 2, v[66:67]
	v_add_f32_e32 v64, v64, v65
	global_store_dword v[66:67], v64, off

.LBB0_1228:
	v_or_b32_e32 v70, 4, v128
	v_or_b32_e32 v72, v96, v70
	v_ashrrev_i32_e32 v73, 31, v72
	v_lshlrev_b64 v[64:65], 12, v[72:73]
	v_lshl_add_u64 v[64:65], s[42:43], 0, v[64:65]
	v_lshl_add_u64 v[84:85], v[98:99], 2, v[64:65]
	s_movk_i32 s4, 0x1000
	v_mul_u32_u24_e32 v74, 0x110, v128
	v_cmp_gt_i32_e32 vcc, s4, v72
	v_add_u32_e32 v86, v74, v97
	s_nop 0
	v_cndmask_b32_e32 v74, v71, v102, vcc
	v_and_b32_e32 v74, 1, v74
	v_cmp_eq_u32_e32 vcc, 1, v74
	s_nop 1
	v_cndmask_b32_e64 v74, v171, 0, vcc
	v_add_u32_e32 v74, v103, v74
	ds_read_b128 v[76:79], v86 offset:1088
	ds_read_b128 v[80:83], v74
	s_and_b64 vcc, exec, s[0:1]
	s_waitcnt vmcnt(7) lgkmcnt(0)
	v_pk_fma_f32 v[66:67], v[78:79], v[82:83], v[204:205]
	v_pk_fma_f32 v[64:65], v[76:77], v[80:81], v[202:203]
	global_store_dwordx4 v[84:85], v[64:67], off
	s_cbranch_vccnz .LBB0_1232
	ds_read_b128 v[74:77], v74 offset:2048
	v_lshlrev_b64 v[72:73], 10, v[72:73]
	v_lshl_add_u64 v[72:73], v[72:73], 1, s[44:45]
	v_lshl_add_u64 v[72:73], v[98:99], 1, v[72:73]
	s_waitcnt lgkmcnt(0)
	v_pk_mul_f32 v[74:75], v[64:65], v[74:75]
	v_pk_mul_f32 v[64:65], v[64:65], v[64:65]
	v_pk_mul_f32 v[76:77], v[66:67], v[76:77]
	v_pk_mul_f32 v[66:67], v[66:67], v[66:67]
	v_add_f32_e32 v64, v64, v65
	v_add_f32_e32 v64, v66, v64
	v_add_f32_e32 v64, v67, v64
	v_cvt_pk_bf16_f32 v74, v74, v75
	v_cvt_pk_bf16_f32 v75, v76, v77
	v_add_f32_dpp v64, v64, v64 quad_perm:[1,0,3,2] row_mask:0xf bank_mask:0xf bound_ctrl:1
	global_store_dwordx2 v[72:73], v[74:75], off
	s_nop 0
	v_add_f32_dpp v64, v64, v64 quad_perm:[2,3,0,1] row_mask:0xf bank_mask:0xf bound_ctrl:1
	s_nop 1
	v_add_f32_dpp v64, v64, v64 row_half_mirror row_mask:0xf bank_mask:0xf bound_ctrl:1
	s_nop 1
	v_mov_b32_dpp v65, v64 row_mirror row_mask:0xf bank_mask:0xf bound_ctrl:1
	s_and_saveexec_b64 s[4:5], s[40:41]
	s_cbranch_execz .LBB0_1231
	v_ashrrev_i32_e32 v97, 31, v96
	v_lshl_add_u64 v[66:67], s[48:49], 0, v[68:69]
	v_lshl_add_u64 v[72:73], v[96:97], 0, v[128:129]
	v_lshl_add_u64 v[66:67], v[72:73], 2, v[66:67]
	v_add_f32_e32 v64, v64, v65
	global_store_dword v[66:67], v64, off offset:16

.LBB0_1232:
	v_or_b32_e32 v72, 8, v128
	v_or_b32_e32 v74, v96, v72
	v_ashrrev_i32_e32 v75, 31, v74
	v_lshlrev_b64 v[64:65], 12, v[74:75]
	v_lshl_add_u64 v[64:65], s[42:43], 0, v[64:65]
	v_lshl_add_u64 v[84:85], v[98:99], 2, v[64:65]
	s_movk_i32 s4, 0x1000
	v_cmp_gt_i32_e32 vcc, s4, v74
	s_nop 1
	v_cndmask_b32_e32 v73, v71, v102, vcc
	v_and_b32_e32 v73, 1, v73
	v_cmp_eq_u32_e32 vcc, 1, v73
	s_nop 1
	v_cndmask_b32_e64 v73, v171, 0, vcc
	v_add_u32_e32 v73, v103, v73
	ds_read_b128 v[76:79], v86 offset:2176
	ds_read_b128 v[80:83], v73
	s_and_b64 vcc, exec, s[0:1]
	s_waitcnt vmcnt(7) lgkmcnt(0)
	v_pk_fma_f32 v[66:67], v[78:79], v[82:83], v[208:209]
	v_pk_fma_f32 v[64:65], v[76:77], v[80:81], v[206:207]
	global_store_dwordx4 v[84:85], v[64:67], off
	s_cbranch_vccnz .LBB0_1236
	ds_read_b128 v[76:79], v73 offset:2048
	v_lshlrev_b64 v[74:75], 10, v[74:75]
	v_lshl_add_u64 v[74:75], v[74:75], 1, s[44:45]
	v_lshl_add_u64 v[74:75], v[98:99], 1, v[74:75]
	s_waitcnt lgkmcnt(0)
	v_pk_mul_f32 v[76:77], v[64:65], v[76:77]
	v_pk_mul_f32 v[64:65], v[64:65], v[64:65]
	v_pk_mul_f32 v[78:79], v[66:67], v[78:79]
	v_pk_mul_f32 v[66:67], v[66:67], v[66:67]
	v_add_f32_e32 v64, v64, v65
	v_add_f32_e32 v64, v66, v64
	v_add_f32_e32 v64, v67, v64
	v_cvt_pk_bf16_f32 v76, v76, v77
	v_cvt_pk_bf16_f32 v77, v78, v79
	v_add_f32_dpp v64, v64, v64 quad_perm:[1,0,3,2] row_mask:0xf bank_mask:0xf bound_ctrl:1
	global_store_dwordx2 v[74:75], v[76:77], off
	s_nop 0
	v_add_f32_dpp v64, v64, v64 quad_perm:[2,3,0,1] row_mask:0xf bank_mask:0xf bound_ctrl:1
	s_nop 1
	v_add_f32_dpp v64, v64, v64 row_half_mirror row_mask:0xf bank_mask:0xf bound_ctrl:1
	s_nop 1
	v_mov_b32_dpp v65, v64 row_mirror row_mask:0xf bank_mask:0xf bound_ctrl:1
	s_and_saveexec_b64 s[4:5], s[40:41]
	s_cbranch_execz .LBB0_1235
	v_ashrrev_i32_e32 v97, 31, v96
	v_lshl_add_u64 v[66:67], s[48:49], 0, v[68:69]
	v_lshl_add_u64 v[74:75], v[96:97], 0, v[128:129]
	v_lshl_add_u64 v[66:67], v[74:75], 2, v[66:67]
	v_add_f32_e32 v64, v64, v65
	global_store_dword v[66:67], v64, off offset:32

.LBB0_1236:
	v_or_b32_e32 v74, 12, v128
	v_or_b32_e32 v76, v96, v74
	v_ashrrev_i32_e32 v77, 31, v76
	v_lshlrev_b64 v[64:65], 12, v[76:77]
	v_lshl_add_u64 v[64:65], s[42:43], 0, v[64:65]
	v_lshl_add_u64 v[88:89], v[98:99], 2, v[64:65]
	s_movk_i32 s4, 0x1000
	v_cmp_gt_i32_e32 vcc, s4, v76
	s_nop 1
	v_cndmask_b32_e32 v73, v71, v102, vcc
	v_and_b32_e32 v73, 1, v73
	v_cmp_eq_u32_e32 vcc, 1, v73
	s_nop 1
	v_cndmask_b32_e64 v73, v171, 0, vcc
	v_add_u32_e32 v73, v103, v73
	ds_read_b128 v[78:81], v86 offset:3264
	ds_read_b128 v[82:85], v73
	s_and_b64 vcc, exec, s[0:1]
	s_waitcnt vmcnt(7) lgkmcnt(0)
	v_pk_fma_f32 v[66:67], v[80:81], v[84:85], v[212:213]
	v_pk_fma_f32 v[64:65], v[78:79], v[82:83], v[210:211]
	global_store_dwordx4 v[88:89], v[64:67], off
	s_cbranch_vccnz .LBB0_1240
	ds_read_b128 v[78:81], v73 offset:2048
	v_lshlrev_b64 v[76:77], 10, v[76:77]
	v_lshl_add_u64 v[76:77], v[76:77], 1, s[44:45]
	v_lshl_add_u64 v[76:77], v[98:99], 1, v[76:77]
	s_waitcnt lgkmcnt(0)
	v_pk_mul_f32 v[78:79], v[64:65], v[78:79]
	v_pk_mul_f32 v[64:65], v[64:65], v[64:65]
	v_pk_mul_f32 v[80:81], v[66:67], v[80:81]
	v_pk_mul_f32 v[66:67], v[66:67], v[66:67]
	v_add_f32_e32 v64, v64, v65
	v_add_f32_e32 v64, v66, v64
	v_add_f32_e32 v64, v67, v64
	v_cvt_pk_bf16_f32 v78, v78, v79
	v_cvt_pk_bf16_f32 v79, v80, v81
	v_add_f32_dpp v64, v64, v64 quad_perm:[1,0,3,2] row_mask:0xf bank_mask:0xf bound_ctrl:1
	global_store_dwordx2 v[76:77], v[78:79], off
	s_nop 0
	v_add_f32_dpp v64, v64, v64 quad_perm:[2,3,0,1] row_mask:0xf bank_mask:0xf bound_ctrl:1
	s_nop 1
	v_add_f32_dpp v64, v64, v64 row_half_mirror row_mask:0xf bank_mask:0xf bound_ctrl:1
	s_nop 1
	v_mov_b32_dpp v65, v64 row_mirror row_mask:0xf bank_mask:0xf bound_ctrl:1
	s_and_saveexec_b64 s[4:5], s[40:41]
	s_cbranch_execz .LBB0_1239
	v_ashrrev_i32_e32 v97, 31, v96
	v_lshl_add_u64 v[66:67], s[48:49], 0, v[68:69]
	v_lshl_add_u64 v[76:77], v[96:97], 0, v[128:129]
	v_lshl_add_u64 v[66:67], v[76:77], 2, v[66:67]
	v_add_f32_e32 v64, v64, v65
	global_store_dword v[66:67], v64, off offset:48

.LBB0_1240:
	v_or_b32_e32 v76, 16, v128
	v_or_b32_e32 v78, v96, v76
	v_ashrrev_i32_e32 v79, 31, v78
	v_lshlrev_b64 v[64:65], 12, v[78:79]
	v_lshl_add_u64 v[64:65], s[42:43], 0, v[64:65]
	v_lshl_add_u64 v[84:85], v[98:99], 2, v[64:65]
	s_movk_i32 s4, 0x1000
	v_cmp_gt_i32_e32 vcc, s4, v78
	s_nop 1
	v_cndmask_b32_e32 v73, v71, v102, vcc
	v_and_b32_e32 v73, 1, v73
	v_cmp_eq_u32_e32 vcc, 1, v73
	s_nop 1
	v_cndmask_b32_e64 v73, v171, 0, vcc
	v_add_u32_e32 v73, v103, v73
	ds_read_b128 v[80:83], v86 offset:4352
	ds_read_b128 v[88:91], v73
	s_and_b64 vcc, exec, s[0:1]
	s_waitcnt vmcnt(7) lgkmcnt(0)
	v_pk_fma_f32 v[66:67], v[82:83], v[90:91], v[216:217]
	v_pk_fma_f32 v[64:65], v[80:81], v[88:89], v[214:215]
	global_store_dwordx4 v[84:85], v[64:67], off
	s_cbranch_vccnz .LBB0_1244
	ds_read_b128 v[80:83], v73 offset:2048
	v_lshlrev_b64 v[78:79], 10, v[78:79]
	v_lshl_add_u64 v[78:79], v[78:79], 1, s[44:45]
	v_lshl_add_u64 v[78:79], v[98:99], 1, v[78:79]
	s_waitcnt lgkmcnt(0)
	v_pk_mul_f32 v[80:81], v[64:65], v[80:81]
	v_pk_mul_f32 v[64:65], v[64:65], v[64:65]
	v_pk_mul_f32 v[82:83], v[66:67], v[82:83]
	v_pk_mul_f32 v[66:67], v[66:67], v[66:67]
	v_add_f32_e32 v64, v64, v65
	v_add_f32_e32 v64, v66, v64
	v_add_f32_e32 v64, v67, v64
	v_cvt_pk_bf16_f32 v80, v80, v81
	v_cvt_pk_bf16_f32 v81, v82, v83
	v_add_f32_dpp v64, v64, v64 quad_perm:[1,0,3,2] row_mask:0xf bank_mask:0xf bound_ctrl:1
	global_store_dwordx2 v[78:79], v[80:81], off
	s_nop 0
	v_add_f32_dpp v64, v64, v64 quad_perm:[2,3,0,1] row_mask:0xf bank_mask:0xf bound_ctrl:1
	s_nop 1
	v_add_f32_dpp v64, v64, v64 row_half_mirror row_mask:0xf bank_mask:0xf bound_ctrl:1
	s_nop 1
	v_mov_b32_dpp v65, v64 row_mirror row_mask:0xf bank_mask:0xf bound_ctrl:1
	s_and_saveexec_b64 s[4:5], s[40:41]
	s_cbranch_execz .LBB0_1243
	v_ashrrev_i32_e32 v97, 31, v96
	v_lshl_add_u64 v[66:67], s[48:49], 0, v[68:69]
	v_lshl_add_u64 v[78:79], v[96:97], 0, v[128:129]
	v_lshl_add_u64 v[66:67], v[78:79], 2, v[66:67]
	v_add_f32_e32 v64, v64, v65
	global_store_dword v[66:67], v64, off offset:64

.LBB0_1244:
	v_or_b32_e32 v78, 20, v128
	v_or_b32_e32 v80, v96, v78
	v_ashrrev_i32_e32 v81, 31, v80
	v_lshlrev_b64 v[64:65], 12, v[80:81]
	v_lshl_add_u64 v[64:65], s[42:43], 0, v[64:65]
	v_lshl_add_u64 v[92:93], v[98:99], 2, v[64:65]
	s_movk_i32 s4, 0x1000
	v_cmp_gt_i32_e32 vcc, s4, v80
	s_nop 1
	v_cndmask_b32_e32 v73, v71, v102, vcc
	v_and_b32_e32 v73, 1, v73
	v_cmp_eq_u32_e32 vcc, 1, v73
	s_nop 1
	v_cndmask_b32_e64 v73, v171, 0, vcc
	v_add_u32_e32 v73, v103, v73
	ds_read_b128 v[82:85], v86 offset:5440
	ds_read_b128 v[88:91], v73
	s_and_b64 vcc, exec, s[0:1]
	s_waitcnt vmcnt(7) lgkmcnt(0)
	v_pk_fma_f32 v[66:67], v[84:85], v[90:91], v[220:221]
	v_pk_fma_f32 v[64:65], v[82:83], v[88:89], v[218:219]
	global_store_dwordx4 v[92:93], v[64:67], off
	s_cbranch_vccnz .LBB0_1248
	ds_read_b128 v[82:85], v73 offset:2048
	v_lshlrev_b64 v[80:81], 10, v[80:81]
	v_lshl_add_u64 v[80:81], v[80:81], 1, s[44:45]
	v_lshl_add_u64 v[80:81], v[98:99], 1, v[80:81]
	s_waitcnt lgkmcnt(0)
	v_pk_mul_f32 v[82:83], v[64:65], v[82:83]
	v_pk_mul_f32 v[64:65], v[64:65], v[64:65]
	v_pk_mul_f32 v[84:85], v[66:67], v[84:85]
	v_pk_mul_f32 v[66:67], v[66:67], v[66:67]
	v_add_f32_e32 v64, v64, v65
	v_add_f32_e32 v64, v66, v64
	v_add_f32_e32 v64, v67, v64
	v_cvt_pk_bf16_f32 v82, v82, v83
	v_cvt_pk_bf16_f32 v83, v84, v85
	v_add_f32_dpp v64, v64, v64 quad_perm:[1,0,3,2] row_mask:0xf bank_mask:0xf bound_ctrl:1
	global_store_dwordx2 v[80:81], v[82:83], off
	s_nop 0
	v_add_f32_dpp v64, v64, v64 quad_perm:[2,3,0,1] row_mask:0xf bank_mask:0xf bound_ctrl:1
	s_nop 1
	v_add_f32_dpp v64, v64, v64 row_half_mirror row_mask:0xf bank_mask:0xf bound_ctrl:1
	s_nop 1
	v_mov_b32_dpp v65, v64 row_mirror row_mask:0xf bank_mask:0xf bound_ctrl:1
	s_and_saveexec_b64 s[4:5], s[40:41]
	s_cbranch_execz .LBB0_1247
	v_ashrrev_i32_e32 v97, 31, v96
	v_lshl_add_u64 v[66:67], s[48:49], 0, v[68:69]
	v_lshl_add_u64 v[80:81], v[96:97], 0, v[128:129]
	v_lshl_add_u64 v[66:67], v[80:81], 2, v[66:67]
	v_add_f32_e32 v64, v64, v65
	global_store_dword v[66:67], v64, off offset:80

.LBB0_1248:
	v_or_b32_e32 v80, 24, v128
	v_or_b32_e32 v82, v96, v80
	v_ashrrev_i32_e32 v83, 31, v82
	v_lshlrev_b64 v[64:65], 12, v[82:83]
	v_lshl_add_u64 v[64:65], s[42:43], 0, v[64:65]
	v_lshl_add_u64 v[84:85], v[98:99], 2, v[64:65]
	s_movk_i32 s4, 0x1000
	v_cmp_gt_i32_e32 vcc, s4, v82
	s_nop 1
	v_cndmask_b32_e32 v73, v71, v102, vcc
	v_and_b32_e32 v73, 1, v73
	v_cmp_eq_u32_e32 vcc, 1, v73
	s_nop 1
	v_cndmask_b32_e64 v73, v171, 0, vcc
	v_add_u32_e32 v73, v103, v73
	ds_read_b128 v[88:91], v86 offset:6528
	ds_read_b128 v[92:95], v73
	s_and_b64 vcc, exec, s[0:1]
	s_waitcnt vmcnt(7) lgkmcnt(0)
	v_pk_fma_f32 v[66:67], v[90:91], v[94:95], v[224:225]
	v_pk_fma_f32 v[64:65], v[88:89], v[92:93], v[222:223]
	global_store_dwordx4 v[84:85], v[64:67], off
	s_cbranch_vccnz .LBB0_1252
	ds_read_b128 v[88:91], v73 offset:2048
	v_lshlrev_b64 v[82:83], 10, v[82:83]
	v_lshl_add_u64 v[82:83], v[82:83], 1, s[44:45]
	v_lshl_add_u64 v[82:83], v[98:99], 1, v[82:83]
	s_waitcnt lgkmcnt(0)
	v_pk_mul_f32 v[88:89], v[64:65], v[88:89]
	v_pk_mul_f32 v[64:65], v[64:65], v[64:65]
	v_pk_mul_f32 v[84:85], v[66:67], v[90:91]
	v_pk_mul_f32 v[66:67], v[66:67], v[66:67]
	v_add_f32_e32 v64, v64, v65
	v_add_f32_e32 v64, v66, v64
	v_add_f32_e32 v64, v67, v64
	v_cvt_pk_bf16_f32 v88, v88, v89
	v_cvt_pk_bf16_f32 v89, v84, v85
	v_add_f32_dpp v64, v64, v64 quad_perm:[1,0,3,2] row_mask:0xf bank_mask:0xf bound_ctrl:1
	global_store_dwordx2 v[82:83], v[88:89], off
	s_nop 0
	v_add_f32_dpp v64, v64, v64 quad_perm:[2,3,0,1] row_mask:0xf bank_mask:0xf bound_ctrl:1
	s_nop 1
	v_add_f32_dpp v64, v64, v64 row_half_mirror row_mask:0xf bank_mask:0xf bound_ctrl:1
	s_nop 1
	v_mov_b32_dpp v65, v64 row_mirror row_mask:0xf bank_mask:0xf bound_ctrl:1
	s_and_saveexec_b64 s[4:5], s[40:41]
	s_cbranch_execz .LBB0_1251
	v_ashrrev_i32_e32 v97, 31, v96
	v_lshl_add_u64 v[66:67], s[48:49], 0, v[68:69]
	v_lshl_add_u64 v[82:83], v[96:97], 0, v[128:129]
	v_lshl_add_u64 v[66:67], v[82:83], 2, v[66:67]
	v_add_f32_e32 v64, v64, v65
	global_store_dword v[66:67], v64, off offset:96

.LBB0_1252:
	v_or_b32_e32 v82, 28, v128
	v_or_b32_e32 v84, v96, v82
	v_ashrrev_i32_e32 v85, 31, v84
	v_lshlrev_b64 v[64:65], 12, v[84:85]
	v_lshl_add_u64 v[64:65], s[42:43], 0, v[64:65]
	v_lshl_add_u64 v[100:101], v[98:99], 2, v[64:65]
	s_movk_i32 s4, 0x1000
	v_cmp_gt_i32_e32 vcc, s4, v84
	s_nop 1
	v_cndmask_b32_e32 v71, v71, v102, vcc
	v_and_b32_e32 v71, 1, v71
	v_cmp_eq_u32_e32 vcc, 1, v71
	s_nop 1
	v_cndmask_b32_e64 v71, v171, 0, vcc
	v_add_u32_e32 v71, v103, v71
	ds_read_b128 v[88:91], v86 offset:7616
	ds_read_b128 v[92:95], v71
	s_and_b64 vcc, exec, s[0:1]
	s_waitcnt vmcnt(7) lgkmcnt(0)
	v_pk_fma_f32 v[66:67], v[90:91], v[94:95], v[228:229]
	v_pk_fma_f32 v[64:65], v[88:89], v[92:93], v[226:227]
	global_store_dwordx4 v[100:101], v[64:67], off
	s_cbranch_vccnz .LBB0_1256
	ds_read_b128 v[88:91], v71 offset:2048
	v_lshlrev_b64 v[84:85], 10, v[84:85]
	v_lshl_add_u64 v[84:85], v[84:85], 1, s[44:45]
	v_lshl_add_u64 v[84:85], v[98:99], 1, v[84:85]
	s_waitcnt lgkmcnt(0)
	v_pk_mul_f32 v[88:89], v[64:65], v[88:89]
	v_pk_mul_f32 v[64:65], v[64:65], v[64:65]
	v_pk_mul_f32 v[90:91], v[66:67], v[90:91]
	v_pk_mul_f32 v[66:67], v[66:67], v[66:67]
	v_add_f32_e32 v64, v64, v65
	v_add_f32_e32 v64, v66, v64
	v_add_f32_e32 v64, v67, v64
	v_cvt_pk_bf16_f32 v88, v88, v89
	v_cvt_pk_bf16_f32 v89, v90, v91
	v_add_f32_dpp v64, v64, v64 quad_perm:[1,0,3,2] row_mask:0xf bank_mask:0xf bound_ctrl:1
	global_store_dwordx2 v[84:85], v[88:89], off
	s_nop 0
	v_add_f32_dpp v64, v64, v64 quad_perm:[2,3,0,1] row_mask:0xf bank_mask:0xf bound_ctrl:1
	s_nop 1
	v_add_f32_dpp v64, v64, v64 row_half_mirror row_mask:0xf bank_mask:0xf bound_ctrl:1
	s_nop 1
	v_mov_b32_dpp v65, v64 row_mirror row_mask:0xf bank_mask:0xf bound_ctrl:1
	s_and_saveexec_b64 s[4:5], s[40:41]
	s_cbranch_execz .LBB0_1255
	v_ashrrev_i32_e32 v97, 31, v96
	v_lshl_add_u64 v[66:67], s[48:49], 0, v[68:69]
	v_lshl_add_u64 v[84:85], v[96:97], 0, v[128:129]
	v_lshl_add_u64 v[66:67], v[84:85], 2, v[66:67]
	v_add_f32_e32 v64, v64, v65
	global_store_dword v[66:67], v64, off offset:112

.LBB0_1256:
	s_nop 0
	v_add_u32_e32 v66, 32, v96
	v_or_b32_e32 v64, v66, v128
	v_ashrrev_i32_e32 v65, 31, v64
	v_lshlrev_b64 v[84:85], 12, v[64:65]
	v_lshl_add_u64 v[84:85], s[42:43], 0, v[84:85]
	v_lshl_add_u64 v[84:85], v[98:99], 2, v[84:85]
	global_load_dwordx4 v[198:201], v[84:85], off
	v_add_co_u32_e32 v182, vcc, 0x4000, v84
	s_nop 1
	v_addc_co_u32_e32 v183, vcc, 0, v85, vcc
	global_load_dwordx4 v[202:205], v[182:183], off
	v_add_co_u32_e32 v182, vcc, 0x4000, v182
	s_nop 1
	v_addc_co_u32_e32 v183, vcc, 0, v183, vcc
	global_load_dwordx4 v[206:209], v[182:183], off
	v_add_co_u32_e32 v182, vcc, 0x4000, v182
	s_nop 1
	v_addc_co_u32_e32 v183, vcc, 0, v183, vcc
	global_load_dwordx4 v[210:213], v[182:183], off
	v_add_co_u32_e32 v182, vcc, 0x4000, v182
	s_nop 1
	v_addc_co_u32_e32 v183, vcc, 0, v183, vcc
	global_load_dwordx4 v[214:217], v[182:183], off
	v_add_co_u32_e32 v182, vcc, 0x4000, v182
	s_nop 1
	v_addc_co_u32_e32 v183, vcc, 0, v183, vcc
	global_load_dwordx4 v[218:221], v[182:183], off
	v_add_co_u32_e32 v182, vcc, 0x4000, v182
	s_nop 1
	v_addc_co_u32_e32 v183, vcc, 0, v183, vcc
	global_load_dwordx4 v[222:225], v[182:183], off
	v_add_co_u32_e32 v182, vcc, 0x4000, v182
	s_nop 1
	v_addc_co_u32_e32 v183, vcc, 0, v183, vcc
	global_load_dwordx4 v[226:229], v[182:183], off
	ds_write_b128 v104, v[32:35]
	ds_write_b128 v104, v[36:39] offset:32
	ds_write_b128 v104, v[40:43] offset:64
	ds_write_b128 v104, v[44:47] offset:96
	ds_write_b128 v104, v[48:51] offset:128
	ds_write_b128 v104, v[52:55] offset:160
	ds_write_b128 v104, v[56:59] offset:192
	ds_write_b128 v104, v[60:63] offset:224
	v_add_u32_e32 v32, 0xfffff020, v96
	v_xor_b32_e32 v32, s7, v32
	s_movk_i32 s4, 0x400
	v_cmp_gt_u32_e32 vcc, s4, v32
	s_and_b64 s[4:5], s[2:3], vcc
	v_cndmask_b32_e64 v38, 0, 1, s[4:5]
	s_movk_i32 s4, 0x1000
	v_cmp_gt_i32_e32 vcc, s4, v64
	s_nop 1
	v_cndmask_b32_e32 v32, v38, v102, vcc
	v_and_b32_e32 v32, 1, v32
	v_cmp_eq_u32_e32 vcc, 1, v32
	s_nop 1
	v_cndmask_b32_e64 v32, v171, 0, vcc
	v_add_u32_e32 v36, v103, v32
	ds_read_b128 v[32:35], v86
	ds_read_b128 v[40:43], v36
	s_and_b64 vcc, exec, s[0:1]
	s_waitcnt vmcnt(7) lgkmcnt(0)
	v_pk_fma_f32 v[34:35], v[34:35], v[42:43], v[200:201]
	v_pk_fma_f32 v[32:33], v[32:33], v[40:41], v[198:199]
	global_store_dwordx4 v[84:85], v[32:35], off
	s_cbranch_vccnz .LBB0_1260
	ds_read_b128 v[40:43], v36 offset:2048
	v_lshlrev_b64 v[36:37], 10, v[64:65]
	v_lshl_add_u64 v[36:37], v[36:37], 1, s[44:45]
	v_lshl_add_u64 v[36:37], v[98:99], 1, v[36:37]
	s_waitcnt lgkmcnt(0)
	v_pk_mul_f32 v[40:41], v[32:33], v[40:41]
	v_pk_mul_f32 v[32:33], v[32:33], v[32:33]
	v_pk_mul_f32 v[42:43], v[34:35], v[42:43]
	v_pk_mul_f32 v[34:35], v[34:35], v[34:35]
	v_add_f32_e32 v32, v32, v33
	v_add_f32_e32 v32, v34, v32
	v_add_f32_e32 v32, v35, v32
	v_cvt_pk_bf16_f32 v40, v40, v41
	v_cvt_pk_bf16_f32 v41, v42, v43
	v_add_f32_dpp v32, v32, v32 quad_perm:[1,0,3,2] row_mask:0xf bank_mask:0xf bound_ctrl:1
	global_store_dwordx2 v[36:37], v[40:41], off
	s_nop 0
	v_add_f32_dpp v32, v32, v32 quad_perm:[2,3,0,1] row_mask:0xf bank_mask:0xf bound_ctrl:1
	s_nop 1
	v_add_f32_dpp v32, v32, v32 row_half_mirror row_mask:0xf bank_mask:0xf bound_ctrl:1
	s_nop 1
	v_mov_b32_dpp v33, v32 row_mirror row_mask:0xf bank_mask:0xf bound_ctrl:1
	s_and_saveexec_b64 s[4:5], s[40:41]
	s_cbranch_execz .LBB0_1259
	v_ashrrev_i32_e32 v97, 31, v96
	v_lshl_add_u64 v[34:35], s[48:49], 0, v[68:69]
	v_lshl_add_u64 v[36:37], v[96:97], 0, v[128:129]
	v_lshl_add_u64 v[34:35], v[36:37], 2, v[34:35]
	v_add_f32_e32 v32, v32, v33
	global_store_dword v[34:35], v32, off offset:128

.LBB0_1260:
	v_or_b32_e32 v36, v66, v70
	v_ashrrev_i32_e32 v37, 31, v36
	v_lshlrev_b64 v[32:33], 12, v[36:37]
	v_lshl_add_u64 v[32:33], s[42:43], 0, v[32:33]
	v_lshl_add_u64 v[48:49], v[98:99], 2, v[32:33]
	s_movk_i32 s4, 0x1000
	v_cmp_gt_i32_e32 vcc, s4, v36
	s_nop 1
	v_cndmask_b32_e32 v39, v38, v102, vcc
	v_and_b32_e32 v39, 1, v39
	v_cmp_eq_u32_e32 vcc, 1, v39
	s_nop 1
	v_cndmask_b32_e64 v39, v171, 0, vcc
	v_add_u32_e32 v39, v103, v39
	ds_read_b128 v[40:43], v86 offset:1088
	ds_read_b128 v[44:47], v39
	s_and_b64 vcc, exec, s[0:1]
	s_waitcnt vmcnt(7) lgkmcnt(0)
	v_pk_fma_f32 v[34:35], v[42:43], v[46:47], v[204:205]
	v_pk_fma_f32 v[32:33], v[40:41], v[44:45], v[202:203]
	global_store_dwordx4 v[48:49], v[32:35], off
	s_cbranch_vccnz .LBB0_1264
	ds_read_b128 v[40:43], v39 offset:2048
	v_lshlrev_b64 v[36:37], 10, v[36:37]
	v_lshl_add_u64 v[36:37], v[36:37], 1, s[44:45]
	v_lshl_add_u64 v[36:37], v[98:99], 1, v[36:37]
	s_waitcnt lgkmcnt(0)
	v_pk_mul_f32 v[40:41], v[32:33], v[40:41]
	v_pk_mul_f32 v[32:33], v[32:33], v[32:33]
	v_pk_mul_f32 v[42:43], v[34:35], v[42:43]
	v_pk_mul_f32 v[34:35], v[34:35], v[34:35]
	v_add_f32_e32 v32, v32, v33
	v_add_f32_e32 v32, v34, v32
	v_add_f32_e32 v32, v35, v32
	v_cvt_pk_bf16_f32 v40, v40, v41
	v_cvt_pk_bf16_f32 v41, v42, v43
	v_add_f32_dpp v32, v32, v32 quad_perm:[1,0,3,2] row_mask:0xf bank_mask:0xf bound_ctrl:1
	global_store_dwordx2 v[36:37], v[40:41], off
	s_nop 0
	v_add_f32_dpp v32, v32, v32 quad_perm:[2,3,0,1] row_mask:0xf bank_mask:0xf bound_ctrl:1
	s_nop 1
	v_add_f32_dpp v32, v32, v32 row_half_mirror row_mask:0xf bank_mask:0xf bound_ctrl:1
	s_nop 1
	v_mov_b32_dpp v33, v32 row_mirror row_mask:0xf bank_mask:0xf bound_ctrl:1
	s_and_saveexec_b64 s[4:5], s[40:41]
	s_cbranch_execz .LBB0_1263
	v_mov_b32_e32 v71, v129
	v_ashrrev_i32_e32 v97, 31, v96
	v_lshl_add_u64 v[34:35], s[48:49], 0, v[68:69]
	v_lshl_add_u64 v[36:37], v[96:97], 0, v[70:71]
	v_lshl_add_u64 v[34:35], v[36:37], 2, v[34:35]
	v_add_f32_e32 v32, v32, v33
	global_store_dword v[34:35], v32, off offset:128

.LBB0_1264:
	v_or_b32_e32 v36, v66, v72
	v_ashrrev_i32_e32 v37, 31, v36
	v_lshlrev_b64 v[32:33], 12, v[36:37]
	v_lshl_add_u64 v[32:33], s[42:43], 0, v[32:33]
	v_lshl_add_u64 v[48:49], v[98:99], 2, v[32:33]
	s_movk_i32 s4, 0x1000
	v_cmp_gt_i32_e32 vcc, s4, v36
	s_nop 1
	v_cndmask_b32_e32 v39, v38, v102, vcc
	v_and_b32_e32 v39, 1, v39
	v_cmp_eq_u32_e32 vcc, 1, v39
	s_nop 1
	v_cndmask_b32_e64 v39, v171, 0, vcc
	v_add_u32_e32 v39, v103, v39
	ds_read_b128 v[40:43], v86 offset:2176
	ds_read_b128 v[44:47], v39
	s_and_b64 vcc, exec, s[0:1]
	s_waitcnt vmcnt(7) lgkmcnt(0)
	v_pk_fma_f32 v[34:35], v[42:43], v[46:47], v[208:209]
	v_pk_fma_f32 v[32:33], v[40:41], v[44:45], v[206:207]
	global_store_dwordx4 v[48:49], v[32:35], off
	s_cbranch_vccnz .LBB0_1268
	ds_read_b128 v[40:43], v39 offset:2048
	v_lshlrev_b64 v[36:37], 10, v[36:37]
	v_lshl_add_u64 v[36:37], v[36:37], 1, s[44:45]
	v_lshl_add_u64 v[36:37], v[98:99], 1, v[36:37]
	s_waitcnt lgkmcnt(0)
	v_pk_mul_f32 v[40:41], v[32:33], v[40:41]
	v_pk_mul_f32 v[32:33], v[32:33], v[32:33]
	v_pk_mul_f32 v[42:43], v[34:35], v[42:43]
	v_pk_mul_f32 v[34:35], v[34:35], v[34:35]
	v_add_f32_e32 v32, v32, v33
	v_add_f32_e32 v32, v34, v32
	v_add_f32_e32 v32, v35, v32
	v_cvt_pk_bf16_f32 v40, v40, v41
	v_cvt_pk_bf16_f32 v41, v42, v43
	v_add_f32_dpp v32, v32, v32 quad_perm:[1,0,3,2] row_mask:0xf bank_mask:0xf bound_ctrl:1
	global_store_dwordx2 v[36:37], v[40:41], off
	s_nop 0
	v_add_f32_dpp v32, v32, v32 quad_perm:[2,3,0,1] row_mask:0xf bank_mask:0xf bound_ctrl:1
	s_nop 1
	v_add_f32_dpp v32, v32, v32 row_half_mirror row_mask:0xf bank_mask:0xf bound_ctrl:1
	s_nop 1
	v_mov_b32_dpp v33, v32 row_mirror row_mask:0xf bank_mask:0xf bound_ctrl:1
	s_and_saveexec_b64 s[4:5], s[40:41]
	s_cbranch_execz .LBB0_1267
	v_mov_b32_e32 v73, v129
	v_ashrrev_i32_e32 v97, 31, v96
	v_lshl_add_u64 v[34:35], s[48:49], 0, v[68:69]
	v_lshl_add_u64 v[36:37], v[96:97], 0, v[72:73]
	v_lshl_add_u64 v[34:35], v[36:37], 2, v[34:35]
	v_add_f32_e32 v32, v32, v33
	global_store_dword v[34:35], v32, off offset:128

.LBB0_1268:
	v_or_b32_e32 v36, v66, v74
	v_ashrrev_i32_e32 v37, 31, v36
	v_lshlrev_b64 v[32:33], 12, v[36:37]
	v_lshl_add_u64 v[32:33], s[42:43], 0, v[32:33]
	v_lshl_add_u64 v[48:49], v[98:99], 2, v[32:33]
	s_movk_i32 s4, 0x1000
	v_cmp_gt_i32_e32 vcc, s4, v36
	s_nop 1
	v_cndmask_b32_e32 v39, v38, v102, vcc
	v_and_b32_e32 v39, 1, v39
	v_cmp_eq_u32_e32 vcc, 1, v39
	s_nop 1
	v_cndmask_b32_e64 v39, v171, 0, vcc
	v_add_u32_e32 v39, v103, v39
	ds_read_b128 v[40:43], v86 offset:3264
	ds_read_b128 v[44:47], v39
	s_and_b64 vcc, exec, s[0:1]
	s_waitcnt vmcnt(7) lgkmcnt(0)
	v_pk_fma_f32 v[34:35], v[42:43], v[46:47], v[212:213]
	v_pk_fma_f32 v[32:33], v[40:41], v[44:45], v[210:211]
	global_store_dwordx4 v[48:49], v[32:35], off
	s_cbranch_vccnz .LBB0_1272
	ds_read_b128 v[40:43], v39 offset:2048
	v_lshlrev_b64 v[36:37], 10, v[36:37]
	v_lshl_add_u64 v[36:37], v[36:37], 1, s[44:45]
	v_lshl_add_u64 v[36:37], v[98:99], 1, v[36:37]
	s_waitcnt lgkmcnt(0)
	v_pk_mul_f32 v[40:41], v[32:33], v[40:41]
	v_pk_mul_f32 v[32:33], v[32:33], v[32:33]
	v_pk_mul_f32 v[42:43], v[34:35], v[42:43]
	v_pk_mul_f32 v[34:35], v[34:35], v[34:35]
	v_add_f32_e32 v32, v32, v33
	v_add_f32_e32 v32, v34, v32
	v_add_f32_e32 v32, v35, v32
	v_cvt_pk_bf16_f32 v40, v40, v41
	v_cvt_pk_bf16_f32 v41, v42, v43
	v_add_f32_dpp v32, v32, v32 quad_perm:[1,0,3,2] row_mask:0xf bank_mask:0xf bound_ctrl:1
	global_store_dwordx2 v[36:37], v[40:41], off
	s_nop 0
	v_add_f32_dpp v32, v32, v32 quad_perm:[2,3,0,1] row_mask:0xf bank_mask:0xf bound_ctrl:1
	s_nop 1
	v_add_f32_dpp v32, v32, v32 row_half_mirror row_mask:0xf bank_mask:0xf bound_ctrl:1
	s_nop 1
	v_mov_b32_dpp v33, v32 row_mirror row_mask:0xf bank_mask:0xf bound_ctrl:1
	s_and_saveexec_b64 s[4:5], s[40:41]
	s_cbranch_execz .LBB0_1271
	v_mov_b32_e32 v75, v129
	v_ashrrev_i32_e32 v97, 31, v96
	v_lshl_add_u64 v[34:35], s[48:49], 0, v[68:69]
	v_lshl_add_u64 v[36:37], v[96:97], 0, v[74:75]
	v_lshl_add_u64 v[34:35], v[36:37], 2, v[34:35]
	v_add_f32_e32 v32, v32, v33
	global_store_dword v[34:35], v32, off offset:128

.LBB0_1272:
	v_or_b32_e32 v36, v66, v76
	v_ashrrev_i32_e32 v37, 31, v36
	v_lshlrev_b64 v[32:33], 12, v[36:37]
	v_lshl_add_u64 v[32:33], s[42:43], 0, v[32:33]
	v_lshl_add_u64 v[48:49], v[98:99], 2, v[32:33]
	s_movk_i32 s4, 0x1000
	v_cmp_gt_i32_e32 vcc, s4, v36
	s_nop 1
	v_cndmask_b32_e32 v39, v38, v102, vcc
	v_and_b32_e32 v39, 1, v39
	v_cmp_eq_u32_e32 vcc, 1, v39
	s_nop 1
	v_cndmask_b32_e64 v39, v171, 0, vcc
	v_add_u32_e32 v39, v103, v39
	ds_read_b128 v[40:43], v86 offset:4352
	ds_read_b128 v[44:47], v39
	s_and_b64 vcc, exec, s[0:1]
	s_waitcnt vmcnt(7) lgkmcnt(0)
	v_pk_fma_f32 v[34:35], v[42:43], v[46:47], v[216:217]
	v_pk_fma_f32 v[32:33], v[40:41], v[44:45], v[214:215]
	global_store_dwordx4 v[48:49], v[32:35], off
	s_cbranch_vccnz .LBB0_1276
	ds_read_b128 v[40:43], v39 offset:2048
	v_lshlrev_b64 v[36:37], 10, v[36:37]
	v_lshl_add_u64 v[36:37], v[36:37], 1, s[44:45]
	v_lshl_add_u64 v[36:37], v[98:99], 1, v[36:37]
	s_waitcnt lgkmcnt(0)
	v_pk_mul_f32 v[40:41], v[32:33], v[40:41]
	v_pk_mul_f32 v[32:33], v[32:33], v[32:33]
	v_pk_mul_f32 v[42:43], v[34:35], v[42:43]
	v_pk_mul_f32 v[34:35], v[34:35], v[34:35]
	v_add_f32_e32 v32, v32, v33
	v_add_f32_e32 v32, v34, v32
	v_add_f32_e32 v32, v35, v32
	v_cvt_pk_bf16_f32 v40, v40, v41
	v_cvt_pk_bf16_f32 v41, v42, v43
	v_add_f32_dpp v32, v32, v32 quad_perm:[1,0,3,2] row_mask:0xf bank_mask:0xf bound_ctrl:1
	global_store_dwordx2 v[36:37], v[40:41], off
	s_nop 0
	v_add_f32_dpp v32, v32, v32 quad_perm:[2,3,0,1] row_mask:0xf bank_mask:0xf bound_ctrl:1
	s_nop 1
	v_add_f32_dpp v32, v32, v32 row_half_mirror row_mask:0xf bank_mask:0xf bound_ctrl:1
	s_nop 1
	v_mov_b32_dpp v33, v32 row_mirror row_mask:0xf bank_mask:0xf bound_ctrl:1
	s_and_saveexec_b64 s[4:5], s[40:41]
	s_cbranch_execz .LBB0_1275
	v_mov_b32_e32 v77, v129
	v_ashrrev_i32_e32 v97, 31, v96
	v_lshl_add_u64 v[34:35], s[48:49], 0, v[68:69]
	v_lshl_add_u64 v[36:37], v[96:97], 0, v[76:77]
	v_lshl_add_u64 v[34:35], v[36:37], 2, v[34:35]
	v_add_f32_e32 v32, v32, v33
	global_store_dword v[34:35], v32, off offset:128

.LBB0_1276:
	v_or_b32_e32 v36, v66, v78
	v_ashrrev_i32_e32 v37, 31, v36
	v_lshlrev_b64 v[32:33], 12, v[36:37]
	v_lshl_add_u64 v[32:33], s[42:43], 0, v[32:33]
	v_lshl_add_u64 v[48:49], v[98:99], 2, v[32:33]
	s_movk_i32 s4, 0x1000
	v_cmp_gt_i32_e32 vcc, s4, v36
	s_nop 1
	v_cndmask_b32_e32 v39, v38, v102, vcc
	v_and_b32_e32 v39, 1, v39
	v_cmp_eq_u32_e32 vcc, 1, v39
	s_nop 1
	v_cndmask_b32_e64 v39, v171, 0, vcc
	v_add_u32_e32 v39, v103, v39
	ds_read_b128 v[40:43], v86 offset:5440
	ds_read_b128 v[44:47], v39
	s_and_b64 vcc, exec, s[0:1]
	s_waitcnt vmcnt(7) lgkmcnt(0)
	v_pk_fma_f32 v[34:35], v[42:43], v[46:47], v[220:221]
	v_pk_fma_f32 v[32:33], v[40:41], v[44:45], v[218:219]
	global_store_dwordx4 v[48:49], v[32:35], off
	s_cbranch_vccnz .LBB0_1280
	ds_read_b128 v[40:43], v39 offset:2048
	v_lshlrev_b64 v[36:37], 10, v[36:37]
	v_lshl_add_u64 v[36:37], v[36:37], 1, s[44:45]
	v_lshl_add_u64 v[36:37], v[98:99], 1, v[36:37]
	s_waitcnt lgkmcnt(0)
	v_pk_mul_f32 v[40:41], v[32:33], v[40:41]
	v_pk_mul_f32 v[32:33], v[32:33], v[32:33]
	v_pk_mul_f32 v[42:43], v[34:35], v[42:43]
	v_pk_mul_f32 v[34:35], v[34:35], v[34:35]
	v_add_f32_e32 v32, v32, v33
	v_add_f32_e32 v32, v34, v32
	v_add_f32_e32 v32, v35, v32
	v_cvt_pk_bf16_f32 v40, v40, v41
	v_cvt_pk_bf16_f32 v41, v42, v43
	v_add_f32_dpp v32, v32, v32 quad_perm:[1,0,3,2] row_mask:0xf bank_mask:0xf bound_ctrl:1
	global_store_dwordx2 v[36:37], v[40:41], off
	s_nop 0
	v_add_f32_dpp v32, v32, v32 quad_perm:[2,3,0,1] row_mask:0xf bank_mask:0xf bound_ctrl:1
	s_nop 1
	v_add_f32_dpp v32, v32, v32 row_half_mirror row_mask:0xf bank_mask:0xf bound_ctrl:1
	s_nop 1
	v_mov_b32_dpp v33, v32 row_mirror row_mask:0xf bank_mask:0xf bound_ctrl:1
	s_and_saveexec_b64 s[4:5], s[40:41]
	s_cbranch_execz .LBB0_1279
	v_mov_b32_e32 v79, v129
	v_ashrrev_i32_e32 v97, 31, v96
	v_lshl_add_u64 v[34:35], s[48:49], 0, v[68:69]
	v_lshl_add_u64 v[36:37], v[96:97], 0, v[78:79]
	v_lshl_add_u64 v[34:35], v[36:37], 2, v[34:35]
	v_add_f32_e32 v32, v32, v33
	global_store_dword v[34:35], v32, off offset:128

.LBB0_1280:
	v_or_b32_e32 v36, v66, v80
	v_ashrrev_i32_e32 v37, 31, v36
	v_lshlrev_b64 v[32:33], 12, v[36:37]
	v_lshl_add_u64 v[32:33], s[42:43], 0, v[32:33]
	v_lshl_add_u64 v[48:49], v[98:99], 2, v[32:33]
	s_movk_i32 s4, 0x1000
	v_cmp_gt_i32_e32 vcc, s4, v36
	s_nop 1
	v_cndmask_b32_e32 v39, v38, v102, vcc
	v_and_b32_e32 v39, 1, v39
	v_cmp_eq_u32_e32 vcc, 1, v39
	s_nop 1
	v_cndmask_b32_e64 v39, v171, 0, vcc
	v_add_u32_e32 v39, v103, v39
	ds_read_b128 v[40:43], v86 offset:6528
	ds_read_b128 v[44:47], v39
	s_and_b64 vcc, exec, s[0:1]
	s_waitcnt vmcnt(7) lgkmcnt(0)
	v_pk_fma_f32 v[34:35], v[42:43], v[46:47], v[224:225]
	v_pk_fma_f32 v[32:33], v[40:41], v[44:45], v[222:223]
	global_store_dwordx4 v[48:49], v[32:35], off
	s_cbranch_vccnz .LBB0_1284
	ds_read_b128 v[40:43], v39 offset:2048
	v_lshlrev_b64 v[36:37], 10, v[36:37]
	v_lshl_add_u64 v[36:37], v[36:37], 1, s[44:45]
	v_lshl_add_u64 v[36:37], v[98:99], 1, v[36:37]
	s_waitcnt lgkmcnt(0)
	v_pk_mul_f32 v[40:41], v[32:33], v[40:41]
	v_pk_mul_f32 v[32:33], v[32:33], v[32:33]
	v_pk_mul_f32 v[42:43], v[34:35], v[42:43]
	v_pk_mul_f32 v[34:35], v[34:35], v[34:35]
	v_add_f32_e32 v32, v32, v33
	v_add_f32_e32 v32, v34, v32
	v_add_f32_e32 v32, v35, v32
	v_cvt_pk_bf16_f32 v40, v40, v41
	v_cvt_pk_bf16_f32 v41, v42, v43
	v_add_f32_dpp v32, v32, v32 quad_perm:[1,0,3,2] row_mask:0xf bank_mask:0xf bound_ctrl:1
	global_store_dwordx2 v[36:37], v[40:41], off
	s_nop 0
	v_add_f32_dpp v32, v32, v32 quad_perm:[2,3,0,1] row_mask:0xf bank_mask:0xf bound_ctrl:1
	s_nop 1
	v_add_f32_dpp v32, v32, v32 row_half_mirror row_mask:0xf bank_mask:0xf bound_ctrl:1
	s_nop 1
	v_mov_b32_dpp v33, v32 row_mirror row_mask:0xf bank_mask:0xf bound_ctrl:1
	s_and_saveexec_b64 s[4:5], s[40:41]
	s_cbranch_execz .LBB0_1283
	v_mov_b32_e32 v81, v129
	v_ashrrev_i32_e32 v97, 31, v96
	v_lshl_add_u64 v[34:35], s[48:49], 0, v[68:69]
	v_lshl_add_u64 v[36:37], v[96:97], 0, v[80:81]
	v_lshl_add_u64 v[34:35], v[36:37], 2, v[34:35]
	v_add_f32_e32 v32, v32, v33
	global_store_dword v[34:35], v32, off offset:128

.LBB0_1284:
	v_or_b32_e32 v36, v66, v82
	v_ashrrev_i32_e32 v37, 31, v36
	v_lshlrev_b64 v[32:33], 12, v[36:37]
	v_lshl_add_u64 v[32:33], s[42:43], 0, v[32:33]
	v_lshl_add_u64 v[48:49], v[98:99], 2, v[32:33]
	s_movk_i32 s4, 0x1000
	v_cmp_gt_i32_e32 vcc, s4, v36
	s_nop 1
	v_cndmask_b32_e32 v38, v38, v102, vcc
	v_and_b32_e32 v38, 1, v38
	v_cmp_eq_u32_e32 vcc, 1, v38
	s_nop 1
	v_cndmask_b32_e64 v38, v171, 0, vcc
	v_add_u32_e32 v38, v103, v38
	ds_read_b128 v[40:43], v86 offset:7616
	ds_read_b128 v[44:47], v38
	s_and_b64 vcc, exec, s[0:1]
	s_waitcnt vmcnt(7) lgkmcnt(0)
	v_pk_fma_f32 v[34:35], v[42:43], v[46:47], v[228:229]
	v_pk_fma_f32 v[32:33], v[40:41], v[44:45], v[226:227]
	global_store_dwordx4 v[48:49], v[32:35], off
	s_cbranch_vccnz .LBB0_1288
	ds_read_b128 v[38:41], v38 offset:2048
	v_lshlrev_b64 v[36:37], 10, v[36:37]
	v_lshl_add_u64 v[36:37], v[36:37], 1, s[44:45]
	v_lshl_add_u64 v[36:37], v[98:99], 1, v[36:37]
	s_waitcnt lgkmcnt(0)
	v_pk_mul_f32 v[38:39], v[32:33], v[38:39]
	v_pk_mul_f32 v[32:33], v[32:33], v[32:33]
	v_pk_mul_f32 v[40:41], v[34:35], v[40:41]
	v_pk_mul_f32 v[34:35], v[34:35], v[34:35]
	v_add_f32_e32 v32, v32, v33
	v_add_f32_e32 v32, v34, v32
	v_add_f32_e32 v32, v35, v32
	v_cvt_pk_bf16_f32 v38, v38, v39
	v_cvt_pk_bf16_f32 v39, v40, v41
	v_add_f32_dpp v32, v32, v32 quad_perm:[1,0,3,2] row_mask:0xf bank_mask:0xf bound_ctrl:1
	global_store_dwordx2 v[36:37], v[38:39], off
	s_nop 0
	v_add_f32_dpp v32, v32, v32 quad_perm:[2,3,0,1] row_mask:0xf bank_mask:0xf bound_ctrl:1
	s_nop 1
	v_add_f32_dpp v32, v32, v32 row_half_mirror row_mask:0xf bank_mask:0xf bound_ctrl:1
	s_nop 1
	v_mov_b32_dpp v33, v32 row_mirror row_mask:0xf bank_mask:0xf bound_ctrl:1
	s_and_saveexec_b64 s[4:5], s[40:41]
	s_cbranch_execz .LBB0_1287
	v_mov_b32_e32 v83, v129
	v_ashrrev_i32_e32 v97, 31, v96
	v_lshl_add_u64 v[34:35], s[48:49], 0, v[68:69]
	v_lshl_add_u64 v[36:37], v[96:97], 0, v[82:83]
	v_lshl_add_u64 v[34:35], v[36:37], 2, v[34:35]
	v_add_f32_e32 v32, v32, v33
	global_store_dword v[34:35], v32, off offset:128

.LBB0_1288:
	s_nop 0
	v_add_u32_e32 v34, 64, v96
	v_or_b32_e32 v32, v34, v128
	v_ashrrev_i32_e32 v33, 31, v32
	v_lshlrev_b64 v[36:37], 12, v[32:33]
	v_lshl_add_u64 v[36:37], s[42:43], 0, v[36:37]
	v_lshl_add_u64 v[40:41], v[98:99], 2, v[36:37]
	global_load_dwordx4 v[198:201], v[40:41], off
	v_add_co_u32_e32 v182, vcc, 0x4000, v40
	s_nop 1
	v_addc_co_u32_e32 v183, vcc, 0, v41, vcc
	global_load_dwordx4 v[202:205], v[182:183], off
	v_add_co_u32_e32 v182, vcc, 0x4000, v182
	s_nop 1
	v_addc_co_u32_e32 v183, vcc, 0, v183, vcc
	global_load_dwordx4 v[206:209], v[182:183], off
	v_add_co_u32_e32 v182, vcc, 0x4000, v182
	s_nop 1
	v_addc_co_u32_e32 v183, vcc, 0, v183, vcc
	global_load_dwordx4 v[210:213], v[182:183], off
	v_add_co_u32_e32 v182, vcc, 0x4000, v182
	s_nop 1
	v_addc_co_u32_e32 v183, vcc, 0, v183, vcc
	global_load_dwordx4 v[214:217], v[182:183], off
	v_add_co_u32_e32 v182, vcc, 0x4000, v182
	s_nop 1
	v_addc_co_u32_e32 v183, vcc, 0, v183, vcc
	global_load_dwordx4 v[218:221], v[182:183], off
	v_add_co_u32_e32 v182, vcc, 0x4000, v182
	s_nop 1
	v_addc_co_u32_e32 v183, vcc, 0, v183, vcc
	global_load_dwordx4 v[222:225], v[182:183], off
	v_add_co_u32_e32 v182, vcc, 0x4000, v182
	s_nop 1
	v_addc_co_u32_e32 v183, vcc, 0, v183, vcc
	global_load_dwordx4 v[226:229], v[182:183], off
	ds_write_b128 v104, v[0:3]
	ds_write_b128 v104, v[4:7] offset:32
	ds_write_b128 v104, v[8:11] offset:64
	ds_write_b128 v104, v[12:15] offset:96
	ds_write_b128 v104, v[16:19] offset:128
	ds_write_b128 v104, v[20:23] offset:160
	ds_write_b128 v104, v[24:27] offset:192
	ds_write_b128 v104, v[28:31] offset:224
	v_add_u32_e32 v0, 0xfffff040, v96
	v_xor_b32_e32 v0, s7, v0
	s_movk_i32 s4, 0x400
	v_cmp_gt_u32_e32 vcc, s4, v0
	s_and_b64 s[2:3], s[2:3], vcc
	v_cndmask_b32_e64 v6, 0, 1, s[2:3]
	s_movk_i32 s2, 0x1000
	v_cmp_gt_i32_e32 vcc, s2, v32
	s_nop 1
	v_cndmask_b32_e32 v0, v6, v102, vcc
	v_and_b32_e32 v0, 1, v0
	v_cmp_eq_u32_e32 vcc, 1, v0
	s_nop 1
	v_cndmask_b32_e64 v0, v171, 0, vcc
	v_add_u32_e32 v4, v103, v0
	ds_read_b128 v[0:3], v86
	ds_read_b128 v[8:11], v4
	s_and_b64 vcc, exec, s[0:1]
	s_waitcnt vmcnt(7) lgkmcnt(0)
	v_pk_fma_f32 v[2:3], v[2:3], v[10:11], v[200:201]
	v_pk_fma_f32 v[0:1], v[0:1], v[8:9], v[198:199]
	global_store_dwordx4 v[40:41], v[0:3], off
	s_cbranch_vccnz .LBB0_1292
	ds_read_b128 v[8:11], v4 offset:2048
	v_lshlrev_b64 v[4:5], 10, v[32:33]
	v_lshl_add_u64 v[4:5], v[4:5], 1, s[44:45]
	v_lshl_add_u64 v[4:5], v[98:99], 1, v[4:5]
	s_waitcnt lgkmcnt(0)
	v_pk_mul_f32 v[8:9], v[0:1], v[8:9]
	v_pk_mul_f32 v[0:1], v[0:1], v[0:1]
	v_pk_mul_f32 v[10:11], v[2:3], v[10:11]
	v_pk_mul_f32 v[2:3], v[2:3], v[2:3]
	v_add_f32_e32 v0, v0, v1
	v_add_f32_e32 v0, v2, v0
	v_add_f32_e32 v0, v3, v0
	v_cvt_pk_bf16_f32 v8, v8, v9
	v_cvt_pk_bf16_f32 v9, v10, v11
	v_add_f32_dpp v0, v0, v0 quad_perm:[1,0,3,2] row_mask:0xf bank_mask:0xf bound_ctrl:1
	global_store_dwordx2 v[4:5], v[8:9], off
	s_nop 0
	v_add_f32_dpp v0, v0, v0 quad_perm:[2,3,0,1] row_mask:0xf bank_mask:0xf bound_ctrl:1
	s_nop 1
	v_add_f32_dpp v0, v0, v0 row_half_mirror row_mask:0xf bank_mask:0xf bound_ctrl:1
	s_nop 1
	v_mov_b32_dpp v1, v0 row_mirror row_mask:0xf bank_mask:0xf bound_ctrl:1
	s_and_saveexec_b64 s[2:3], s[40:41]
	s_cbranch_execz .LBB0_1291
	v_ashrrev_i32_e32 v97, 31, v96
	v_lshl_add_u64 v[2:3], s[48:49], 0, v[68:69]
	v_lshl_add_u64 v[4:5], v[96:97], 0, v[128:129]
	v_lshl_add_u64 v[2:3], v[4:5], 2, v[2:3]
	v_add_f32_e32 v0, v0, v1
	global_store_dword v[2:3], v0, off offset:256

.LBB0_1292:
	v_or_b32_e32 v4, v34, v70
	v_ashrrev_i32_e32 v5, 31, v4
	v_lshlrev_b64 v[0:1], 12, v[4:5]
	v_lshl_add_u64 v[0:1], s[42:43], 0, v[0:1]
	v_lshl_add_u64 v[16:17], v[98:99], 2, v[0:1]
	s_movk_i32 s2, 0x1000
	v_cmp_gt_i32_e32 vcc, s2, v4
	s_nop 1
	v_cndmask_b32_e32 v7, v6, v102, vcc
	v_and_b32_e32 v7, 1, v7
	v_cmp_eq_u32_e32 vcc, 1, v7
	s_nop 1
	v_cndmask_b32_e64 v7, v171, 0, vcc
	v_add_u32_e32 v7, v103, v7
	ds_read_b128 v[8:11], v86 offset:1088
	ds_read_b128 v[12:15], v7
	s_and_b64 vcc, exec, s[0:1]
	s_waitcnt vmcnt(7) lgkmcnt(0)
	v_pk_fma_f32 v[2:3], v[10:11], v[14:15], v[204:205]
	v_pk_fma_f32 v[0:1], v[8:9], v[12:13], v[202:203]
	global_store_dwordx4 v[16:17], v[0:3], off
	s_cbranch_vccnz .LBB0_1296
	ds_read_b128 v[8:11], v7 offset:2048
	v_lshlrev_b64 v[4:5], 10, v[4:5]
	v_lshl_add_u64 v[4:5], v[4:5], 1, s[44:45]
	v_lshl_add_u64 v[4:5], v[98:99], 1, v[4:5]
	s_waitcnt lgkmcnt(0)
	v_pk_mul_f32 v[8:9], v[0:1], v[8:9]
	v_pk_mul_f32 v[0:1], v[0:1], v[0:1]
	v_pk_mul_f32 v[10:11], v[2:3], v[10:11]
	v_pk_mul_f32 v[2:3], v[2:3], v[2:3]
	v_add_f32_e32 v0, v0, v1
	v_add_f32_e32 v0, v2, v0
	v_add_f32_e32 v0, v3, v0
	v_cvt_pk_bf16_f32 v8, v8, v9
	v_cvt_pk_bf16_f32 v9, v10, v11
	v_add_f32_dpp v0, v0, v0 quad_perm:[1,0,3,2] row_mask:0xf bank_mask:0xf bound_ctrl:1
	global_store_dwordx2 v[4:5], v[8:9], off
	s_nop 0
	v_add_f32_dpp v0, v0, v0 quad_perm:[2,3,0,1] row_mask:0xf bank_mask:0xf bound_ctrl:1
	s_nop 1
	v_add_f32_dpp v0, v0, v0 row_half_mirror row_mask:0xf bank_mask:0xf bound_ctrl:1
	s_nop 1
	v_mov_b32_dpp v1, v0 row_mirror row_mask:0xf bank_mask:0xf bound_ctrl:1
	s_and_saveexec_b64 s[2:3], s[40:41]
	s_cbranch_execz .LBB0_1295
	v_mov_b32_e32 v71, v129
	v_ashrrev_i32_e32 v97, 31, v96
	v_lshl_add_u64 v[2:3], s[48:49], 0, v[68:69]
	v_lshl_add_u64 v[4:5], v[96:97], 0, v[70:71]
	v_lshl_add_u64 v[2:3], v[4:5], 2, v[2:3]
	v_add_f32_e32 v0, v0, v1
	global_store_dword v[2:3], v0, off offset:256

.LBB0_1296:
	v_or_b32_e32 v4, v34, v72
	v_ashrrev_i32_e32 v5, 31, v4
	v_lshlrev_b64 v[0:1], 12, v[4:5]
	v_lshl_add_u64 v[0:1], s[42:43], 0, v[0:1]
	v_lshl_add_u64 v[16:17], v[98:99], 2, v[0:1]
	s_movk_i32 s2, 0x1000
	v_cmp_gt_i32_e32 vcc, s2, v4
	s_nop 1
	v_cndmask_b32_e32 v7, v6, v102, vcc
	v_and_b32_e32 v7, 1, v7
	v_cmp_eq_u32_e32 vcc, 1, v7
	s_nop 1
	v_cndmask_b32_e64 v7, v171, 0, vcc
	v_add_u32_e32 v7, v103, v7
	ds_read_b128 v[8:11], v86 offset:2176
	ds_read_b128 v[12:15], v7
	s_and_b64 vcc, exec, s[0:1]
	s_waitcnt vmcnt(7) lgkmcnt(0)
	v_pk_fma_f32 v[2:3], v[10:11], v[14:15], v[208:209]
	v_pk_fma_f32 v[0:1], v[8:9], v[12:13], v[206:207]
	global_store_dwordx4 v[16:17], v[0:3], off
	s_cbranch_vccnz .LBB0_1300
	ds_read_b128 v[8:11], v7 offset:2048
	v_lshlrev_b64 v[4:5], 10, v[4:5]
	v_lshl_add_u64 v[4:5], v[4:5], 1, s[44:45]
	v_lshl_add_u64 v[4:5], v[98:99], 1, v[4:5]
	s_waitcnt lgkmcnt(0)
	v_pk_mul_f32 v[8:9], v[0:1], v[8:9]
	v_pk_mul_f32 v[0:1], v[0:1], v[0:1]
	v_pk_mul_f32 v[10:11], v[2:3], v[10:11]
	v_pk_mul_f32 v[2:3], v[2:3], v[2:3]
	v_add_f32_e32 v0, v0, v1
	v_add_f32_e32 v0, v2, v0
	v_add_f32_e32 v0, v3, v0
	v_cvt_pk_bf16_f32 v8, v8, v9
	v_cvt_pk_bf16_f32 v9, v10, v11
	v_add_f32_dpp v0, v0, v0 quad_perm:[1,0,3,2] row_mask:0xf bank_mask:0xf bound_ctrl:1
	global_store_dwordx2 v[4:5], v[8:9], off
	s_nop 0
	v_add_f32_dpp v0, v0, v0 quad_perm:[2,3,0,1] row_mask:0xf bank_mask:0xf bound_ctrl:1
	s_nop 1
	v_add_f32_dpp v0, v0, v0 row_half_mirror row_mask:0xf bank_mask:0xf bound_ctrl:1
	s_nop 1
	v_mov_b32_dpp v1, v0 row_mirror row_mask:0xf bank_mask:0xf bound_ctrl:1
	s_and_saveexec_b64 s[2:3], s[40:41]
	s_cbranch_execz .LBB0_1299
	v_mov_b32_e32 v73, v129
	v_ashrrev_i32_e32 v97, 31, v96
	v_lshl_add_u64 v[2:3], s[48:49], 0, v[68:69]
	v_lshl_add_u64 v[4:5], v[96:97], 0, v[72:73]
	v_lshl_add_u64 v[2:3], v[4:5], 2, v[2:3]
	v_add_f32_e32 v0, v0, v1
	global_store_dword v[2:3], v0, off offset:256

.LBB0_1300:
	v_or_b32_e32 v4, v34, v74
	v_ashrrev_i32_e32 v5, 31, v4
	v_lshlrev_b64 v[0:1], 12, v[4:5]
	v_lshl_add_u64 v[0:1], s[42:43], 0, v[0:1]
	v_lshl_add_u64 v[16:17], v[98:99], 2, v[0:1]
	s_movk_i32 s2, 0x1000
	v_cmp_gt_i32_e32 vcc, s2, v4
	s_nop 1
	v_cndmask_b32_e32 v7, v6, v102, vcc
	v_and_b32_e32 v7, 1, v7
	v_cmp_eq_u32_e32 vcc, 1, v7
	s_nop 1
	v_cndmask_b32_e64 v7, v171, 0, vcc
	v_add_u32_e32 v7, v103, v7
	ds_read_b128 v[8:11], v86 offset:3264
	ds_read_b128 v[12:15], v7
	s_and_b64 vcc, exec, s[0:1]
	s_waitcnt vmcnt(7) lgkmcnt(0)
	v_pk_fma_f32 v[2:3], v[10:11], v[14:15], v[212:213]
	v_pk_fma_f32 v[0:1], v[8:9], v[12:13], v[210:211]
	global_store_dwordx4 v[16:17], v[0:3], off
	s_cbranch_vccnz .LBB0_1304
	ds_read_b128 v[8:11], v7 offset:2048
	v_lshlrev_b64 v[4:5], 10, v[4:5]
	v_lshl_add_u64 v[4:5], v[4:5], 1, s[44:45]
	v_lshl_add_u64 v[4:5], v[98:99], 1, v[4:5]
	s_waitcnt lgkmcnt(0)
	v_pk_mul_f32 v[8:9], v[0:1], v[8:9]
	v_pk_mul_f32 v[0:1], v[0:1], v[0:1]
	v_pk_mul_f32 v[10:11], v[2:3], v[10:11]
	v_pk_mul_f32 v[2:3], v[2:3], v[2:3]
	v_add_f32_e32 v0, v0, v1
	v_add_f32_e32 v0, v2, v0
	v_add_f32_e32 v0, v3, v0
	v_cvt_pk_bf16_f32 v8, v8, v9
	v_cvt_pk_bf16_f32 v9, v10, v11
	v_add_f32_dpp v0, v0, v0 quad_perm:[1,0,3,2] row_mask:0xf bank_mask:0xf bound_ctrl:1
	global_store_dwordx2 v[4:5], v[8:9], off
	s_nop 0
	v_add_f32_dpp v0, v0, v0 quad_perm:[2,3,0,1] row_mask:0xf bank_mask:0xf bound_ctrl:1
	s_nop 1
	v_add_f32_dpp v0, v0, v0 row_half_mirror row_mask:0xf bank_mask:0xf bound_ctrl:1
	s_nop 1
	v_mov_b32_dpp v1, v0 row_mirror row_mask:0xf bank_mask:0xf bound_ctrl:1
	s_and_saveexec_b64 s[2:3], s[40:41]
	s_cbranch_execz .LBB0_1303
	v_mov_b32_e32 v75, v129
	v_ashrrev_i32_e32 v97, 31, v96
	v_lshl_add_u64 v[2:3], s[48:49], 0, v[68:69]
	v_lshl_add_u64 v[4:5], v[96:97], 0, v[74:75]
	v_lshl_add_u64 v[2:3], v[4:5], 2, v[2:3]
	v_add_f32_e32 v0, v0, v1
	global_store_dword v[2:3], v0, off offset:256

.LBB0_1304:
	v_or_b32_e32 v4, v34, v76
	v_ashrrev_i32_e32 v5, 31, v4
	v_lshlrev_b64 v[0:1], 12, v[4:5]
	v_lshl_add_u64 v[0:1], s[42:43], 0, v[0:1]
	v_lshl_add_u64 v[16:17], v[98:99], 2, v[0:1]
	s_movk_i32 s2, 0x1000
	v_cmp_gt_i32_e32 vcc, s2, v4
	s_nop 1
	v_cndmask_b32_e32 v7, v6, v102, vcc
	v_and_b32_e32 v7, 1, v7
	v_cmp_eq_u32_e32 vcc, 1, v7
	s_nop 1
	v_cndmask_b32_e64 v7, v171, 0, vcc
	v_add_u32_e32 v7, v103, v7
	ds_read_b128 v[8:11], v86 offset:4352
	ds_read_b128 v[12:15], v7
	s_and_b64 vcc, exec, s[0:1]
	s_waitcnt vmcnt(7) lgkmcnt(0)
	v_pk_fma_f32 v[2:3], v[10:11], v[14:15], v[216:217]
	v_pk_fma_f32 v[0:1], v[8:9], v[12:13], v[214:215]
	global_store_dwordx4 v[16:17], v[0:3], off
	s_cbranch_vccnz .LBB0_1308
	ds_read_b128 v[8:11], v7 offset:2048
	v_lshlrev_b64 v[4:5], 10, v[4:5]
	v_lshl_add_u64 v[4:5], v[4:5], 1, s[44:45]
	v_lshl_add_u64 v[4:5], v[98:99], 1, v[4:5]
	s_waitcnt lgkmcnt(0)
	v_pk_mul_f32 v[8:9], v[0:1], v[8:9]
	v_pk_mul_f32 v[0:1], v[0:1], v[0:1]
	v_pk_mul_f32 v[10:11], v[2:3], v[10:11]
	v_pk_mul_f32 v[2:3], v[2:3], v[2:3]
	v_add_f32_e32 v0, v0, v1
	v_add_f32_e32 v0, v2, v0
	v_add_f32_e32 v0, v3, v0
	v_cvt_pk_bf16_f32 v8, v8, v9
	v_cvt_pk_bf16_f32 v9, v10, v11
	v_add_f32_dpp v0, v0, v0 quad_perm:[1,0,3,2] row_mask:0xf bank_mask:0xf bound_ctrl:1
	global_store_dwordx2 v[4:5], v[8:9], off
	s_nop 0
	v_add_f32_dpp v0, v0, v0 quad_perm:[2,3,0,1] row_mask:0xf bank_mask:0xf bound_ctrl:1
	s_nop 1
	v_add_f32_dpp v0, v0, v0 row_half_mirror row_mask:0xf bank_mask:0xf bound_ctrl:1
	s_nop 1
	v_mov_b32_dpp v1, v0 row_mirror row_mask:0xf bank_mask:0xf bound_ctrl:1
	s_and_saveexec_b64 s[2:3], s[40:41]
	s_cbranch_execz .LBB0_1307
	v_mov_b32_e32 v77, v129
	v_ashrrev_i32_e32 v97, 31, v96
	v_lshl_add_u64 v[2:3], s[48:49], 0, v[68:69]
	v_lshl_add_u64 v[4:5], v[96:97], 0, v[76:77]
	v_lshl_add_u64 v[2:3], v[4:5], 2, v[2:3]
	v_add_f32_e32 v0, v0, v1
	global_store_dword v[2:3], v0, off offset:256

.LBB0_1308:
	v_or_b32_e32 v4, v34, v78
	v_ashrrev_i32_e32 v5, 31, v4
	v_lshlrev_b64 v[0:1], 12, v[4:5]
	v_lshl_add_u64 v[0:1], s[42:43], 0, v[0:1]
	v_lshl_add_u64 v[16:17], v[98:99], 2, v[0:1]
	s_movk_i32 s2, 0x1000
	v_cmp_gt_i32_e32 vcc, s2, v4
	s_nop 1
	v_cndmask_b32_e32 v7, v6, v102, vcc
	v_and_b32_e32 v7, 1, v7
	v_cmp_eq_u32_e32 vcc, 1, v7
	s_nop 1
	v_cndmask_b32_e64 v7, v171, 0, vcc
	v_add_u32_e32 v7, v103, v7
	ds_read_b128 v[8:11], v86 offset:5440
	ds_read_b128 v[12:15], v7
	s_and_b64 vcc, exec, s[0:1]
	s_waitcnt vmcnt(7) lgkmcnt(0)
	v_pk_fma_f32 v[2:3], v[10:11], v[14:15], v[220:221]
	v_pk_fma_f32 v[0:1], v[8:9], v[12:13], v[218:219]
	global_store_dwordx4 v[16:17], v[0:3], off
	s_cbranch_vccnz .LBB0_1312
	ds_read_b128 v[8:11], v7 offset:2048
	v_lshlrev_b64 v[4:5], 10, v[4:5]
	v_lshl_add_u64 v[4:5], v[4:5], 1, s[44:45]
	v_lshl_add_u64 v[4:5], v[98:99], 1, v[4:5]
	s_waitcnt lgkmcnt(0)
	v_pk_mul_f32 v[8:9], v[0:1], v[8:9]
	v_pk_mul_f32 v[0:1], v[0:1], v[0:1]
	v_pk_mul_f32 v[10:11], v[2:3], v[10:11]
	v_pk_mul_f32 v[2:3], v[2:3], v[2:3]
	v_add_f32_e32 v0, v0, v1
	v_add_f32_e32 v0, v2, v0
	v_add_f32_e32 v0, v3, v0
	v_cvt_pk_bf16_f32 v8, v8, v9
	v_cvt_pk_bf16_f32 v9, v10, v11
	v_add_f32_dpp v0, v0, v0 quad_perm:[1,0,3,2] row_mask:0xf bank_mask:0xf bound_ctrl:1
	global_store_dwordx2 v[4:5], v[8:9], off
	s_nop 0
	v_add_f32_dpp v0, v0, v0 quad_perm:[2,3,0,1] row_mask:0xf bank_mask:0xf bound_ctrl:1
	s_nop 1
	v_add_f32_dpp v0, v0, v0 row_half_mirror row_mask:0xf bank_mask:0xf bound_ctrl:1
	s_nop 1
	v_mov_b32_dpp v1, v0 row_mirror row_mask:0xf bank_mask:0xf bound_ctrl:1
	s_and_saveexec_b64 s[2:3], s[40:41]
	s_cbranch_execz .LBB0_1311
	v_mov_b32_e32 v79, v129
	v_ashrrev_i32_e32 v97, 31, v96
	v_lshl_add_u64 v[2:3], s[48:49], 0, v[68:69]
	v_lshl_add_u64 v[4:5], v[96:97], 0, v[78:79]
	v_lshl_add_u64 v[2:3], v[4:5], 2, v[2:3]
	v_add_f32_e32 v0, v0, v1
	global_store_dword v[2:3], v0, off offset:256

.LBB0_1312:
	v_or_b32_e32 v4, v34, v80
	v_ashrrev_i32_e32 v5, 31, v4
	v_lshlrev_b64 v[0:1], 12, v[4:5]
	v_lshl_add_u64 v[0:1], s[42:43], 0, v[0:1]
	v_lshl_add_u64 v[16:17], v[98:99], 2, v[0:1]
	s_movk_i32 s2, 0x1000
	v_cmp_gt_i32_e32 vcc, s2, v4
	s_nop 1
	v_cndmask_b32_e32 v7, v6, v102, vcc
	v_and_b32_e32 v7, 1, v7
	v_cmp_eq_u32_e32 vcc, 1, v7
	s_nop 1
	v_cndmask_b32_e64 v7, v171, 0, vcc
	v_add_u32_e32 v7, v103, v7
	ds_read_b128 v[8:11], v86 offset:6528
	ds_read_b128 v[12:15], v7
	s_and_b64 vcc, exec, s[0:1]
	s_waitcnt vmcnt(7) lgkmcnt(0)
	v_pk_fma_f32 v[2:3], v[10:11], v[14:15], v[224:225]
	v_pk_fma_f32 v[0:1], v[8:9], v[12:13], v[222:223]
	global_store_dwordx4 v[16:17], v[0:3], off
	s_cbranch_vccnz .LBB0_1316
	ds_read_b128 v[8:11], v7 offset:2048
	v_lshlrev_b64 v[4:5], 10, v[4:5]
	v_lshl_add_u64 v[4:5], v[4:5], 1, s[44:45]
	v_lshl_add_u64 v[4:5], v[98:99], 1, v[4:5]
	s_waitcnt lgkmcnt(0)
	v_pk_mul_f32 v[8:9], v[0:1], v[8:9]
	v_pk_mul_f32 v[0:1], v[0:1], v[0:1]
	v_pk_mul_f32 v[10:11], v[2:3], v[10:11]
	v_pk_mul_f32 v[2:3], v[2:3], v[2:3]
	v_add_f32_e32 v0, v0, v1
	v_add_f32_e32 v0, v2, v0
	v_add_f32_e32 v0, v3, v0
	v_cvt_pk_bf16_f32 v8, v8, v9
	v_cvt_pk_bf16_f32 v9, v10, v11
	v_add_f32_dpp v0, v0, v0 quad_perm:[1,0,3,2] row_mask:0xf bank_mask:0xf bound_ctrl:1
	global_store_dwordx2 v[4:5], v[8:9], off
	s_nop 0
	v_add_f32_dpp v0, v0, v0 quad_perm:[2,3,0,1] row_mask:0xf bank_mask:0xf bound_ctrl:1
	s_nop 1
	v_add_f32_dpp v0, v0, v0 row_half_mirror row_mask:0xf bank_mask:0xf bound_ctrl:1
	s_nop 1
	v_mov_b32_dpp v1, v0 row_mirror row_mask:0xf bank_mask:0xf bound_ctrl:1
	s_and_saveexec_b64 s[2:3], s[40:41]
	s_cbranch_execz .LBB0_1315
	v_mov_b32_e32 v81, v129
	v_ashrrev_i32_e32 v97, 31, v96
	v_lshl_add_u64 v[2:3], s[48:49], 0, v[68:69]
	v_lshl_add_u64 v[4:5], v[96:97], 0, v[80:81]
	v_lshl_add_u64 v[2:3], v[4:5], 2, v[2:3]
	v_add_f32_e32 v0, v0, v1
	global_store_dword v[2:3], v0, off offset:256

.LBB0_1316:
	v_or_b32_e32 v4, v34, v82
	v_ashrrev_i32_e32 v5, 31, v4
	v_lshlrev_b64 v[0:1], 12, v[4:5]
	v_lshl_add_u64 v[0:1], s[42:43], 0, v[0:1]
	v_lshl_add_u64 v[16:17], v[98:99], 2, v[0:1]
	s_movk_i32 s2, 0x1000
	v_cmp_gt_i32_e32 vcc, s2, v4
	s_nop 1
	v_cndmask_b32_e32 v6, v6, v102, vcc
	v_and_b32_e32 v6, 1, v6
	v_cmp_eq_u32_e32 vcc, 1, v6
	s_nop 1
	v_cndmask_b32_e64 v6, v171, 0, vcc
	v_add_u32_e32 v6, v103, v6
	ds_read_b128 v[8:11], v86 offset:7616
	ds_read_b128 v[12:15], v6
	s_and_b64 vcc, exec, s[0:1]
	s_waitcnt vmcnt(7) lgkmcnt(0)
	v_pk_fma_f32 v[2:3], v[10:11], v[14:15], v[228:229]
	v_pk_fma_f32 v[0:1], v[8:9], v[12:13], v[226:227]
	global_store_dwordx4 v[16:17], v[0:3], off
	s_cbranch_vccnz .LBB0_1219
	ds_read_b128 v[6:9], v6 offset:2048
	v_lshlrev_b64 v[4:5], 10, v[4:5]
	v_lshl_add_u64 v[4:5], v[4:5], 1, s[44:45]
	v_lshl_add_u64 v[4:5], v[98:99], 1, v[4:5]
	s_waitcnt lgkmcnt(0)
	v_pk_mul_f32 v[6:7], v[0:1], v[6:7]
	v_pk_mul_f32 v[0:1], v[0:1], v[0:1]
	v_pk_mul_f32 v[8:9], v[2:3], v[8:9]
	v_pk_mul_f32 v[2:3], v[2:3], v[2:3]
	v_add_f32_e32 v0, v0, v1
	v_add_f32_e32 v0, v2, v0
	v_add_f32_e32 v0, v3, v0
	v_cvt_pk_bf16_f32 v6, v6, v7
	v_cvt_pk_bf16_f32 v7, v8, v9
	v_add_f32_dpp v0, v0, v0 quad_perm:[1,0,3,2] row_mask:0xf bank_mask:0xf bound_ctrl:1
	global_store_dwordx2 v[4:5], v[6:7], off
	s_nop 0
	v_add_f32_dpp v0, v0, v0 quad_perm:[2,3,0,1] row_mask:0xf bank_mask:0xf bound_ctrl:1
	s_nop 1
	v_add_f32_dpp v0, v0, v0 row_half_mirror row_mask:0xf bank_mask:0xf bound_ctrl:1
	s_nop 1
	v_mov_b32_dpp v1, v0 row_mirror row_mask:0xf bank_mask:0xf bound_ctrl:1
	s_and_saveexec_b64 s[0:1], s[40:41]
	s_cbranch_execz .LBB0_1218
	v_mov_b32_e32 v83, v129
	v_ashrrev_i32_e32 v97, 31, v96
	v_lshl_add_u64 v[2:3], s[48:49], 0, v[68:69]
	v_lshl_add_u64 v[4:5], v[96:97], 0, v[82:83]
	v_lshl_add_u64 v[2:3], v[4:5], 2, v[2:3]
	v_add_f32_e32 v0, v0, v1
	global_store_dword v[2:3], v0, off offset:256
	s_branch .LBB0_1218
